# GEMM K-loops regenerated: depth-2 register prefetch, global loads + ds_writes interleaved 1:2 with MFMAs, fragment reads one k-slice ahead
# speedup vs baseline: 1.0297x; 1.0297x over previous
; #define MFMA(a, b, c) __builtin_amdgcn_mfma_f32_32x32x16_bf16((a), (b), (c), 0, 0, 0)
; template <bool SWAP>
; DI void gemm_block(const bf16_t* __restrict__ A, int lda, const bf16_t* __restrict__ Bt, int ldb, int K, f32x16 (&acc)[2][2], bf16_t* sA, bf16_t* sB) {
;     ...
;   const int lrow = tid >> 3, lch = (tid & 7) * 8;
;   const bf16_t* ga = A + (size_t)lrow * lda + lch;
;   const bf16_t* gb = Bt + (size_t)lrow * ldb + lch;
;   const int soff = lrow * LDT + lch;
;   u32x4 ra[4], rb[4];
; #pragma unroll
;   for (int i = 0; i < 4; ++i) { ra[i] = *(const u32x4*)(ga + (size_t)i * 32 * lda); rb[i] = *(const u32x4*)(gb + (size_t)i * 32 * ldb); }
; #pragma unroll
;   for (int i = 0; i < 4; ++i) { *(u32x4*)(sA + soff + i * 32 * LDT) = ra[i]; *(u32x4*)(sB + soff + i * 32 * LDT) = rb[i]; }
;   __syncthreads();
;   const int nk = K >> 6;
;   for (int kt = 0; kt < nk; ++kt) {
;     const int cur = kt & 1;
;     const bool more = kt + 1 < nk;
;     if (more) {
;       const int k0 = (kt + 1) * 64;
; #pragma unroll
;       for (int i = 0; i < 4; ++i) { ra[i] = *(const u32x4*)(ga + (size_t)i * 32 * lda + k0); rb[i] = *(const u32x4*)(gb + (size_t)i * 32 * ldb + k0); }
;     }
;     const bf16_t* ab = sA + cur * 128 * LDT + (64 * wr + l32) * LDT + h * 8;
;     const bf16_t* bb = sB + cur * 128 * LDT + (64 * wc + l32) * LDT + h * 8;
;     __builtin_amdgcn_s_setprio(1);
;     __builtin_amdgcn_iglp_opt(0);
; #pragma unroll
;     for (int ks = 0; ks < 4; ++ks) {
;       const bf16x8 a0 = *(const bf16x8*)(ab + ks * 16), a1 = *(const bf16x8*)(ab + 32 * LDT + ks * 16);
;       const bf16x8 b0 = *(const bf16x8*)(bb + ks * 16), b1 = *(const bf16x8*)(bb + 32 * LDT + ks * 16);
;       if (!SWAP) {
;         acc[0][0] = MFMA(a0, b0, acc[0][0]); acc[0][1] = MFMA(a0, b1, acc[0][1]);
;         acc[1][0] = MFMA(a1, b0, acc[1][0]); acc[1][1] = MFMA(a1, b1, acc[1][1]);
;       } else {
;         acc[0][0] = MFMA(b0, a0, acc[0][0]); acc[0][1] = MFMA(b1, a0, acc[0][1]);
;         acc[1][0] = MFMA(b0, a1, acc[1][0]); acc[1][1] = MFMA(b1, a1, acc[1][1]);
;       }
;     }
;     __builtin_amdgcn_s_setprio(0);
;     if (more) {
;       const int nb = (cur ^ 1) * 128 * LDT;
; #pragma unroll
;       for (int i = 0; i < 4; ++i) { *(u32x4*)(sA + nb + soff + i * 32 * LDT) = ra[i]; *(u32x4*)(sB + nb + soff + i * 32 * LDT) = rb[i]; }
;     }
;     __syncthreads();
.LBB0_232:
	v_mov_b32_e32 v84, v188
	s_andn2_b64 vcc, exec, s[22:23]
	s_mov_b64 s[22:23], -1
	s_cbranch_vccz .LBB0_234
	v_mov_b32_e32 v34, v188
	s_waitcnt vmcnt(7)
	v_ashrrev_i32_e32 v2, 3, v34
	v_lshlrev_b32_e32 v0, 3, v34
	v_ashrrev_i32_e32 v3, 31, v2
	v_and_b32_e32 v35, 56, v0
	v_lshlrev_b64 v[4:5], 11, v[2:3]
	s_waitcnt vmcnt(6)
	v_lshl_add_u64 v[6:7], s[20:21], 0, v[4:5]
	v_lshlrev_b32_e32 v0, 1, v35
	v_lshl_add_u64 v[68:69], v[6:7], 0, v[0:1]
	v_lshl_add_u64 v[4:5], s[42:43], 0, v[4:5]
	v_add_co_u32_e32 v72, vcc, s50, v68
	v_lshl_add_u64 v[70:71], v[4:5], 0, v[0:1]
	s_nop 0
	v_addc_co_u32_e32 v73, vcc, 0, v69, vcc
	v_add_co_u32_e32 v74, vcc, s50, v70
	v_mul_lo_u32 v0, v2, s33
	s_nop 0
	v_addc_co_u32_e32 v75, vcc, 0, v71, vcc
	v_add_co_u32_e32 v76, vcc, s51, v68
	global_load_dwordx4 v[2:5], v[68:69], off
	s_nop 0
	v_addc_co_u32_e32 v77, vcc, 0, v69, vcc
	v_add_co_u32_e32 v78, vcc, s51, v70
	global_load_dwordx4 v[6:9], v[70:71], off
	s_nop 0
	v_addc_co_u32_e32 v79, vcc, 0, v71, vcc
	v_add_co_u32_e32 v80, vcc, s52, v68
	global_load_dwordx4 v[10:13], v[72:73], off
	s_nop 0
	v_addc_co_u32_e32 v81, vcc, 0, v69, vcc
	v_add_co_u32_e32 v82, vcc, s52, v70
	global_load_dwordx4 v[14:17], v[74:75], off
	s_nop 0
	v_addc_co_u32_e32 v83, vcc, 0, v71, vcc
	global_load_dwordx4 v[18:21], v[76:77], off
	global_load_dwordx4 v[22:25], v[78:79], off
	global_load_dwordx4 v[26:29], v[80:81], off
	global_load_dwordx4 v[30:33], v[82:83], off
	global_load_dwordx4 v[152:155], v[68:69], off offset:128
	global_load_dwordx4 v[156:159], v[70:71], off offset:128
	global_load_dwordx4 v[160:163], v[72:73], off offset:128
	global_load_dwordx4 v[164:167], v[74:75], off offset:128
	global_load_dwordx4 v[168:171], v[76:77], off offset:128
	global_load_dwordx4 v[172:175], v[78:79], off offset:128
	global_load_dwordx4 v[176:179], v[80:81], off offset:128
	global_load_dwordx4 v[180:183], v[82:83], off offset:128
	v_add_lshl_u32 v85, v0, v35, 1
	v_and_b32_e32 v0, 31, v34
	v_add_u32_e32 v86, 0x9000, v85
	s_waitcnt vmcnt(15)
	ds_write_b128 v85, v[2:5]
	v_lshrrev_b32_e32 v2, 1, v34
	v_and_or_b32 v3, v2, s53, v0
	v_and_b32_e32 v0, 16, v2
	v_and_b32_e32 v2, 0x5f, v34
	s_waitcnt vmcnt(14)
	ds_write_b128 v85, v[6:9] offset:36864
	v_mad_u64_u32 v[66:67], s[0:1], v3, s54, v[0:1]
	v_mad_u32_u24 v0, v2, s54, v0
	s_waitcnt vmcnt(13)
	ds_write_b128 v85, v[10:13] offset:4608
	s_waitcnt vmcnt(12)
	ds_write_b128 v85, v[14:17] offset:41472
	s_waitcnt vmcnt(11)
	ds_write_b128 v85, v[18:21] offset:9216
	s_waitcnt vmcnt(10)
	ds_write_b128 v85, v[22:25] offset:46080
	s_waitcnt vmcnt(9)
	ds_write_b128 v85, v[26:29] offset:13824
	s_waitcnt vmcnt(8)
	ds_write_b128 v85, v[30:33] offset:50688
	s_waitcnt lgkmcnt(0)
	s_barrier
	ds_read_b128 v[120:123], v66
	ds_read_b128 v[128:131], v0 offset:36864
	ds_read_b128 v[132:135], v0 offset:41472
	ds_read_b128 v[124:127], v66 offset:4608
	ds_read_b128 v[136:139], v66 offset:32
	ds_read_b128 v[184:187], v0 offset:36896
	ds_read_b128 v[200:203], v0 offset:41504
	ds_read_b128 v[140:143], v66 offset:4640
	s_setprio 1
	s_waitcnt lgkmcnt(4)
	v_mfma_f32_32x32x16_bf16 v[34:49], v[128:131], v[120:123], 0
	global_load_dwordx4 v[88:91], v[68:69], off offset:256
	v_mfma_f32_32x32x16_bf16 v[18:33], v[132:135], v[120:123], 0
	s_waitcnt vmcnt(8)
	ds_write_b128 v85, v[152:155] offset:18432
	v_mfma_f32_32x32x16_bf16 v[50:65], v[132:135], v[124:127], 0
	global_load_dwordx4 v[92:95], v[70:71], off offset:256
	v_mfma_f32_32x32x16_bf16 v[2:17], v[128:131], v[124:127], 0
	s_waitcnt vmcnt(8)
	ds_write_b128 v85, v[156:159] offset:55296
	ds_read_b128 v[120:123], v66 offset:64
	ds_read_b128 v[128:131], v0 offset:36928
	ds_read_b128 v[132:135], v0 offset:41536
	ds_read_b128 v[124:127], v66 offset:4672
	s_waitcnt lgkmcnt(6)
	v_mfma_f32_32x32x16_bf16 v[34:49], v[184:187], v[136:139], v[34:49]
	global_load_dwordx4 v[96:99], v[72:73], off offset:256
	v_mfma_f32_32x32x16_bf16 v[18:33], v[200:203], v[136:139], v[18:33]
	s_waitcnt vmcnt(8)
	ds_write_b128 v85, v[160:163] offset:23040
	v_mfma_f32_32x32x16_bf16 v[50:65], v[200:203], v[140:143], v[50:65]
	global_load_dwordx4 v[100:103], v[74:75], off offset:256
	v_mfma_f32_32x32x16_bf16 v[2:17], v[184:187], v[140:143], v[2:17]
	s_waitcnt vmcnt(8)
	ds_write_b128 v85, v[164:167] offset:59904
	ds_read_b128 v[136:139], v66 offset:96
	ds_read_b128 v[184:187], v0 offset:36960
	ds_read_b128 v[200:203], v0 offset:41568
	ds_read_b128 v[140:143], v66 offset:4704
	s_waitcnt lgkmcnt(6)
	v_mfma_f32_32x32x16_bf16 v[34:49], v[128:131], v[120:123], v[34:49]
	global_load_dwordx4 v[104:107], v[76:77], off offset:256
	v_mfma_f32_32x32x16_bf16 v[18:33], v[132:135], v[120:123], v[18:33]
	s_waitcnt vmcnt(8)
	ds_write_b128 v85, v[168:171] offset:27648
	v_mfma_f32_32x32x16_bf16 v[50:65], v[132:135], v[124:127], v[50:65]
	global_load_dwordx4 v[108:111], v[78:79], off offset:256
	v_mfma_f32_32x32x16_bf16 v[2:17], v[128:131], v[124:127], v[2:17]
	s_waitcnt vmcnt(8)
	ds_write_b128 v85, v[172:175] offset:64512
	s_waitcnt lgkmcnt(2)
	v_mfma_f32_32x32x16_bf16 v[34:49], v[184:187], v[136:139], v[34:49]
	global_load_dwordx4 v[112:115], v[80:81], off offset:256
	v_mfma_f32_32x32x16_bf16 v[18:33], v[200:203], v[136:139], v[18:33]
	s_waitcnt vmcnt(8)
	ds_write_b128 v85, v[176:179] offset:32256
	v_mfma_f32_32x32x16_bf16 v[50:65], v[200:203], v[140:143], v[50:65]
	global_load_dwordx4 v[116:119], v[82:83], off offset:256
	v_mfma_f32_32x32x16_bf16 v[2:17], v[184:187], v[140:143], v[2:17]
	s_waitcnt vmcnt(8)
	ds_write_b128 v86, v[180:183] offset:32256
	s_setprio 0
	s_waitcnt lgkmcnt(0)
	s_barrier
; #define MFMA(a, b, c) __builtin_amdgcn_mfma_f32_32x32x16_bf16((a), (b), (c), 0, 0, 0)
; template <bool SWAP>
; DI void gemm_block(const bf16_t* __restrict__ A, int lda, const bf16_t* __restrict__ Bt, int ldb, int K, f32x16 (&acc)[2][2], bf16_t* sA, bf16_t* sB) {
;     ...
;   for (int kt = 0; kt < nk; ++kt) {
;     const int cur = kt & 1;
;     const bool more = kt + 1 < nk;
;     if (more) {
;       const int k0 = (kt + 1) * 64;
; #pragma unroll
;       for (int i = 0; i < 4; ++i) { ra[i] = *(const u32x4*)(ga + (size_t)i * 32 * lda + k0); rb[i] = *(const u32x4*)(gb + (size_t)i * 32 * ldb + k0); }
;     }
;     const bf16_t* ab = sA + cur * 128 * LDT + (64 * wr + l32) * LDT + h * 8;
;     const bf16_t* bb = sB + cur * 128 * LDT + (64 * wc + l32) * LDT + h * 8;
;     __builtin_amdgcn_s_setprio(1);
;     __builtin_amdgcn_iglp_opt(0);
; #pragma unroll
;     for (int ks = 0; ks < 4; ++ks) {
;       const bf16x8 a0 = *(const bf16x8*)(ab + ks * 16), a1 = *(const bf16x8*)(ab + 32 * LDT + ks * 16);
;       const bf16x8 b0 = *(const bf16x8*)(bb + ks * 16), b1 = *(const bf16x8*)(bb + 32 * LDT + ks * 16);
;       if (!SWAP) {
;         acc[0][0] = MFMA(a0, b0, acc[0][0]); acc[0][1] = MFMA(a0, b1, acc[0][1]);
;         acc[1][0] = MFMA(a1, b0, acc[1][0]); acc[1][1] = MFMA(a1, b1, acc[1][1]);
;       } else {
;         acc[0][0] = MFMA(b0, a0, acc[0][0]); acc[0][1] = MFMA(b1, a0, acc[0][1]);
;         acc[1][0] = MFMA(b0, a1, acc[1][0]); acc[1][1] = MFMA(b1, a1, acc[1][1]);
;       }
;     }
;     __builtin_amdgcn_s_setprio(0);
;     if (more) {
;       const int nb = (cur ^ 1) * 128 * LDT;
; #pragma unroll
;       for (int i = 0; i < 4; ++i) { *(u32x4*)(sA + nb + soff + i * 32 * LDT) = ra[i]; *(u32x4*)(sB + nb + soff + i * 32 * LDT) = rb[i]; }
;     }
;     __syncthreads();
	ds_read_b128 v[120:123], v66 offset:18432
	ds_read_b128 v[128:131], v0 offset:55296
	ds_read_b128 v[132:135], v0 offset:59904
	ds_read_b128 v[124:127], v66 offset:23040
	ds_read_b128 v[136:139], v66 offset:18464
	ds_read_b128 v[184:187], v0 offset:55328
	ds_read_b128 v[200:203], v0 offset:59936
	ds_read_b128 v[140:143], v66 offset:23072
	s_setprio 1
	s_waitcnt lgkmcnt(4)
	v_mfma_f32_32x32x16_bf16 v[34:49], v[128:131], v[120:123], v[34:49]
	global_load_dwordx4 v[152:155], v[68:69], off offset:384
	v_mfma_f32_32x32x16_bf16 v[18:33], v[132:135], v[120:123], v[18:33]
	s_waitcnt vmcnt(8)
	ds_write_b128 v85, v[88:91]
	v_mfma_f32_32x32x16_bf16 v[50:65], v[132:135], v[124:127], v[50:65]
	global_load_dwordx4 v[156:159], v[70:71], off offset:384
	v_mfma_f32_32x32x16_bf16 v[2:17], v[128:131], v[124:127], v[2:17]
	s_waitcnt vmcnt(8)
	ds_write_b128 v85, v[92:95] offset:36864
	ds_read_b128 v[120:123], v66 offset:18496
	ds_read_b128 v[128:131], v0 offset:55360
	ds_read_b128 v[132:135], v0 offset:59968
	ds_read_b128 v[124:127], v66 offset:23104
	s_waitcnt lgkmcnt(6)
	v_mfma_f32_32x32x16_bf16 v[34:49], v[184:187], v[136:139], v[34:49]
	global_load_dwordx4 v[160:163], v[72:73], off offset:384
	v_mfma_f32_32x32x16_bf16 v[18:33], v[200:203], v[136:139], v[18:33]
	s_waitcnt vmcnt(8)
	ds_write_b128 v85, v[96:99] offset:4608
	v_mfma_f32_32x32x16_bf16 v[50:65], v[200:203], v[140:143], v[50:65]
	global_load_dwordx4 v[164:167], v[74:75], off offset:384
	v_mfma_f32_32x32x16_bf16 v[2:17], v[184:187], v[140:143], v[2:17]
	s_waitcnt vmcnt(8)
	ds_write_b128 v85, v[100:103] offset:41472
	ds_read_b128 v[136:139], v66 offset:18528
	ds_read_b128 v[184:187], v0 offset:55392
	ds_read_b128 v[200:203], v0 offset:60000
	ds_read_b128 v[140:143], v66 offset:23136
	s_waitcnt lgkmcnt(6)
	v_mfma_f32_32x32x16_bf16 v[34:49], v[128:131], v[120:123], v[34:49]
	global_load_dwordx4 v[168:171], v[76:77], off offset:384
	v_mfma_f32_32x32x16_bf16 v[18:33], v[132:135], v[120:123], v[18:33]
	s_waitcnt vmcnt(8)
	ds_write_b128 v85, v[104:107] offset:9216
	v_mfma_f32_32x32x16_bf16 v[50:65], v[132:135], v[124:127], v[50:65]
	global_load_dwordx4 v[172:175], v[78:79], off offset:384
	v_mfma_f32_32x32x16_bf16 v[2:17], v[128:131], v[124:127], v[2:17]
	s_waitcnt vmcnt(8)
	ds_write_b128 v85, v[108:111] offset:46080
	s_waitcnt lgkmcnt(2)
	v_mfma_f32_32x32x16_bf16 v[34:49], v[184:187], v[136:139], v[34:49]
	global_load_dwordx4 v[176:179], v[80:81], off offset:384
	v_mfma_f32_32x32x16_bf16 v[18:33], v[200:203], v[136:139], v[18:33]
	s_waitcnt vmcnt(8)
	ds_write_b128 v85, v[112:115] offset:13824
	v_mfma_f32_32x32x16_bf16 v[50:65], v[200:203], v[140:143], v[50:65]
	global_load_dwordx4 v[180:183], v[82:83], off offset:384
	v_mfma_f32_32x32x16_bf16 v[2:17], v[184:187], v[140:143], v[2:17]
	s_waitcnt vmcnt(8)
	ds_write_b128 v85, v[116:119] offset:50688
	s_setprio 0
	s_waitcnt lgkmcnt(0)
	s_barrier
	ds_read_b128 v[120:123], v66
	ds_read_b128 v[128:131], v0 offset:36864
	ds_read_b128 v[132:135], v0 offset:41472
	ds_read_b128 v[124:127], v66 offset:4608
	ds_read_b128 v[136:139], v66 offset:32
	ds_read_b128 v[184:187], v0 offset:36896
	ds_read_b128 v[200:203], v0 offset:41504
	ds_read_b128 v[140:143], v66 offset:4640
	s_setprio 1
	s_waitcnt lgkmcnt(4)
	v_mfma_f32_32x32x16_bf16 v[34:49], v[128:131], v[120:123], v[34:49]
	global_load_dwordx4 v[88:91], v[68:69], off offset:512
	v_mfma_f32_32x32x16_bf16 v[18:33], v[132:135], v[120:123], v[18:33]
	s_waitcnt vmcnt(8)
	ds_write_b128 v85, v[152:155] offset:18432
	v_mfma_f32_32x32x16_bf16 v[50:65], v[132:135], v[124:127], v[50:65]
	global_load_dwordx4 v[92:95], v[70:71], off offset:512
	v_mfma_f32_32x32x16_bf16 v[2:17], v[128:131], v[124:127], v[2:17]
	s_waitcnt vmcnt(8)
	ds_write_b128 v85, v[156:159] offset:55296
	ds_read_b128 v[120:123], v66 offset:64
	ds_read_b128 v[128:131], v0 offset:36928
	ds_read_b128 v[132:135], v0 offset:41536
	ds_read_b128 v[124:127], v66 offset:4672
	s_waitcnt lgkmcnt(6)
	v_mfma_f32_32x32x16_bf16 v[34:49], v[184:187], v[136:139], v[34:49]
	global_load_dwordx4 v[96:99], v[72:73], off offset:512
	v_mfma_f32_32x32x16_bf16 v[18:33], v[200:203], v[136:139], v[18:33]
	s_waitcnt vmcnt(8)
	ds_write_b128 v85, v[160:163] offset:23040
	v_mfma_f32_32x32x16_bf16 v[50:65], v[200:203], v[140:143], v[50:65]
	global_load_dwordx4 v[100:103], v[74:75], off offset:512
	v_mfma_f32_32x32x16_bf16 v[2:17], v[184:187], v[140:143], v[2:17]
	s_waitcnt vmcnt(8)
	ds_write_b128 v85, v[164:167] offset:59904
	ds_read_b128 v[136:139], v66 offset:96
	ds_read_b128 v[184:187], v0 offset:36960
	ds_read_b128 v[200:203], v0 offset:41568
	ds_read_b128 v[140:143], v66 offset:4704
	s_waitcnt lgkmcnt(6)
	v_mfma_f32_32x32x16_bf16 v[34:49], v[128:131], v[120:123], v[34:49]
	global_load_dwordx4 v[104:107], v[76:77], off offset:512
	v_mfma_f32_32x32x16_bf16 v[18:33], v[132:135], v[120:123], v[18:33]
	s_waitcnt vmcnt(8)
	ds_write_b128 v85, v[168:171] offset:27648
	v_mfma_f32_32x32x16_bf16 v[50:65], v[132:135], v[124:127], v[50:65]
	global_load_dwordx4 v[108:111], v[78:79], off offset:512
	v_mfma_f32_32x32x16_bf16 v[2:17], v[128:131], v[124:127], v[2:17]
	s_waitcnt vmcnt(8)
	ds_write_b128 v85, v[172:175] offset:64512
	s_waitcnt lgkmcnt(2)
	v_mfma_f32_32x32x16_bf16 v[34:49], v[184:187], v[136:139], v[34:49]
	global_load_dwordx4 v[112:115], v[80:81], off offset:512
	v_mfma_f32_32x32x16_bf16 v[18:33], v[200:203], v[136:139], v[18:33]
	s_waitcnt vmcnt(8)
	ds_write_b128 v85, v[176:179] offset:32256
	v_mfma_f32_32x32x16_bf16 v[50:65], v[200:203], v[140:143], v[50:65]
	global_load_dwordx4 v[116:119], v[82:83], off offset:512
	v_mfma_f32_32x32x16_bf16 v[2:17], v[184:187], v[140:143], v[2:17]
	s_waitcnt vmcnt(8)
	ds_write_b128 v86, v[180:183] offset:32256
	s_setprio 0
	s_waitcnt lgkmcnt(0)
	s_barrier
; #define MFMA(a, b, c) __builtin_amdgcn_mfma_f32_32x32x16_bf16((a), (b), (c), 0, 0, 0)
; template <bool SWAP>
; DI void gemm_block(const bf16_t* __restrict__ A, int lda, const bf16_t* __restrict__ Bt, int ldb, int K, f32x16 (&acc)[2][2], bf16_t* sA, bf16_t* sB) {
;     ...
;   for (int kt = 0; kt < nk; ++kt) {
;     const int cur = kt & 1;
;     const bool more = kt + 1 < nk;
;     if (more) {
;       const int k0 = (kt + 1) * 64;
; #pragma unroll
;       for (int i = 0; i < 4; ++i) { ra[i] = *(const u32x4*)(ga + (size_t)i * 32 * lda + k0); rb[i] = *(const u32x4*)(gb + (size_t)i * 32 * ldb + k0); }
;     }
;     const bf16_t* ab = sA + cur * 128 * LDT + (64 * wr + l32) * LDT + h * 8;
;     const bf16_t* bb = sB + cur * 128 * LDT + (64 * wc + l32) * LDT + h * 8;
;     __builtin_amdgcn_s_setprio(1);
;     __builtin_amdgcn_iglp_opt(0);
; #pragma unroll
;     for (int ks = 0; ks < 4; ++ks) {
;       const bf16x8 a0 = *(const bf16x8*)(ab + ks * 16), a1 = *(const bf16x8*)(ab + 32 * LDT + ks * 16);
;       const bf16x8 b0 = *(const bf16x8*)(bb + ks * 16), b1 = *(const bf16x8*)(bb + 32 * LDT + ks * 16);
;       if (!SWAP) {
;         acc[0][0] = MFMA(a0, b0, acc[0][0]); acc[0][1] = MFMA(a0, b1, acc[0][1]);
;         acc[1][0] = MFMA(a1, b0, acc[1][0]); acc[1][1] = MFMA(a1, b1, acc[1][1]);
;       } else {
;         acc[0][0] = MFMA(b0, a0, acc[0][0]); acc[0][1] = MFMA(b1, a0, acc[0][1]);
;         acc[1][0] = MFMA(b0, a1, acc[1][0]); acc[1][1] = MFMA(b1, a1, acc[1][1]);
;       }
;     }
;     __builtin_amdgcn_s_setprio(0);
;     if (more) {
;       const int nb = (cur ^ 1) * 128 * LDT;
; #pragma unroll
;       for (int i = 0; i < 4; ++i) { *(u32x4*)(sA + nb + soff + i * 32 * LDT) = ra[i]; *(u32x4*)(sB + nb + soff + i * 32 * LDT) = rb[i]; }
;     }
;     __syncthreads();
	ds_read_b128 v[120:123], v66 offset:18432
	ds_read_b128 v[128:131], v0 offset:55296
	ds_read_b128 v[132:135], v0 offset:59904
	ds_read_b128 v[124:127], v66 offset:23040
	ds_read_b128 v[136:139], v66 offset:18464
	ds_read_b128 v[184:187], v0 offset:55328
	ds_read_b128 v[200:203], v0 offset:59936
	ds_read_b128 v[140:143], v66 offset:23072
	s_setprio 1
	s_waitcnt lgkmcnt(4)
	v_mfma_f32_32x32x16_bf16 v[34:49], v[128:131], v[120:123], v[34:49]
	global_load_dwordx4 v[152:155], v[68:69], off offset:640
	v_mfma_f32_32x32x16_bf16 v[18:33], v[132:135], v[120:123], v[18:33]
	s_waitcnt vmcnt(8)
	ds_write_b128 v85, v[88:91]
	v_mfma_f32_32x32x16_bf16 v[50:65], v[132:135], v[124:127], v[50:65]
	global_load_dwordx4 v[156:159], v[70:71], off offset:640
	v_mfma_f32_32x32x16_bf16 v[2:17], v[128:131], v[124:127], v[2:17]
	s_waitcnt vmcnt(8)
	ds_write_b128 v85, v[92:95] offset:36864
	ds_read_b128 v[120:123], v66 offset:18496
	ds_read_b128 v[128:131], v0 offset:55360
	ds_read_b128 v[132:135], v0 offset:59968
	ds_read_b128 v[124:127], v66 offset:23104
	s_waitcnt lgkmcnt(6)
	v_mfma_f32_32x32x16_bf16 v[34:49], v[184:187], v[136:139], v[34:49]
	global_load_dwordx4 v[160:163], v[72:73], off offset:640
	v_mfma_f32_32x32x16_bf16 v[18:33], v[200:203], v[136:139], v[18:33]
	s_waitcnt vmcnt(8)
	ds_write_b128 v85, v[96:99] offset:4608
	v_mfma_f32_32x32x16_bf16 v[50:65], v[200:203], v[140:143], v[50:65]
	global_load_dwordx4 v[164:167], v[74:75], off offset:640
	v_mfma_f32_32x32x16_bf16 v[2:17], v[184:187], v[140:143], v[2:17]
	s_waitcnt vmcnt(8)
	ds_write_b128 v85, v[100:103] offset:41472
	ds_read_b128 v[136:139], v66 offset:18528
	ds_read_b128 v[184:187], v0 offset:55392
	ds_read_b128 v[200:203], v0 offset:60000
	ds_read_b128 v[140:143], v66 offset:23136
	s_waitcnt lgkmcnt(6)
	v_mfma_f32_32x32x16_bf16 v[34:49], v[128:131], v[120:123], v[34:49]
	global_load_dwordx4 v[168:171], v[76:77], off offset:640
	v_mfma_f32_32x32x16_bf16 v[18:33], v[132:135], v[120:123], v[18:33]
	s_waitcnt vmcnt(8)
	ds_write_b128 v85, v[104:107] offset:9216
	v_mfma_f32_32x32x16_bf16 v[50:65], v[132:135], v[124:127], v[50:65]
	global_load_dwordx4 v[172:175], v[78:79], off offset:640
	v_mfma_f32_32x32x16_bf16 v[2:17], v[128:131], v[124:127], v[2:17]
	s_waitcnt vmcnt(8)
	ds_write_b128 v85, v[108:111] offset:46080
	s_waitcnt lgkmcnt(2)
	v_mfma_f32_32x32x16_bf16 v[34:49], v[184:187], v[136:139], v[34:49]
	global_load_dwordx4 v[176:179], v[80:81], off offset:640
	v_mfma_f32_32x32x16_bf16 v[18:33], v[200:203], v[136:139], v[18:33]
	s_waitcnt vmcnt(8)
	ds_write_b128 v85, v[112:115] offset:13824
	v_mfma_f32_32x32x16_bf16 v[50:65], v[200:203], v[140:143], v[50:65]
	global_load_dwordx4 v[180:183], v[82:83], off offset:640
	v_mfma_f32_32x32x16_bf16 v[2:17], v[184:187], v[140:143], v[2:17]
	s_waitcnt vmcnt(8)
	ds_write_b128 v85, v[116:119] offset:50688
	s_setprio 0
	s_waitcnt lgkmcnt(0)
	s_barrier
	ds_read_b128 v[120:123], v66
	ds_read_b128 v[128:131], v0 offset:36864
	ds_read_b128 v[132:135], v0 offset:41472
	ds_read_b128 v[124:127], v66 offset:4608
	ds_read_b128 v[136:139], v66 offset:32
	ds_read_b128 v[184:187], v0 offset:36896
	ds_read_b128 v[200:203], v0 offset:41504
	ds_read_b128 v[140:143], v66 offset:4640
	s_setprio 1
	s_waitcnt lgkmcnt(4)
	v_mfma_f32_32x32x16_bf16 v[34:49], v[128:131], v[120:123], v[34:49]
	global_load_dwordx4 v[88:91], v[68:69], off offset:768
	v_mfma_f32_32x32x16_bf16 v[18:33], v[132:135], v[120:123], v[18:33]
	s_waitcnt vmcnt(8)
	ds_write_b128 v85, v[152:155] offset:18432
	v_mfma_f32_32x32x16_bf16 v[50:65], v[132:135], v[124:127], v[50:65]
	global_load_dwordx4 v[92:95], v[70:71], off offset:768
	v_mfma_f32_32x32x16_bf16 v[2:17], v[128:131], v[124:127], v[2:17]
	s_waitcnt vmcnt(8)
	ds_write_b128 v85, v[156:159] offset:55296
	ds_read_b128 v[120:123], v66 offset:64
	ds_read_b128 v[128:131], v0 offset:36928
	ds_read_b128 v[132:135], v0 offset:41536
	ds_read_b128 v[124:127], v66 offset:4672
	s_waitcnt lgkmcnt(6)
	v_mfma_f32_32x32x16_bf16 v[34:49], v[184:187], v[136:139], v[34:49]
	global_load_dwordx4 v[96:99], v[72:73], off offset:768
	v_mfma_f32_32x32x16_bf16 v[18:33], v[200:203], v[136:139], v[18:33]
	s_waitcnt vmcnt(8)
	ds_write_b128 v85, v[160:163] offset:23040
	v_mfma_f32_32x32x16_bf16 v[50:65], v[200:203], v[140:143], v[50:65]
	global_load_dwordx4 v[100:103], v[74:75], off offset:768
	v_mfma_f32_32x32x16_bf16 v[2:17], v[184:187], v[140:143], v[2:17]
	s_waitcnt vmcnt(8)
	ds_write_b128 v85, v[164:167] offset:59904
	ds_read_b128 v[136:139], v66 offset:96
	ds_read_b128 v[184:187], v0 offset:36960
	ds_read_b128 v[200:203], v0 offset:41568
	ds_read_b128 v[140:143], v66 offset:4704
	s_waitcnt lgkmcnt(6)
	v_mfma_f32_32x32x16_bf16 v[34:49], v[128:131], v[120:123], v[34:49]
	global_load_dwordx4 v[104:107], v[76:77], off offset:768
	v_mfma_f32_32x32x16_bf16 v[18:33], v[132:135], v[120:123], v[18:33]
	s_waitcnt vmcnt(8)
	ds_write_b128 v85, v[168:171] offset:27648
	v_mfma_f32_32x32x16_bf16 v[50:65], v[132:135], v[124:127], v[50:65]
	global_load_dwordx4 v[108:111], v[78:79], off offset:768
	v_mfma_f32_32x32x16_bf16 v[2:17], v[128:131], v[124:127], v[2:17]
	s_waitcnt vmcnt(8)
	ds_write_b128 v85, v[172:175] offset:64512
	s_waitcnt lgkmcnt(2)
	v_mfma_f32_32x32x16_bf16 v[34:49], v[184:187], v[136:139], v[34:49]
	global_load_dwordx4 v[112:115], v[80:81], off offset:768
	v_mfma_f32_32x32x16_bf16 v[18:33], v[200:203], v[136:139], v[18:33]
	s_waitcnt vmcnt(8)
	ds_write_b128 v85, v[176:179] offset:32256
	v_mfma_f32_32x32x16_bf16 v[50:65], v[200:203], v[140:143], v[50:65]
	global_load_dwordx4 v[116:119], v[82:83], off offset:768
	v_mfma_f32_32x32x16_bf16 v[2:17], v[184:187], v[140:143], v[2:17]
	s_waitcnt vmcnt(8)
	ds_write_b128 v86, v[180:183] offset:32256
	s_setprio 0
	s_waitcnt lgkmcnt(0)
	s_barrier
; #define MFMA(a, b, c) __builtin_amdgcn_mfma_f32_32x32x16_bf16((a), (b), (c), 0, 0, 0)
; template <bool SWAP>
; DI void gemm_block(const bf16_t* __restrict__ A, int lda, const bf16_t* __restrict__ Bt, int ldb, int K, f32x16 (&acc)[2][2], bf16_t* sA, bf16_t* sB) {
;     ...
;   for (int kt = 0; kt < nk; ++kt) {
;     const int cur = kt & 1;
;     const bool more = kt + 1 < nk;
;     if (more) {
;       const int k0 = (kt + 1) * 64;
; #pragma unroll
;       for (int i = 0; i < 4; ++i) { ra[i] = *(const u32x4*)(ga + (size_t)i * 32 * lda + k0); rb[i] = *(const u32x4*)(gb + (size_t)i * 32 * ldb + k0); }
;     }
;     const bf16_t* ab = sA + cur * 128 * LDT + (64 * wr + l32) * LDT + h * 8;
;     const bf16_t* bb = sB + cur * 128 * LDT + (64 * wc + l32) * LDT + h * 8;
;     __builtin_amdgcn_s_setprio(1);
;     __builtin_amdgcn_iglp_opt(0);
; #pragma unroll
;     for (int ks = 0; ks < 4; ++ks) {
;       const bf16x8 a0 = *(const bf16x8*)(ab + ks * 16), a1 = *(const bf16x8*)(ab + 32 * LDT + ks * 16);
;       const bf16x8 b0 = *(const bf16x8*)(bb + ks * 16), b1 = *(const bf16x8*)(bb + 32 * LDT + ks * 16);
;       if (!SWAP) {
;         acc[0][0] = MFMA(a0, b0, acc[0][0]); acc[0][1] = MFMA(a0, b1, acc[0][1]);
;         acc[1][0] = MFMA(a1, b0, acc[1][0]); acc[1][1] = MFMA(a1, b1, acc[1][1]);
;       } else {
;         acc[0][0] = MFMA(b0, a0, acc[0][0]); acc[0][1] = MFMA(b1, a0, acc[0][1]);
;         acc[1][0] = MFMA(b0, a1, acc[1][0]); acc[1][1] = MFMA(b1, a1, acc[1][1]);
;       }
;     }
;     __builtin_amdgcn_s_setprio(0);
;     if (more) {
;       const int nb = (cur ^ 1) * 128 * LDT;
; #pragma unroll
;       for (int i = 0; i < 4; ++i) { *(u32x4*)(sA + nb + soff + i * 32 * LDT) = ra[i]; *(u32x4*)(sB + nb + soff + i * 32 * LDT) = rb[i]; }
;     }
;     __syncthreads();
	ds_read_b128 v[120:123], v66 offset:18432
	ds_read_b128 v[128:131], v0 offset:55296
	ds_read_b128 v[132:135], v0 offset:59904
	ds_read_b128 v[124:127], v66 offset:23040
	ds_read_b128 v[136:139], v66 offset:18464
	ds_read_b128 v[184:187], v0 offset:55328
	ds_read_b128 v[200:203], v0 offset:59936
	ds_read_b128 v[140:143], v66 offset:23072
	s_setprio 1
	s_waitcnt lgkmcnt(4)
	v_mfma_f32_32x32x16_bf16 v[34:49], v[128:131], v[120:123], v[34:49]
	global_load_dwordx4 v[152:155], v[68:69], off offset:896
	v_mfma_f32_32x32x16_bf16 v[18:33], v[132:135], v[120:123], v[18:33]
	s_waitcnt vmcnt(8)
	ds_write_b128 v85, v[88:91]
	v_mfma_f32_32x32x16_bf16 v[50:65], v[132:135], v[124:127], v[50:65]
	global_load_dwordx4 v[156:159], v[70:71], off offset:896
	v_mfma_f32_32x32x16_bf16 v[2:17], v[128:131], v[124:127], v[2:17]
	s_waitcnt vmcnt(8)
	ds_write_b128 v85, v[92:95] offset:36864
	ds_read_b128 v[120:123], v66 offset:18496
	ds_read_b128 v[128:131], v0 offset:55360
	ds_read_b128 v[132:135], v0 offset:59968
	ds_read_b128 v[124:127], v66 offset:23104
	s_waitcnt lgkmcnt(6)
	v_mfma_f32_32x32x16_bf16 v[34:49], v[184:187], v[136:139], v[34:49]
	global_load_dwordx4 v[160:163], v[72:73], off offset:896
	v_mfma_f32_32x32x16_bf16 v[18:33], v[200:203], v[136:139], v[18:33]
	s_waitcnt vmcnt(8)
	ds_write_b128 v85, v[96:99] offset:4608
	v_mfma_f32_32x32x16_bf16 v[50:65], v[200:203], v[140:143], v[50:65]
	global_load_dwordx4 v[164:167], v[74:75], off offset:896
	v_mfma_f32_32x32x16_bf16 v[2:17], v[184:187], v[140:143], v[2:17]
	s_waitcnt vmcnt(8)
	ds_write_b128 v85, v[100:103] offset:41472
	ds_read_b128 v[136:139], v66 offset:18528
	ds_read_b128 v[184:187], v0 offset:55392
	ds_read_b128 v[200:203], v0 offset:60000
	ds_read_b128 v[140:143], v66 offset:23136
	s_waitcnt lgkmcnt(6)
	v_mfma_f32_32x32x16_bf16 v[34:49], v[128:131], v[120:123], v[34:49]
	global_load_dwordx4 v[168:171], v[76:77], off offset:896
	v_mfma_f32_32x32x16_bf16 v[18:33], v[132:135], v[120:123], v[18:33]
	s_waitcnt vmcnt(8)
	ds_write_b128 v85, v[104:107] offset:9216
	v_mfma_f32_32x32x16_bf16 v[50:65], v[132:135], v[124:127], v[50:65]
	global_load_dwordx4 v[172:175], v[78:79], off offset:896
	v_mfma_f32_32x32x16_bf16 v[2:17], v[128:131], v[124:127], v[2:17]
	s_waitcnt vmcnt(8)
	ds_write_b128 v85, v[108:111] offset:46080
	s_waitcnt lgkmcnt(2)
	v_mfma_f32_32x32x16_bf16 v[34:49], v[184:187], v[136:139], v[34:49]
	global_load_dwordx4 v[176:179], v[80:81], off offset:896
	v_mfma_f32_32x32x16_bf16 v[18:33], v[200:203], v[136:139], v[18:33]
	s_waitcnt vmcnt(8)
	ds_write_b128 v85, v[112:115] offset:13824
	v_mfma_f32_32x32x16_bf16 v[50:65], v[200:203], v[140:143], v[50:65]
	global_load_dwordx4 v[180:183], v[82:83], off offset:896
	v_mfma_f32_32x32x16_bf16 v[2:17], v[184:187], v[140:143], v[2:17]
	s_waitcnt vmcnt(8)
	ds_write_b128 v85, v[116:119] offset:50688
	s_setprio 0
	s_waitcnt lgkmcnt(0)
	s_barrier
	ds_read_b128 v[120:123], v66
	ds_read_b128 v[128:131], v0 offset:36864
	ds_read_b128 v[132:135], v0 offset:41472
	ds_read_b128 v[124:127], v66 offset:4608
	ds_read_b128 v[136:139], v66 offset:32
	ds_read_b128 v[184:187], v0 offset:36896
	ds_read_b128 v[200:203], v0 offset:41504
	ds_read_b128 v[140:143], v66 offset:4640
	s_setprio 1
	s_waitcnt lgkmcnt(4)
	v_mfma_f32_32x32x16_bf16 v[34:49], v[128:131], v[120:123], v[34:49]
	global_load_dwordx4 v[88:91], v[68:69], off offset:1024
	v_mfma_f32_32x32x16_bf16 v[18:33], v[132:135], v[120:123], v[18:33]
	s_waitcnt vmcnt(8)
	ds_write_b128 v85, v[152:155] offset:18432
	v_mfma_f32_32x32x16_bf16 v[50:65], v[132:135], v[124:127], v[50:65]
	global_load_dwordx4 v[92:95], v[70:71], off offset:1024
	v_mfma_f32_32x32x16_bf16 v[2:17], v[128:131], v[124:127], v[2:17]
	s_waitcnt vmcnt(8)
	ds_write_b128 v85, v[156:159] offset:55296
	ds_read_b128 v[120:123], v66 offset:64
	ds_read_b128 v[128:131], v0 offset:36928
	ds_read_b128 v[132:135], v0 offset:41536
	ds_read_b128 v[124:127], v66 offset:4672
	s_waitcnt lgkmcnt(6)
	v_mfma_f32_32x32x16_bf16 v[34:49], v[184:187], v[136:139], v[34:49]
	global_load_dwordx4 v[96:99], v[72:73], off offset:1024
	v_mfma_f32_32x32x16_bf16 v[18:33], v[200:203], v[136:139], v[18:33]
	s_waitcnt vmcnt(8)
	ds_write_b128 v85, v[160:163] offset:23040
	v_mfma_f32_32x32x16_bf16 v[50:65], v[200:203], v[140:143], v[50:65]
	global_load_dwordx4 v[100:103], v[74:75], off offset:1024
	v_mfma_f32_32x32x16_bf16 v[2:17], v[184:187], v[140:143], v[2:17]
	s_waitcnt vmcnt(8)
	ds_write_b128 v85, v[164:167] offset:59904
	ds_read_b128 v[136:139], v66 offset:96
	ds_read_b128 v[184:187], v0 offset:36960
	ds_read_b128 v[200:203], v0 offset:41568
	ds_read_b128 v[140:143], v66 offset:4704
	s_waitcnt lgkmcnt(6)
	v_mfma_f32_32x32x16_bf16 v[34:49], v[128:131], v[120:123], v[34:49]
	global_load_dwordx4 v[104:107], v[76:77], off offset:1024
	v_mfma_f32_32x32x16_bf16 v[18:33], v[132:135], v[120:123], v[18:33]
	s_waitcnt vmcnt(8)
	ds_write_b128 v85, v[168:171] offset:27648
	v_mfma_f32_32x32x16_bf16 v[50:65], v[132:135], v[124:127], v[50:65]
	global_load_dwordx4 v[108:111], v[78:79], off offset:1024
	v_mfma_f32_32x32x16_bf16 v[2:17], v[128:131], v[124:127], v[2:17]
	s_waitcnt vmcnt(8)
	ds_write_b128 v85, v[172:175] offset:64512
	s_waitcnt lgkmcnt(2)
	v_mfma_f32_32x32x16_bf16 v[34:49], v[184:187], v[136:139], v[34:49]
	global_load_dwordx4 v[112:115], v[80:81], off offset:1024
	v_mfma_f32_32x32x16_bf16 v[18:33], v[200:203], v[136:139], v[18:33]
	s_waitcnt vmcnt(8)
	ds_write_b128 v85, v[176:179] offset:32256
	v_mfma_f32_32x32x16_bf16 v[50:65], v[200:203], v[140:143], v[50:65]
	global_load_dwordx4 v[116:119], v[82:83], off offset:1024
	v_mfma_f32_32x32x16_bf16 v[2:17], v[184:187], v[140:143], v[2:17]
	s_waitcnt vmcnt(8)
	ds_write_b128 v86, v[180:183] offset:32256
	s_setprio 0
	s_waitcnt lgkmcnt(0)
	s_barrier
; #define MFMA(a, b, c) __builtin_amdgcn_mfma_f32_32x32x16_bf16((a), (b), (c), 0, 0, 0)
; template <bool SWAP>
; DI void gemm_block(const bf16_t* __restrict__ A, int lda, const bf16_t* __restrict__ Bt, int ldb, int K, f32x16 (&acc)[2][2], bf16_t* sA, bf16_t* sB) {
;     ...
;   for (int kt = 0; kt < nk; ++kt) {
;     const int cur = kt & 1;
;     const bool more = kt + 1 < nk;
;     if (more) {
;       const int k0 = (kt + 1) * 64;
; #pragma unroll
;       for (int i = 0; i < 4; ++i) { ra[i] = *(const u32x4*)(ga + (size_t)i * 32 * lda + k0); rb[i] = *(const u32x4*)(gb + (size_t)i * 32 * ldb + k0); }
;     }
;     const bf16_t* ab = sA + cur * 128 * LDT + (64 * wr + l32) * LDT + h * 8;
;     const bf16_t* bb = sB + cur * 128 * LDT + (64 * wc + l32) * LDT + h * 8;
;     __builtin_amdgcn_s_setprio(1);
;     __builtin_amdgcn_iglp_opt(0);
; #pragma unroll
;     for (int ks = 0; ks < 4; ++ks) {
;       const bf16x8 a0 = *(const bf16x8*)(ab + ks * 16), a1 = *(const bf16x8*)(ab + 32 * LDT + ks * 16);
;       const bf16x8 b0 = *(const bf16x8*)(bb + ks * 16), b1 = *(const bf16x8*)(bb + 32 * LDT + ks * 16);
;       if (!SWAP) {
;         acc[0][0] = MFMA(a0, b0, acc[0][0]); acc[0][1] = MFMA(a0, b1, acc[0][1]);
;         acc[1][0] = MFMA(a1, b0, acc[1][0]); acc[1][1] = MFMA(a1, b1, acc[1][1]);
;       } else {
;         acc[0][0] = MFMA(b0, a0, acc[0][0]); acc[0][1] = MFMA(b1, a0, acc[0][1]);
;         acc[1][0] = MFMA(b0, a1, acc[1][0]); acc[1][1] = MFMA(b1, a1, acc[1][1]);
;       }
;     }
;     __builtin_amdgcn_s_setprio(0);
;     if (more) {
;       const int nb = (cur ^ 1) * 128 * LDT;
; #pragma unroll
;       for (int i = 0; i < 4; ++i) { *(u32x4*)(sA + nb + soff + i * 32 * LDT) = ra[i]; *(u32x4*)(sB + nb + soff + i * 32 * LDT) = rb[i]; }
;     }
;     __syncthreads();
	ds_read_b128 v[120:123], v66 offset:18432
	ds_read_b128 v[128:131], v0 offset:55296
	ds_read_b128 v[132:135], v0 offset:59904
	ds_read_b128 v[124:127], v66 offset:23040
	ds_read_b128 v[136:139], v66 offset:18464
	ds_read_b128 v[184:187], v0 offset:55328
	ds_read_b128 v[200:203], v0 offset:59936
	ds_read_b128 v[140:143], v66 offset:23072
	s_setprio 1
	s_waitcnt lgkmcnt(4)
	v_mfma_f32_32x32x16_bf16 v[34:49], v[128:131], v[120:123], v[34:49]
	global_load_dwordx4 v[152:155], v[68:69], off offset:1152
	v_mfma_f32_32x32x16_bf16 v[18:33], v[132:135], v[120:123], v[18:33]
	s_waitcnt vmcnt(8)
	ds_write_b128 v85, v[88:91]
	v_mfma_f32_32x32x16_bf16 v[50:65], v[132:135], v[124:127], v[50:65]
	global_load_dwordx4 v[156:159], v[70:71], off offset:1152
	v_mfma_f32_32x32x16_bf16 v[2:17], v[128:131], v[124:127], v[2:17]
	s_waitcnt vmcnt(8)
	ds_write_b128 v85, v[92:95] offset:36864
	ds_read_b128 v[120:123], v66 offset:18496
	ds_read_b128 v[128:131], v0 offset:55360
	ds_read_b128 v[132:135], v0 offset:59968
	ds_read_b128 v[124:127], v66 offset:23104
	s_waitcnt lgkmcnt(6)
	v_mfma_f32_32x32x16_bf16 v[34:49], v[184:187], v[136:139], v[34:49]
	global_load_dwordx4 v[160:163], v[72:73], off offset:1152
	v_mfma_f32_32x32x16_bf16 v[18:33], v[200:203], v[136:139], v[18:33]
	s_waitcnt vmcnt(8)
	ds_write_b128 v85, v[96:99] offset:4608
	v_mfma_f32_32x32x16_bf16 v[50:65], v[200:203], v[140:143], v[50:65]
	global_load_dwordx4 v[164:167], v[74:75], off offset:1152
	v_mfma_f32_32x32x16_bf16 v[2:17], v[184:187], v[140:143], v[2:17]
	s_waitcnt vmcnt(8)
	ds_write_b128 v85, v[100:103] offset:41472
	ds_read_b128 v[136:139], v66 offset:18528
	ds_read_b128 v[184:187], v0 offset:55392
	ds_read_b128 v[200:203], v0 offset:60000
	ds_read_b128 v[140:143], v66 offset:23136
	s_waitcnt lgkmcnt(6)
	v_mfma_f32_32x32x16_bf16 v[34:49], v[128:131], v[120:123], v[34:49]
	global_load_dwordx4 v[168:171], v[76:77], off offset:1152
	v_mfma_f32_32x32x16_bf16 v[18:33], v[132:135], v[120:123], v[18:33]
	s_waitcnt vmcnt(8)
	ds_write_b128 v85, v[104:107] offset:9216
	v_mfma_f32_32x32x16_bf16 v[50:65], v[132:135], v[124:127], v[50:65]
	global_load_dwordx4 v[172:175], v[78:79], off offset:1152
	v_mfma_f32_32x32x16_bf16 v[2:17], v[128:131], v[124:127], v[2:17]
	s_waitcnt vmcnt(8)
	ds_write_b128 v85, v[108:111] offset:46080
	s_waitcnt lgkmcnt(2)
	v_mfma_f32_32x32x16_bf16 v[34:49], v[184:187], v[136:139], v[34:49]
	global_load_dwordx4 v[176:179], v[80:81], off offset:1152
	v_mfma_f32_32x32x16_bf16 v[18:33], v[200:203], v[136:139], v[18:33]
	s_waitcnt vmcnt(8)
	ds_write_b128 v85, v[112:115] offset:13824
	v_mfma_f32_32x32x16_bf16 v[50:65], v[200:203], v[140:143], v[50:65]
	global_load_dwordx4 v[180:183], v[82:83], off offset:1152
	v_mfma_f32_32x32x16_bf16 v[2:17], v[184:187], v[140:143], v[2:17]
	s_waitcnt vmcnt(8)
	ds_write_b128 v85, v[116:119] offset:50688
	s_setprio 0
	s_waitcnt lgkmcnt(0)
	s_barrier
	ds_read_b128 v[120:123], v66
	ds_read_b128 v[128:131], v0 offset:36864
	ds_read_b128 v[132:135], v0 offset:41472
	ds_read_b128 v[124:127], v66 offset:4608
	ds_read_b128 v[136:139], v66 offset:32
	ds_read_b128 v[184:187], v0 offset:36896
	ds_read_b128 v[200:203], v0 offset:41504
	ds_read_b128 v[140:143], v66 offset:4640
	s_setprio 1
	s_waitcnt lgkmcnt(4)
	v_mfma_f32_32x32x16_bf16 v[34:49], v[128:131], v[120:123], v[34:49]
	global_load_dwordx4 v[88:91], v[68:69], off offset:1280
	v_mfma_f32_32x32x16_bf16 v[18:33], v[132:135], v[120:123], v[18:33]
	s_waitcnt vmcnt(8)
	ds_write_b128 v85, v[152:155] offset:18432
	v_mfma_f32_32x32x16_bf16 v[50:65], v[132:135], v[124:127], v[50:65]
	global_load_dwordx4 v[92:95], v[70:71], off offset:1280
	v_mfma_f32_32x32x16_bf16 v[2:17], v[128:131], v[124:127], v[2:17]
	s_waitcnt vmcnt(8)
	ds_write_b128 v85, v[156:159] offset:55296
	ds_read_b128 v[120:123], v66 offset:64
	ds_read_b128 v[128:131], v0 offset:36928
	ds_read_b128 v[132:135], v0 offset:41536
	ds_read_b128 v[124:127], v66 offset:4672
	s_waitcnt lgkmcnt(6)
	v_mfma_f32_32x32x16_bf16 v[34:49], v[184:187], v[136:139], v[34:49]
	global_load_dwordx4 v[96:99], v[72:73], off offset:1280
	v_mfma_f32_32x32x16_bf16 v[18:33], v[200:203], v[136:139], v[18:33]
	s_waitcnt vmcnt(8)
	ds_write_b128 v85, v[160:163] offset:23040
	v_mfma_f32_32x32x16_bf16 v[50:65], v[200:203], v[140:143], v[50:65]
	global_load_dwordx4 v[100:103], v[74:75], off offset:1280
	v_mfma_f32_32x32x16_bf16 v[2:17], v[184:187], v[140:143], v[2:17]
	s_waitcnt vmcnt(8)
	ds_write_b128 v85, v[164:167] offset:59904
	ds_read_b128 v[136:139], v66 offset:96
	ds_read_b128 v[184:187], v0 offset:36960
	ds_read_b128 v[200:203], v0 offset:41568
	ds_read_b128 v[140:143], v66 offset:4704
	s_waitcnt lgkmcnt(6)
	v_mfma_f32_32x32x16_bf16 v[34:49], v[128:131], v[120:123], v[34:49]
	global_load_dwordx4 v[104:107], v[76:77], off offset:1280
	v_mfma_f32_32x32x16_bf16 v[18:33], v[132:135], v[120:123], v[18:33]
	s_waitcnt vmcnt(8)
	ds_write_b128 v85, v[168:171] offset:27648
	v_mfma_f32_32x32x16_bf16 v[50:65], v[132:135], v[124:127], v[50:65]
	global_load_dwordx4 v[108:111], v[78:79], off offset:1280
	v_mfma_f32_32x32x16_bf16 v[2:17], v[128:131], v[124:127], v[2:17]
	s_waitcnt vmcnt(8)
	ds_write_b128 v85, v[172:175] offset:64512
	s_waitcnt lgkmcnt(2)
	v_mfma_f32_32x32x16_bf16 v[34:49], v[184:187], v[136:139], v[34:49]
	global_load_dwordx4 v[112:115], v[80:81], off offset:1280
	v_mfma_f32_32x32x16_bf16 v[18:33], v[200:203], v[136:139], v[18:33]
	s_waitcnt vmcnt(8)
	ds_write_b128 v85, v[176:179] offset:32256
	v_mfma_f32_32x32x16_bf16 v[50:65], v[200:203], v[140:143], v[50:65]
	global_load_dwordx4 v[116:119], v[82:83], off offset:1280
	v_mfma_f32_32x32x16_bf16 v[2:17], v[184:187], v[140:143], v[2:17]
	s_waitcnt vmcnt(8)
	ds_write_b128 v86, v[180:183] offset:32256
	s_setprio 0
	s_waitcnt lgkmcnt(0)
	s_barrier
; #define MFMA(a, b, c) __builtin_amdgcn_mfma_f32_32x32x16_bf16((a), (b), (c), 0, 0, 0)
; template <bool SWAP>
; DI void gemm_block(const bf16_t* __restrict__ A, int lda, const bf16_t* __restrict__ Bt, int ldb, int K, f32x16 (&acc)[2][2], bf16_t* sA, bf16_t* sB) {
;     ...
;   for (int kt = 0; kt < nk; ++kt) {
;     const int cur = kt & 1;
;     const bool more = kt + 1 < nk;
;     if (more) {
;       const int k0 = (kt + 1) * 64;
; #pragma unroll
;       for (int i = 0; i < 4; ++i) { ra[i] = *(const u32x4*)(ga + (size_t)i * 32 * lda + k0); rb[i] = *(const u32x4*)(gb + (size_t)i * 32 * ldb + k0); }
;     }
;     const bf16_t* ab = sA + cur * 128 * LDT + (64 * wr + l32) * LDT + h * 8;
;     const bf16_t* bb = sB + cur * 128 * LDT + (64 * wc + l32) * LDT + h * 8;
;     __builtin_amdgcn_s_setprio(1);
;     __builtin_amdgcn_iglp_opt(0);
; #pragma unroll
;     for (int ks = 0; ks < 4; ++ks) {
;       const bf16x8 a0 = *(const bf16x8*)(ab + ks * 16), a1 = *(const bf16x8*)(ab + 32 * LDT + ks * 16);
;       const bf16x8 b0 = *(const bf16x8*)(bb + ks * 16), b1 = *(const bf16x8*)(bb + 32 * LDT + ks * 16);
;       if (!SWAP) {
;         acc[0][0] = MFMA(a0, b0, acc[0][0]); acc[0][1] = MFMA(a0, b1, acc[0][1]);
;         acc[1][0] = MFMA(a1, b0, acc[1][0]); acc[1][1] = MFMA(a1, b1, acc[1][1]);
;       } else {
;         acc[0][0] = MFMA(b0, a0, acc[0][0]); acc[0][1] = MFMA(b1, a0, acc[0][1]);
;         acc[1][0] = MFMA(b0, a1, acc[1][0]); acc[1][1] = MFMA(b1, a1, acc[1][1]);
;       }
;     }
;     __builtin_amdgcn_s_setprio(0);
;     if (more) {
;       const int nb = (cur ^ 1) * 128 * LDT;
; #pragma unroll
;       for (int i = 0; i < 4; ++i) { *(u32x4*)(sA + nb + soff + i * 32 * LDT) = ra[i]; *(u32x4*)(sB + nb + soff + i * 32 * LDT) = rb[i]; }
;     }
;     __syncthreads();
	ds_read_b128 v[120:123], v66 offset:18432
	ds_read_b128 v[128:131], v0 offset:55296
	ds_read_b128 v[132:135], v0 offset:59904
	ds_read_b128 v[124:127], v66 offset:23040
	ds_read_b128 v[136:139], v66 offset:18464
	ds_read_b128 v[184:187], v0 offset:55328
	ds_read_b128 v[200:203], v0 offset:59936
	ds_read_b128 v[140:143], v66 offset:23072
	s_setprio 1
	s_waitcnt lgkmcnt(4)
	v_mfma_f32_32x32x16_bf16 v[34:49], v[128:131], v[120:123], v[34:49]
	global_load_dwordx4 v[152:155], v[68:69], off offset:1408
	v_mfma_f32_32x32x16_bf16 v[18:33], v[132:135], v[120:123], v[18:33]
	s_waitcnt vmcnt(8)
	ds_write_b128 v85, v[88:91]
	v_mfma_f32_32x32x16_bf16 v[50:65], v[132:135], v[124:127], v[50:65]
	global_load_dwordx4 v[156:159], v[70:71], off offset:1408
	v_mfma_f32_32x32x16_bf16 v[2:17], v[128:131], v[124:127], v[2:17]
	s_waitcnt vmcnt(8)
	ds_write_b128 v85, v[92:95] offset:36864
	ds_read_b128 v[120:123], v66 offset:18496
	ds_read_b128 v[128:131], v0 offset:55360
	ds_read_b128 v[132:135], v0 offset:59968
	ds_read_b128 v[124:127], v66 offset:23104
	s_waitcnt lgkmcnt(6)
	v_mfma_f32_32x32x16_bf16 v[34:49], v[184:187], v[136:139], v[34:49]
	global_load_dwordx4 v[160:163], v[72:73], off offset:1408
	v_mfma_f32_32x32x16_bf16 v[18:33], v[200:203], v[136:139], v[18:33]
	s_waitcnt vmcnt(8)
	ds_write_b128 v85, v[96:99] offset:4608
	v_mfma_f32_32x32x16_bf16 v[50:65], v[200:203], v[140:143], v[50:65]
	global_load_dwordx4 v[164:167], v[74:75], off offset:1408
	v_mfma_f32_32x32x16_bf16 v[2:17], v[184:187], v[140:143], v[2:17]
	s_waitcnt vmcnt(8)
	ds_write_b128 v85, v[100:103] offset:41472
	ds_read_b128 v[136:139], v66 offset:18528
	ds_read_b128 v[184:187], v0 offset:55392
	ds_read_b128 v[200:203], v0 offset:60000
	ds_read_b128 v[140:143], v66 offset:23136
	s_waitcnt lgkmcnt(6)
	v_mfma_f32_32x32x16_bf16 v[34:49], v[128:131], v[120:123], v[34:49]
	global_load_dwordx4 v[168:171], v[76:77], off offset:1408
	v_mfma_f32_32x32x16_bf16 v[18:33], v[132:135], v[120:123], v[18:33]
	s_waitcnt vmcnt(8)
	ds_write_b128 v85, v[104:107] offset:9216
	v_mfma_f32_32x32x16_bf16 v[50:65], v[132:135], v[124:127], v[50:65]
	global_load_dwordx4 v[172:175], v[78:79], off offset:1408
	v_mfma_f32_32x32x16_bf16 v[2:17], v[128:131], v[124:127], v[2:17]
	s_waitcnt vmcnt(8)
	ds_write_b128 v85, v[108:111] offset:46080
	s_waitcnt lgkmcnt(2)
	v_mfma_f32_32x32x16_bf16 v[34:49], v[184:187], v[136:139], v[34:49]
	global_load_dwordx4 v[176:179], v[80:81], off offset:1408
	v_mfma_f32_32x32x16_bf16 v[18:33], v[200:203], v[136:139], v[18:33]
	s_waitcnt vmcnt(8)
	ds_write_b128 v85, v[112:115] offset:13824
	v_mfma_f32_32x32x16_bf16 v[50:65], v[200:203], v[140:143], v[50:65]
	global_load_dwordx4 v[180:183], v[82:83], off offset:1408
	v_mfma_f32_32x32x16_bf16 v[2:17], v[184:187], v[140:143], v[2:17]
	s_waitcnt vmcnt(8)
	ds_write_b128 v85, v[116:119] offset:50688
	s_setprio 0
	s_waitcnt lgkmcnt(0)
	s_barrier
	ds_read_b128 v[120:123], v66
	ds_read_b128 v[128:131], v0 offset:36864
	ds_read_b128 v[132:135], v0 offset:41472
	ds_read_b128 v[124:127], v66 offset:4608
	ds_read_b128 v[136:139], v66 offset:32
	ds_read_b128 v[184:187], v0 offset:36896
	ds_read_b128 v[200:203], v0 offset:41504
	ds_read_b128 v[140:143], v66 offset:4640
	s_setprio 1
	s_waitcnt lgkmcnt(4)
	v_mfma_f32_32x32x16_bf16 v[34:49], v[128:131], v[120:123], v[34:49]
	global_load_dwordx4 v[88:91], v[68:69], off offset:1536
	v_mfma_f32_32x32x16_bf16 v[18:33], v[132:135], v[120:123], v[18:33]
	s_waitcnt vmcnt(8)
	ds_write_b128 v85, v[152:155] offset:18432
	v_mfma_f32_32x32x16_bf16 v[50:65], v[132:135], v[124:127], v[50:65]
	global_load_dwordx4 v[92:95], v[70:71], off offset:1536
	v_mfma_f32_32x32x16_bf16 v[2:17], v[128:131], v[124:127], v[2:17]
	s_waitcnt vmcnt(8)
	ds_write_b128 v85, v[156:159] offset:55296
	ds_read_b128 v[120:123], v66 offset:64
	ds_read_b128 v[128:131], v0 offset:36928
	ds_read_b128 v[132:135], v0 offset:41536
	ds_read_b128 v[124:127], v66 offset:4672
	s_waitcnt lgkmcnt(6)
	v_mfma_f32_32x32x16_bf16 v[34:49], v[184:187], v[136:139], v[34:49]
	global_load_dwordx4 v[96:99], v[72:73], off offset:1536
	v_mfma_f32_32x32x16_bf16 v[18:33], v[200:203], v[136:139], v[18:33]
	s_waitcnt vmcnt(8)
	ds_write_b128 v85, v[160:163] offset:23040
	v_mfma_f32_32x32x16_bf16 v[50:65], v[200:203], v[140:143], v[50:65]
	global_load_dwordx4 v[100:103], v[74:75], off offset:1536
	v_mfma_f32_32x32x16_bf16 v[2:17], v[184:187], v[140:143], v[2:17]
	s_waitcnt vmcnt(8)
	ds_write_b128 v85, v[164:167] offset:59904
	ds_read_b128 v[136:139], v66 offset:96
	ds_read_b128 v[184:187], v0 offset:36960
	ds_read_b128 v[200:203], v0 offset:41568
	ds_read_b128 v[140:143], v66 offset:4704
	s_waitcnt lgkmcnt(6)
	v_mfma_f32_32x32x16_bf16 v[34:49], v[128:131], v[120:123], v[34:49]
	global_load_dwordx4 v[104:107], v[76:77], off offset:1536
	v_mfma_f32_32x32x16_bf16 v[18:33], v[132:135], v[120:123], v[18:33]
	s_waitcnt vmcnt(8)
	ds_write_b128 v85, v[168:171] offset:27648
	v_mfma_f32_32x32x16_bf16 v[50:65], v[132:135], v[124:127], v[50:65]
	global_load_dwordx4 v[108:111], v[78:79], off offset:1536
	v_mfma_f32_32x32x16_bf16 v[2:17], v[128:131], v[124:127], v[2:17]
	s_waitcnt vmcnt(8)
	ds_write_b128 v85, v[172:175] offset:64512
	s_waitcnt lgkmcnt(2)
	v_mfma_f32_32x32x16_bf16 v[34:49], v[184:187], v[136:139], v[34:49]
	global_load_dwordx4 v[112:115], v[80:81], off offset:1536
	v_mfma_f32_32x32x16_bf16 v[18:33], v[200:203], v[136:139], v[18:33]
	s_waitcnt vmcnt(8)
	ds_write_b128 v85, v[176:179] offset:32256
	v_mfma_f32_32x32x16_bf16 v[50:65], v[200:203], v[140:143], v[50:65]
	global_load_dwordx4 v[116:119], v[82:83], off offset:1536
	v_mfma_f32_32x32x16_bf16 v[2:17], v[184:187], v[140:143], v[2:17]
	s_waitcnt vmcnt(8)
	ds_write_b128 v86, v[180:183] offset:32256
	s_setprio 0
	s_waitcnt lgkmcnt(0)
	s_barrier
; #define MFMA(a, b, c) __builtin_amdgcn_mfma_f32_32x32x16_bf16((a), (b), (c), 0, 0, 0)
; template <bool SWAP>
; DI void gemm_block(const bf16_t* __restrict__ A, int lda, const bf16_t* __restrict__ Bt, int ldb, int K, f32x16 (&acc)[2][2], bf16_t* sA, bf16_t* sB) {
;     ...
;   for (int kt = 0; kt < nk; ++kt) {
;     const int cur = kt & 1;
;     const bool more = kt + 1 < nk;
;     if (more) {
;       const int k0 = (kt + 1) * 64;
; #pragma unroll
;       for (int i = 0; i < 4; ++i) { ra[i] = *(const u32x4*)(ga + (size_t)i * 32 * lda + k0); rb[i] = *(const u32x4*)(gb + (size_t)i * 32 * ldb + k0); }
;     }
;     const bf16_t* ab = sA + cur * 128 * LDT + (64 * wr + l32) * LDT + h * 8;
;     const bf16_t* bb = sB + cur * 128 * LDT + (64 * wc + l32) * LDT + h * 8;
;     __builtin_amdgcn_s_setprio(1);
;     __builtin_amdgcn_iglp_opt(0);
; #pragma unroll
;     for (int ks = 0; ks < 4; ++ks) {
;       const bf16x8 a0 = *(const bf16x8*)(ab + ks * 16), a1 = *(const bf16x8*)(ab + 32 * LDT + ks * 16);
;       const bf16x8 b0 = *(const bf16x8*)(bb + ks * 16), b1 = *(const bf16x8*)(bb + 32 * LDT + ks * 16);
;       if (!SWAP) {
;         acc[0][0] = MFMA(a0, b0, acc[0][0]); acc[0][1] = MFMA(a0, b1, acc[0][1]);
;         acc[1][0] = MFMA(a1, b0, acc[1][0]); acc[1][1] = MFMA(a1, b1, acc[1][1]);
;       } else {
;         acc[0][0] = MFMA(b0, a0, acc[0][0]); acc[0][1] = MFMA(b1, a0, acc[0][1]);
;         acc[1][0] = MFMA(b0, a1, acc[1][0]); acc[1][1] = MFMA(b1, a1, acc[1][1]);
;       }
;     }
;     __builtin_amdgcn_s_setprio(0);
;     if (more) {
;       const int nb = (cur ^ 1) * 128 * LDT;
; #pragma unroll
;       for (int i = 0; i < 4; ++i) { *(u32x4*)(sA + nb + soff + i * 32 * LDT) = ra[i]; *(u32x4*)(sB + nb + soff + i * 32 * LDT) = rb[i]; }
;     }
;     __syncthreads();
	ds_read_b128 v[120:123], v66 offset:18432
	ds_read_b128 v[128:131], v0 offset:55296
	ds_read_b128 v[132:135], v0 offset:59904
	ds_read_b128 v[124:127], v66 offset:23040
	ds_read_b128 v[136:139], v66 offset:18464
	ds_read_b128 v[184:187], v0 offset:55328
	ds_read_b128 v[200:203], v0 offset:59936
	ds_read_b128 v[140:143], v66 offset:23072
	s_setprio 1
	s_waitcnt lgkmcnt(4)
	v_mfma_f32_32x32x16_bf16 v[34:49], v[128:131], v[120:123], v[34:49]
	global_load_dwordx4 v[152:155], v[68:69], off offset:1664
	v_mfma_f32_32x32x16_bf16 v[18:33], v[132:135], v[120:123], v[18:33]
	s_waitcnt vmcnt(8)
	ds_write_b128 v85, v[88:91]
	v_mfma_f32_32x32x16_bf16 v[50:65], v[132:135], v[124:127], v[50:65]
	global_load_dwordx4 v[156:159], v[70:71], off offset:1664
	v_mfma_f32_32x32x16_bf16 v[2:17], v[128:131], v[124:127], v[2:17]
	s_waitcnt vmcnt(8)
	ds_write_b128 v85, v[92:95] offset:36864
	ds_read_b128 v[120:123], v66 offset:18496
	ds_read_b128 v[128:131], v0 offset:55360
	ds_read_b128 v[132:135], v0 offset:59968
	ds_read_b128 v[124:127], v66 offset:23104
	s_waitcnt lgkmcnt(6)
	v_mfma_f32_32x32x16_bf16 v[34:49], v[184:187], v[136:139], v[34:49]
	global_load_dwordx4 v[160:163], v[72:73], off offset:1664
	v_mfma_f32_32x32x16_bf16 v[18:33], v[200:203], v[136:139], v[18:33]
	s_waitcnt vmcnt(8)
	ds_write_b128 v85, v[96:99] offset:4608
	v_mfma_f32_32x32x16_bf16 v[50:65], v[200:203], v[140:143], v[50:65]
	global_load_dwordx4 v[164:167], v[74:75], off offset:1664
	v_mfma_f32_32x32x16_bf16 v[2:17], v[184:187], v[140:143], v[2:17]
	s_waitcnt vmcnt(8)
	ds_write_b128 v85, v[100:103] offset:41472
	ds_read_b128 v[136:139], v66 offset:18528
	ds_read_b128 v[184:187], v0 offset:55392
	ds_read_b128 v[200:203], v0 offset:60000
	ds_read_b128 v[140:143], v66 offset:23136
	s_waitcnt lgkmcnt(6)
	v_mfma_f32_32x32x16_bf16 v[34:49], v[128:131], v[120:123], v[34:49]
	global_load_dwordx4 v[168:171], v[76:77], off offset:1664
	v_mfma_f32_32x32x16_bf16 v[18:33], v[132:135], v[120:123], v[18:33]
	s_waitcnt vmcnt(8)
	ds_write_b128 v85, v[104:107] offset:9216
	v_mfma_f32_32x32x16_bf16 v[50:65], v[132:135], v[124:127], v[50:65]
	global_load_dwordx4 v[172:175], v[78:79], off offset:1664
	v_mfma_f32_32x32x16_bf16 v[2:17], v[128:131], v[124:127], v[2:17]
	s_waitcnt vmcnt(8)
	ds_write_b128 v85, v[108:111] offset:46080
	s_waitcnt lgkmcnt(2)
	v_mfma_f32_32x32x16_bf16 v[34:49], v[184:187], v[136:139], v[34:49]
	global_load_dwordx4 v[176:179], v[80:81], off offset:1664
	v_mfma_f32_32x32x16_bf16 v[18:33], v[200:203], v[136:139], v[18:33]
	s_waitcnt vmcnt(8)
	ds_write_b128 v85, v[112:115] offset:13824
	v_mfma_f32_32x32x16_bf16 v[50:65], v[200:203], v[140:143], v[50:65]
	global_load_dwordx4 v[180:183], v[82:83], off offset:1664
	v_mfma_f32_32x32x16_bf16 v[2:17], v[184:187], v[140:143], v[2:17]
	s_waitcnt vmcnt(8)
	ds_write_b128 v85, v[116:119] offset:50688
	s_setprio 0
	s_waitcnt lgkmcnt(0)
	s_barrier
	ds_read_b128 v[120:123], v66
	ds_read_b128 v[128:131], v0 offset:36864
	ds_read_b128 v[132:135], v0 offset:41472
	ds_read_b128 v[124:127], v66 offset:4608
	ds_read_b128 v[136:139], v66 offset:32
	ds_read_b128 v[184:187], v0 offset:36896
	ds_read_b128 v[200:203], v0 offset:41504
	ds_read_b128 v[140:143], v66 offset:4640
	s_setprio 1
	s_waitcnt lgkmcnt(4)
	v_mfma_f32_32x32x16_bf16 v[34:49], v[128:131], v[120:123], v[34:49]
	global_load_dwordx4 v[88:91], v[68:69], off offset:1792
	v_mfma_f32_32x32x16_bf16 v[18:33], v[132:135], v[120:123], v[18:33]
	s_waitcnt vmcnt(8)
	ds_write_b128 v85, v[152:155] offset:18432
	v_mfma_f32_32x32x16_bf16 v[50:65], v[132:135], v[124:127], v[50:65]
	global_load_dwordx4 v[92:95], v[70:71], off offset:1792
	v_mfma_f32_32x32x16_bf16 v[2:17], v[128:131], v[124:127], v[2:17]
	s_waitcnt vmcnt(8)
	ds_write_b128 v85, v[156:159] offset:55296
	ds_read_b128 v[120:123], v66 offset:64
	ds_read_b128 v[128:131], v0 offset:36928
	ds_read_b128 v[132:135], v0 offset:41536
	ds_read_b128 v[124:127], v66 offset:4672
	s_waitcnt lgkmcnt(6)
	v_mfma_f32_32x32x16_bf16 v[34:49], v[184:187], v[136:139], v[34:49]
	global_load_dwordx4 v[96:99], v[72:73], off offset:1792
	v_mfma_f32_32x32x16_bf16 v[18:33], v[200:203], v[136:139], v[18:33]
	s_waitcnt vmcnt(8)
	ds_write_b128 v85, v[160:163] offset:23040
	v_mfma_f32_32x32x16_bf16 v[50:65], v[200:203], v[140:143], v[50:65]
	global_load_dwordx4 v[100:103], v[74:75], off offset:1792
	v_mfma_f32_32x32x16_bf16 v[2:17], v[184:187], v[140:143], v[2:17]
	s_waitcnt vmcnt(8)
	ds_write_b128 v85, v[164:167] offset:59904
	ds_read_b128 v[136:139], v66 offset:96
	ds_read_b128 v[184:187], v0 offset:36960
	ds_read_b128 v[200:203], v0 offset:41568
	ds_read_b128 v[140:143], v66 offset:4704
	s_waitcnt lgkmcnt(6)
	v_mfma_f32_32x32x16_bf16 v[34:49], v[128:131], v[120:123], v[34:49]
	global_load_dwordx4 v[104:107], v[76:77], off offset:1792
	v_mfma_f32_32x32x16_bf16 v[18:33], v[132:135], v[120:123], v[18:33]
	s_waitcnt vmcnt(8)
	ds_write_b128 v85, v[168:171] offset:27648
	v_mfma_f32_32x32x16_bf16 v[50:65], v[132:135], v[124:127], v[50:65]
	global_load_dwordx4 v[108:111], v[78:79], off offset:1792
	v_mfma_f32_32x32x16_bf16 v[2:17], v[128:131], v[124:127], v[2:17]
	s_waitcnt vmcnt(8)
	ds_write_b128 v85, v[172:175] offset:64512
	s_waitcnt lgkmcnt(2)
	v_mfma_f32_32x32x16_bf16 v[34:49], v[184:187], v[136:139], v[34:49]
	global_load_dwordx4 v[112:115], v[80:81], off offset:1792
	v_mfma_f32_32x32x16_bf16 v[18:33], v[200:203], v[136:139], v[18:33]
	s_waitcnt vmcnt(8)
	ds_write_b128 v85, v[176:179] offset:32256
	v_mfma_f32_32x32x16_bf16 v[50:65], v[200:203], v[140:143], v[50:65]
	global_load_dwordx4 v[116:119], v[82:83], off offset:1792
	v_mfma_f32_32x32x16_bf16 v[2:17], v[184:187], v[140:143], v[2:17]
	s_waitcnt vmcnt(8)
	ds_write_b128 v86, v[180:183] offset:32256
	s_setprio 0
	s_waitcnt lgkmcnt(0)
	s_barrier
; #define MFMA(a, b, c) __builtin_amdgcn_mfma_f32_32x32x16_bf16((a), (b), (c), 0, 0, 0)
; template <bool SWAP>
; DI void gemm_block(const bf16_t* __restrict__ A, int lda, const bf16_t* __restrict__ Bt, int ldb, int K, f32x16 (&acc)[2][2], bf16_t* sA, bf16_t* sB) {
;     ...
;   for (int kt = 0; kt < nk; ++kt) {
;     const int cur = kt & 1;
;     const bool more = kt + 1 < nk;
;     if (more) {
;       const int k0 = (kt + 1) * 64;
; #pragma unroll
;       for (int i = 0; i < 4; ++i) { ra[i] = *(const u32x4*)(ga + (size_t)i * 32 * lda + k0); rb[i] = *(const u32x4*)(gb + (size_t)i * 32 * ldb + k0); }
;     }
;     const bf16_t* ab = sA + cur * 128 * LDT + (64 * wr + l32) * LDT + h * 8;
;     const bf16_t* bb = sB + cur * 128 * LDT + (64 * wc + l32) * LDT + h * 8;
;     __builtin_amdgcn_s_setprio(1);
;     __builtin_amdgcn_iglp_opt(0);
; #pragma unroll
;     for (int ks = 0; ks < 4; ++ks) {
;       const bf16x8 a0 = *(const bf16x8*)(ab + ks * 16), a1 = *(const bf16x8*)(ab + 32 * LDT + ks * 16);
;       const bf16x8 b0 = *(const bf16x8*)(bb + ks * 16), b1 = *(const bf16x8*)(bb + 32 * LDT + ks * 16);
;       if (!SWAP) {
;         acc[0][0] = MFMA(a0, b0, acc[0][0]); acc[0][1] = MFMA(a0, b1, acc[0][1]);
;         acc[1][0] = MFMA(a1, b0, acc[1][0]); acc[1][1] = MFMA(a1, b1, acc[1][1]);
;       } else {
;         acc[0][0] = MFMA(b0, a0, acc[0][0]); acc[0][1] = MFMA(b1, a0, acc[0][1]);
;         acc[1][0] = MFMA(b0, a1, acc[1][0]); acc[1][1] = MFMA(b1, a1, acc[1][1]);
;       }
;     }
;     __builtin_amdgcn_s_setprio(0);
;     if (more) {
;       const int nb = (cur ^ 1) * 128 * LDT;
; #pragma unroll
;       for (int i = 0; i < 4; ++i) { *(u32x4*)(sA + nb + soff + i * 32 * LDT) = ra[i]; *(u32x4*)(sB + nb + soff + i * 32 * LDT) = rb[i]; }
;     }
;     __syncthreads();
	ds_read_b128 v[120:123], v66 offset:18432
	ds_read_b128 v[128:131], v0 offset:55296
	ds_read_b128 v[132:135], v0 offset:59904
	ds_read_b128 v[124:127], v66 offset:23040
	ds_read_b128 v[136:139], v66 offset:18464
	ds_read_b128 v[184:187], v0 offset:55328
	ds_read_b128 v[200:203], v0 offset:59936
	ds_read_b128 v[140:143], v66 offset:23072
	s_setprio 1
	s_waitcnt lgkmcnt(4)
	v_mfma_f32_32x32x16_bf16 v[34:49], v[128:131], v[120:123], v[34:49]
	global_load_dwordx4 v[152:155], v[68:69], off offset:1920
	v_mfma_f32_32x32x16_bf16 v[18:33], v[132:135], v[120:123], v[18:33]
	s_waitcnt vmcnt(8)
	ds_write_b128 v85, v[88:91]
	v_mfma_f32_32x32x16_bf16 v[50:65], v[132:135], v[124:127], v[50:65]
	global_load_dwordx4 v[156:159], v[70:71], off offset:1920
	v_mfma_f32_32x32x16_bf16 v[2:17], v[128:131], v[124:127], v[2:17]
	s_waitcnt vmcnt(8)
	ds_write_b128 v85, v[92:95] offset:36864
	ds_read_b128 v[120:123], v66 offset:18496
	ds_read_b128 v[128:131], v0 offset:55360
	ds_read_b128 v[132:135], v0 offset:59968
	ds_read_b128 v[124:127], v66 offset:23104
	s_waitcnt lgkmcnt(6)
	v_mfma_f32_32x32x16_bf16 v[34:49], v[184:187], v[136:139], v[34:49]
	global_load_dwordx4 v[160:163], v[72:73], off offset:1920
	v_mfma_f32_32x32x16_bf16 v[18:33], v[200:203], v[136:139], v[18:33]
	s_waitcnt vmcnt(8)
	ds_write_b128 v85, v[96:99] offset:4608
	v_mfma_f32_32x32x16_bf16 v[50:65], v[200:203], v[140:143], v[50:65]
	global_load_dwordx4 v[164:167], v[74:75], off offset:1920
	v_mfma_f32_32x32x16_bf16 v[2:17], v[184:187], v[140:143], v[2:17]
	s_waitcnt vmcnt(8)
	ds_write_b128 v85, v[100:103] offset:41472
	ds_read_b128 v[136:139], v66 offset:18528
	ds_read_b128 v[184:187], v0 offset:55392
	ds_read_b128 v[200:203], v0 offset:60000
	ds_read_b128 v[140:143], v66 offset:23136
	s_waitcnt lgkmcnt(6)
	v_mfma_f32_32x32x16_bf16 v[34:49], v[128:131], v[120:123], v[34:49]
	global_load_dwordx4 v[168:171], v[76:77], off offset:1920
	v_mfma_f32_32x32x16_bf16 v[18:33], v[132:135], v[120:123], v[18:33]
	s_waitcnt vmcnt(8)
	ds_write_b128 v85, v[104:107] offset:9216
	v_mfma_f32_32x32x16_bf16 v[50:65], v[132:135], v[124:127], v[50:65]
	global_load_dwordx4 v[172:175], v[78:79], off offset:1920
	v_mfma_f32_32x32x16_bf16 v[2:17], v[128:131], v[124:127], v[2:17]
	s_waitcnt vmcnt(8)
	ds_write_b128 v85, v[108:111] offset:46080
	s_waitcnt lgkmcnt(2)
	v_mfma_f32_32x32x16_bf16 v[34:49], v[184:187], v[136:139], v[34:49]
	global_load_dwordx4 v[176:179], v[80:81], off offset:1920
	v_mfma_f32_32x32x16_bf16 v[18:33], v[200:203], v[136:139], v[18:33]
	s_waitcnt vmcnt(8)
	ds_write_b128 v85, v[112:115] offset:13824
	v_mfma_f32_32x32x16_bf16 v[50:65], v[200:203], v[140:143], v[50:65]
	global_load_dwordx4 v[180:183], v[82:83], off offset:1920
	v_mfma_f32_32x32x16_bf16 v[2:17], v[184:187], v[140:143], v[2:17]
	s_waitcnt vmcnt(8)
	ds_write_b128 v85, v[116:119] offset:50688
	s_setprio 0
	s_waitcnt lgkmcnt(0)
	s_barrier
	ds_read_b128 v[120:123], v66
	ds_read_b128 v[128:131], v0 offset:36864
	ds_read_b128 v[132:135], v0 offset:41472
	ds_read_b128 v[124:127], v66 offset:4608
	ds_read_b128 v[136:139], v66 offset:32
	ds_read_b128 v[184:187], v0 offset:36896
	ds_read_b128 v[200:203], v0 offset:41504
	ds_read_b128 v[140:143], v66 offset:4640
	s_setprio 1
	s_waitcnt lgkmcnt(4)
	v_mfma_f32_32x32x16_bf16 v[34:49], v[128:131], v[120:123], v[34:49]
	v_mfma_f32_32x32x16_bf16 v[18:33], v[132:135], v[120:123], v[18:33]
	s_waitcnt vmcnt(7)
	ds_write_b128 v85, v[152:155] offset:18432
	v_mfma_f32_32x32x16_bf16 v[50:65], v[132:135], v[124:127], v[50:65]
	v_mfma_f32_32x32x16_bf16 v[2:17], v[128:131], v[124:127], v[2:17]
	s_waitcnt vmcnt(6)
	ds_write_b128 v85, v[156:159] offset:55296
	ds_read_b128 v[120:123], v66 offset:64
	ds_read_b128 v[128:131], v0 offset:36928
	ds_read_b128 v[132:135], v0 offset:41536
	ds_read_b128 v[124:127], v66 offset:4672
	s_waitcnt lgkmcnt(6)
	v_mfma_f32_32x32x16_bf16 v[34:49], v[184:187], v[136:139], v[34:49]
	v_mfma_f32_32x32x16_bf16 v[18:33], v[200:203], v[136:139], v[18:33]
	s_waitcnt vmcnt(5)
	ds_write_b128 v85, v[160:163] offset:23040
	v_mfma_f32_32x32x16_bf16 v[50:65], v[200:203], v[140:143], v[50:65]
	v_mfma_f32_32x32x16_bf16 v[2:17], v[184:187], v[140:143], v[2:17]
	s_waitcnt vmcnt(4)
	ds_write_b128 v85, v[164:167] offset:59904
	ds_read_b128 v[136:139], v66 offset:96
	ds_read_b128 v[184:187], v0 offset:36960
	ds_read_b128 v[200:203], v0 offset:41568
	ds_read_b128 v[140:143], v66 offset:4704
	s_waitcnt lgkmcnt(6)
	v_mfma_f32_32x32x16_bf16 v[34:49], v[128:131], v[120:123], v[34:49]
	v_mfma_f32_32x32x16_bf16 v[18:33], v[132:135], v[120:123], v[18:33]
	s_waitcnt vmcnt(3)
	ds_write_b128 v85, v[168:171] offset:27648
	v_mfma_f32_32x32x16_bf16 v[50:65], v[132:135], v[124:127], v[50:65]
	v_mfma_f32_32x32x16_bf16 v[2:17], v[128:131], v[124:127], v[2:17]
	s_waitcnt vmcnt(2)
	ds_write_b128 v85, v[172:175] offset:64512
	s_waitcnt lgkmcnt(2)
	v_mfma_f32_32x32x16_bf16 v[34:49], v[184:187], v[136:139], v[34:49]
	v_mfma_f32_32x32x16_bf16 v[18:33], v[200:203], v[136:139], v[18:33]
	s_waitcnt vmcnt(1)
	ds_write_b128 v85, v[176:179] offset:32256
	v_mfma_f32_32x32x16_bf16 v[50:65], v[200:203], v[140:143], v[50:65]
	v_mfma_f32_32x32x16_bf16 v[2:17], v[184:187], v[140:143], v[2:17]
	s_waitcnt vmcnt(0)
	ds_write_b128 v86, v[180:183] offset:32256
	s_setprio 0
	s_waitcnt lgkmcnt(0)
	s_barrier
; #define MFMA(a, b, c) __builtin_amdgcn_mfma_f32_32x32x16_bf16((a), (b), (c), 0, 0, 0)
; template <bool SWAP>
; DI void gemm_block(const bf16_t* __restrict__ A, int lda, const bf16_t* __restrict__ Bt, int ldb, int K, f32x16 (&acc)[2][2], bf16_t* sA, bf16_t* sB) {
;     ...
;   const int lrow = tid >> 3, lch = (tid & 7) * 8;
;   const bf16_t* ga = A + (size_t)lrow * lda + lch;
;   const bf16_t* gb = Bt + (size_t)lrow * ldb + lch;
;   const int soff = lrow * LDT + lch;
;   u32x4 ra[4], rb[4];
; #pragma unroll
;   for (int i = 0; i < 4; ++i) { ra[i] = *(const u32x4*)(ga + (size_t)i * 32 * lda); rb[i] = *(const u32x4*)(gb + (size_t)i * 32 * ldb); }
; #pragma unroll
;   for (int i = 0; i < 4; ++i) { *(u32x4*)(sA + soff + i * 32 * LDT) = ra[i]; *(u32x4*)(sB + soff + i * 32 * LDT) = rb[i]; }
;   __syncthreads();
;     ...
;   for (int kt = 0; kt < nk; ++kt) {
;     const int cur = kt & 1;
;     const bool more = kt + 1 < nk;
;     if (more) {
;       const int k0 = (kt + 1) * 64;
; #pragma unroll
;       for (int i = 0; i < 4; ++i) { ra[i] = *(const u32x4*)(ga + (size_t)i * 32 * lda + k0); rb[i] = *(const u32x4*)(gb + (size_t)i * 32 * ldb + k0); }
;     }
;     const bf16_t* ab = sA + cur * 128 * LDT + (64 * wr + l32) * LDT + h * 8;
;     const bf16_t* bb = sB + cur * 128 * LDT + (64 * wc + l32) * LDT + h * 8;
;     __builtin_amdgcn_s_setprio(1);
;     __builtin_amdgcn_iglp_opt(0);
; #pragma unroll
;     for (int ks = 0; ks < 4; ++ks) {
;       const bf16x8 a0 = *(const bf16x8*)(ab + ks * 16), a1 = *(const bf16x8*)(ab + 32 * LDT + ks * 16);
;       const bf16x8 b0 = *(const bf16x8*)(bb + ks * 16), b1 = *(const bf16x8*)(bb + 32 * LDT + ks * 16);
;       if (!SWAP) {
;         acc[0][0] = MFMA(a0, b0, acc[0][0]); acc[0][1] = MFMA(a0, b1, acc[0][1]);
;         acc[1][0] = MFMA(a1, b0, acc[1][0]); acc[1][1] = MFMA(a1, b1, acc[1][1]);
;       } else {
;         acc[0][0] = MFMA(b0, a0, acc[0][0]); acc[0][1] = MFMA(b1, a0, acc[0][1]);
;         acc[1][0] = MFMA(b0, a1, acc[1][0]); acc[1][1] = MFMA(b1, a1, acc[1][1]);
;       }
;     }
;     __builtin_amdgcn_s_setprio(0);
;     if (more) {
;       const int nb = (cur ^ 1) * 128 * LDT;
; #pragma unroll
;       for (int i = 0; i < 4; ++i) { *(u32x4*)(sA + nb + soff + i * 32 * LDT) = ra[i]; *(u32x4*)(sB + nb + soff + i * 32 * LDT) = rb[i]; }
;     }
;     __syncthreads();
	ds_read_b128 v[120:123], v66 offset:18432
	ds_read_b128 v[128:131], v0 offset:55296
	ds_read_b128 v[132:135], v0 offset:59904
	ds_read_b128 v[124:127], v66 offset:23040
	ds_read_b128 v[136:139], v66 offset:18464
	ds_read_b128 v[184:187], v0 offset:55328
	ds_read_b128 v[200:203], v0 offset:59936
	ds_read_b128 v[140:143], v66 offset:23072
	s_setprio 1
	s_waitcnt lgkmcnt(4)
	v_mfma_f32_32x32x16_bf16 v[34:49], v[128:131], v[120:123], v[34:49]
	v_mfma_f32_32x32x16_bf16 v[18:33], v[132:135], v[120:123], v[18:33]
	v_mfma_f32_32x32x16_bf16 v[50:65], v[132:135], v[124:127], v[50:65]
	v_mfma_f32_32x32x16_bf16 v[2:17], v[128:131], v[124:127], v[2:17]
	ds_read_b128 v[120:123], v66 offset:18496
	ds_read_b128 v[128:131], v0 offset:55360
	ds_read_b128 v[132:135], v0 offset:59968
	ds_read_b128 v[124:127], v66 offset:23104
	s_waitcnt lgkmcnt(4)
	v_mfma_f32_32x32x16_bf16 v[34:49], v[184:187], v[136:139], v[34:49]
	v_mfma_f32_32x32x16_bf16 v[18:33], v[200:203], v[136:139], v[18:33]
	v_mfma_f32_32x32x16_bf16 v[50:65], v[200:203], v[140:143], v[50:65]
	v_mfma_f32_32x32x16_bf16 v[2:17], v[184:187], v[140:143], v[2:17]
	ds_read_b128 v[136:139], v66 offset:18528
	ds_read_b128 v[184:187], v0 offset:55392
	ds_read_b128 v[200:203], v0 offset:60000
	ds_read_b128 v[140:143], v66 offset:23136
	s_waitcnt lgkmcnt(4)
	v_mfma_f32_32x32x16_bf16 v[34:49], v[128:131], v[120:123], v[34:49]
	v_mfma_f32_32x32x16_bf16 v[18:33], v[132:135], v[120:123], v[18:33]
	v_mfma_f32_32x32x16_bf16 v[50:65], v[132:135], v[124:127], v[50:65]
	v_mfma_f32_32x32x16_bf16 v[2:17], v[128:131], v[124:127], v[2:17]
	s_waitcnt lgkmcnt(0)
	v_mfma_f32_32x32x16_bf16 v[34:49], v[184:187], v[136:139], v[34:49]
	v_mfma_f32_32x32x16_bf16 v[18:33], v[200:203], v[136:139], v[18:33]
	v_mfma_f32_32x32x16_bf16 v[50:65], v[200:203], v[140:143], v[50:65]
	v_mfma_f32_32x32x16_bf16 v[2:17], v[184:187], v[140:143], v[2:17]
	s_setprio 0
	s_nop 7
	s_nop 7
	s_barrier
	s_mov_b64 s[22:23], 0
.LBB0_234:
	s_andn2_b64 vcc, exec, s[22:23]
	s_cbranch_vccnz .LBB0_236
	s_nop 1
	v_mov_b32_e32 v34, v188
	s_waitcnt vmcnt(7)
	s_nop 1
	v_ashrrev_i32_e32 v2, 3, v34
	v_lshlrev_b32_e32 v0, 3, v34
	v_ashrrev_i32_e32 v3, 31, v2
	v_and_b32_e32 v35, 56, v0
	v_lshlrev_b64 v[4:5], 11, v[2:3]
	s_waitcnt vmcnt(6)
	v_lshl_add_u64 v[6:7], s[20:21], 0, v[4:5]
	v_lshlrev_b32_e32 v0, 1, v35
	v_lshl_add_u64 v[68:69], v[6:7], 0, v[0:1]
	v_lshl_add_u64 v[4:5], s[42:43], 0, v[4:5]
	v_add_co_u32_e32 v72, vcc, s50, v68
	v_lshl_add_u64 v[70:71], v[4:5], 0, v[0:1]
	s_nop 0
	v_addc_co_u32_e32 v73, vcc, 0, v69, vcc
	v_add_co_u32_e32 v74, vcc, s50, v70
	v_mul_lo_u32 v0, v2, s33
	s_nop 0
	v_addc_co_u32_e32 v75, vcc, 0, v71, vcc
	v_add_co_u32_e32 v76, vcc, s51, v68
	global_load_dwordx4 v[2:5], v[68:69], off
	s_nop 0
	v_addc_co_u32_e32 v77, vcc, 0, v69, vcc
	v_add_co_u32_e32 v78, vcc, s51, v70
	global_load_dwordx4 v[6:9], v[70:71], off
	s_nop 0
	v_addc_co_u32_e32 v79, vcc, 0, v71, vcc
	v_add_co_u32_e32 v80, vcc, s52, v68
	global_load_dwordx4 v[10:13], v[72:73], off
	s_nop 0
	v_addc_co_u32_e32 v81, vcc, 0, v69, vcc
	v_add_co_u32_e32 v82, vcc, s52, v70
	global_load_dwordx4 v[14:17], v[74:75], off
	s_nop 0
	v_addc_co_u32_e32 v83, vcc, 0, v71, vcc
	global_load_dwordx4 v[18:21], v[76:77], off
	global_load_dwordx4 v[22:25], v[78:79], off
	global_load_dwordx4 v[26:29], v[80:81], off
	global_load_dwordx4 v[30:33], v[82:83], off
	global_load_dwordx4 v[152:155], v[68:69], off offset:128
	global_load_dwordx4 v[156:159], v[70:71], off offset:128
	global_load_dwordx4 v[160:163], v[72:73], off offset:128
	global_load_dwordx4 v[164:167], v[74:75], off offset:128
	global_load_dwordx4 v[168:171], v[76:77], off offset:128
	global_load_dwordx4 v[172:175], v[78:79], off offset:128
	global_load_dwordx4 v[176:179], v[80:81], off offset:128
	global_load_dwordx4 v[180:183], v[82:83], off offset:128
	v_add_lshl_u32 v85, v0, v35, 1
	v_and_b32_e32 v0, 31, v34
	v_add_u32_e32 v86, 0x9000, v85
	s_waitcnt vmcnt(15)
	ds_write_b128 v85, v[2:5]
	v_lshrrev_b32_e32 v2, 1, v34
	v_and_or_b32 v3, v2, s53, v0
	v_and_b32_e32 v0, 16, v2
	v_and_b32_e32 v2, 0x5f, v34
	s_waitcnt vmcnt(14)
	ds_write_b128 v85, v[6:9] offset:36864
	v_mad_u64_u32 v[66:67], s[0:1], v3, s54, v[0:1]
	v_mad_u32_u24 v0, v2, s54, v0
	s_waitcnt vmcnt(13)
	ds_write_b128 v85, v[10:13] offset:4608
	s_waitcnt vmcnt(12)
	ds_write_b128 v85, v[14:17] offset:41472
	s_waitcnt vmcnt(11)
	ds_write_b128 v85, v[18:21] offset:9216
	s_waitcnt vmcnt(10)
	ds_write_b128 v85, v[22:25] offset:46080
	s_waitcnt vmcnt(9)
	ds_write_b128 v85, v[26:29] offset:13824
	s_waitcnt vmcnt(8)
	ds_write_b128 v85, v[30:33] offset:50688
	s_waitcnt lgkmcnt(0)
	s_barrier
; #define MFMA(a, b, c) __builtin_amdgcn_mfma_f32_32x32x16_bf16((a), (b), (c), 0, 0, 0)
; template <bool SWAP>
; DI void gemm_block(const bf16_t* __restrict__ A, int lda, const bf16_t* __restrict__ Bt, int ldb, int K, f32x16 (&acc)[2][2], bf16_t* sA, bf16_t* sB) {
;     ...
;   const int lrow = tid >> 3, lch = (tid & 7) * 8;
;   const bf16_t* ga = A + (size_t)lrow * lda + lch;
;   const bf16_t* gb = Bt + (size_t)lrow * ldb + lch;
;   const int soff = lrow * LDT + lch;
;   u32x4 ra[4], rb[4];
; #pragma unroll
;   for (int i = 0; i < 4; ++i) { ra[i] = *(const u32x4*)(ga + (size_t)i * 32 * lda); rb[i] = *(const u32x4*)(gb + (size_t)i * 32 * ldb); }
; #pragma unroll
;   for (int i = 0; i < 4; ++i) { *(u32x4*)(sA + soff + i * 32 * LDT) = ra[i]; *(u32x4*)(sB + soff + i * 32 * LDT) = rb[i]; }
;   __syncthreads();
;   const int nk = K >> 6;
;   for (int kt = 0; kt < nk; ++kt) {
;     const int cur = kt & 1;
;     const bool more = kt + 1 < nk;
;     if (more) {
;       const int k0 = (kt + 1) * 64;
; #pragma unroll
;       for (int i = 0; i < 4; ++i) { ra[i] = *(const u32x4*)(ga + (size_t)i * 32 * lda + k0); rb[i] = *(const u32x4*)(gb + (size_t)i * 32 * ldb + k0); }
;     }
;     const bf16_t* ab = sA + cur * 128 * LDT + (64 * wr + l32) * LDT + h * 8;
;     const bf16_t* bb = sB + cur * 128 * LDT + (64 * wc + l32) * LDT + h * 8;
;     __builtin_amdgcn_s_setprio(1);
;     __builtin_amdgcn_iglp_opt(0);
; #pragma unroll
;     for (int ks = 0; ks < 4; ++ks) {
;       const bf16x8 a0 = *(const bf16x8*)(ab + ks * 16), a1 = *(const bf16x8*)(ab + 32 * LDT + ks * 16);
;       const bf16x8 b0 = *(const bf16x8*)(bb + ks * 16), b1 = *(const bf16x8*)(bb + 32 * LDT + ks * 16);
;       if (!SWAP) {
;         acc[0][0] = MFMA(a0, b0, acc[0][0]); acc[0][1] = MFMA(a0, b1, acc[0][1]);
;         acc[1][0] = MFMA(a1, b0, acc[1][0]); acc[1][1] = MFMA(a1, b1, acc[1][1]);
;       } else {
;         acc[0][0] = MFMA(b0, a0, acc[0][0]); acc[0][1] = MFMA(b1, a0, acc[0][1]);
;         acc[1][0] = MFMA(b0, a1, acc[1][0]); acc[1][1] = MFMA(b1, a1, acc[1][1]);
;       }
;     }
;     __builtin_amdgcn_s_setprio(0);
;     if (more) {
;       const int nb = (cur ^ 1) * 128 * LDT;
; #pragma unroll
;       for (int i = 0; i < 4; ++i) { *(u32x4*)(sA + nb + soff + i * 32 * LDT) = ra[i]; *(u32x4*)(sB + nb + soff + i * 32 * LDT) = rb[i]; }
;     }
;     __syncthreads();
	ds_read_b128 v[120:123], v66
	ds_read_b128 v[128:131], v0 offset:36864
	ds_read_b128 v[132:135], v0 offset:41472
	ds_read_b128 v[124:127], v66 offset:4608
	ds_read_b128 v[136:139], v66 offset:32
	ds_read_b128 v[184:187], v0 offset:36896
	ds_read_b128 v[200:203], v0 offset:41504
	ds_read_b128 v[140:143], v66 offset:4640
	s_setprio 1
	s_waitcnt lgkmcnt(4)
	v_mfma_f32_32x32x16_bf16 v[34:49], v[120:123], v[128:131], 0
	global_load_dwordx4 v[88:91], v[68:69], off offset:256
	v_mfma_f32_32x32x16_bf16 v[18:33], v[120:123], v[132:135], 0
	s_waitcnt vmcnt(8)
	ds_write_b128 v85, v[152:155] offset:18432
	v_mfma_f32_32x32x16_bf16 v[50:65], v[124:127], v[132:135], 0
	global_load_dwordx4 v[92:95], v[70:71], off offset:256
	v_mfma_f32_32x32x16_bf16 v[2:17], v[124:127], v[128:131], 0
	s_waitcnt vmcnt(8)
	ds_write_b128 v85, v[156:159] offset:55296
	ds_read_b128 v[120:123], v66 offset:64
	ds_read_b128 v[128:131], v0 offset:36928
	ds_read_b128 v[132:135], v0 offset:41536
	ds_read_b128 v[124:127], v66 offset:4672
	s_waitcnt lgkmcnt(6)
	v_mfma_f32_32x32x16_bf16 v[34:49], v[136:139], v[184:187], v[34:49]
	global_load_dwordx4 v[96:99], v[72:73], off offset:256
	v_mfma_f32_32x32x16_bf16 v[18:33], v[136:139], v[200:203], v[18:33]
	s_waitcnt vmcnt(8)
	ds_write_b128 v85, v[160:163] offset:23040
	v_mfma_f32_32x32x16_bf16 v[50:65], v[140:143], v[200:203], v[50:65]
	global_load_dwordx4 v[100:103], v[74:75], off offset:256
	v_mfma_f32_32x32x16_bf16 v[2:17], v[140:143], v[184:187], v[2:17]
	s_waitcnt vmcnt(8)
	ds_write_b128 v85, v[164:167] offset:59904
	ds_read_b128 v[136:139], v66 offset:96
	ds_read_b128 v[184:187], v0 offset:36960
	ds_read_b128 v[200:203], v0 offset:41568
	ds_read_b128 v[140:143], v66 offset:4704
	s_waitcnt lgkmcnt(6)
	v_mfma_f32_32x32x16_bf16 v[34:49], v[120:123], v[128:131], v[34:49]
	global_load_dwordx4 v[104:107], v[76:77], off offset:256
	v_mfma_f32_32x32x16_bf16 v[18:33], v[120:123], v[132:135], v[18:33]
	s_waitcnt vmcnt(8)
	ds_write_b128 v85, v[168:171] offset:27648
	v_mfma_f32_32x32x16_bf16 v[50:65], v[124:127], v[132:135], v[50:65]
	global_load_dwordx4 v[108:111], v[78:79], off offset:256
	v_mfma_f32_32x32x16_bf16 v[2:17], v[124:127], v[128:131], v[2:17]
	s_waitcnt vmcnt(8)
	ds_write_b128 v85, v[172:175] offset:64512
	s_waitcnt lgkmcnt(2)
	v_mfma_f32_32x32x16_bf16 v[34:49], v[136:139], v[184:187], v[34:49]
	global_load_dwordx4 v[112:115], v[80:81], off offset:256
	v_mfma_f32_32x32x16_bf16 v[18:33], v[136:139], v[200:203], v[18:33]
	s_waitcnt vmcnt(8)
	ds_write_b128 v85, v[176:179] offset:32256
	v_mfma_f32_32x32x16_bf16 v[50:65], v[140:143], v[200:203], v[50:65]
	global_load_dwordx4 v[116:119], v[82:83], off offset:256
	v_mfma_f32_32x32x16_bf16 v[2:17], v[140:143], v[184:187], v[2:17]
	s_waitcnt vmcnt(8)
	ds_write_b128 v86, v[180:183] offset:32256
	s_setprio 0
	s_waitcnt lgkmcnt(0)
	s_barrier
	ds_read_b128 v[120:123], v66 offset:18432
	ds_read_b128 v[128:131], v0 offset:55296
	ds_read_b128 v[132:135], v0 offset:59904
	ds_read_b128 v[124:127], v66 offset:23040
	ds_read_b128 v[136:139], v66 offset:18464
	ds_read_b128 v[184:187], v0 offset:55328
	ds_read_b128 v[200:203], v0 offset:59936
	ds_read_b128 v[140:143], v66 offset:23072
	s_setprio 1
	s_waitcnt lgkmcnt(4)
	v_mfma_f32_32x32x16_bf16 v[34:49], v[120:123], v[128:131], v[34:49]
	global_load_dwordx4 v[152:155], v[68:69], off offset:384
	v_mfma_f32_32x32x16_bf16 v[18:33], v[120:123], v[132:135], v[18:33]
	s_waitcnt vmcnt(8)
	ds_write_b128 v85, v[88:91]
	v_mfma_f32_32x32x16_bf16 v[50:65], v[124:127], v[132:135], v[50:65]
	global_load_dwordx4 v[156:159], v[70:71], off offset:384
	v_mfma_f32_32x32x16_bf16 v[2:17], v[124:127], v[128:131], v[2:17]
	s_waitcnt vmcnt(8)
	ds_write_b128 v85, v[92:95] offset:36864
	ds_read_b128 v[120:123], v66 offset:18496
	ds_read_b128 v[128:131], v0 offset:55360
	ds_read_b128 v[132:135], v0 offset:59968
	ds_read_b128 v[124:127], v66 offset:23104
	s_waitcnt lgkmcnt(6)
	v_mfma_f32_32x32x16_bf16 v[34:49], v[136:139], v[184:187], v[34:49]
	global_load_dwordx4 v[160:163], v[72:73], off offset:384
	v_mfma_f32_32x32x16_bf16 v[18:33], v[136:139], v[200:203], v[18:33]
	s_waitcnt vmcnt(8)
	ds_write_b128 v85, v[96:99] offset:4608
	v_mfma_f32_32x32x16_bf16 v[50:65], v[140:143], v[200:203], v[50:65]
	global_load_dwordx4 v[164:167], v[74:75], off offset:384
	v_mfma_f32_32x32x16_bf16 v[2:17], v[140:143], v[184:187], v[2:17]
	s_waitcnt vmcnt(8)
	ds_write_b128 v85, v[100:103] offset:41472
	ds_read_b128 v[136:139], v66 offset:18528
	ds_read_b128 v[184:187], v0 offset:55392
	ds_read_b128 v[200:203], v0 offset:60000
	ds_read_b128 v[140:143], v66 offset:23136
	s_waitcnt lgkmcnt(6)
	v_mfma_f32_32x32x16_bf16 v[34:49], v[120:123], v[128:131], v[34:49]
	global_load_dwordx4 v[168:171], v[76:77], off offset:384
	v_mfma_f32_32x32x16_bf16 v[18:33], v[120:123], v[132:135], v[18:33]
	s_waitcnt vmcnt(8)
	ds_write_b128 v85, v[104:107] offset:9216
	v_mfma_f32_32x32x16_bf16 v[50:65], v[124:127], v[132:135], v[50:65]
	global_load_dwordx4 v[172:175], v[78:79], off offset:384
	v_mfma_f32_32x32x16_bf16 v[2:17], v[124:127], v[128:131], v[2:17]
	s_waitcnt vmcnt(8)
	ds_write_b128 v85, v[108:111] offset:46080
	s_waitcnt lgkmcnt(2)
	v_mfma_f32_32x32x16_bf16 v[34:49], v[136:139], v[184:187], v[34:49]
	global_load_dwordx4 v[176:179], v[80:81], off offset:384
	v_mfma_f32_32x32x16_bf16 v[18:33], v[136:139], v[200:203], v[18:33]
	s_waitcnt vmcnt(8)
	ds_write_b128 v85, v[112:115] offset:13824
	v_mfma_f32_32x32x16_bf16 v[50:65], v[140:143], v[200:203], v[50:65]
	global_load_dwordx4 v[180:183], v[82:83], off offset:384
	v_mfma_f32_32x32x16_bf16 v[2:17], v[140:143], v[184:187], v[2:17]
	s_waitcnt vmcnt(8)
	ds_write_b128 v85, v[116:119] offset:50688
	s_setprio 0
	s_waitcnt lgkmcnt(0)
	s_barrier
; #define MFMA(a, b, c) __builtin_amdgcn_mfma_f32_32x32x16_bf16((a), (b), (c), 0, 0, 0)
; template <bool SWAP>
; DI void gemm_block(const bf16_t* __restrict__ A, int lda, const bf16_t* __restrict__ Bt, int ldb, int K, f32x16 (&acc)[2][2], bf16_t* sA, bf16_t* sB) {
;     ...
;   for (int kt = 0; kt < nk; ++kt) {
;     const int cur = kt & 1;
;     const bool more = kt + 1 < nk;
;     if (more) {
;       const int k0 = (kt + 1) * 64;
; #pragma unroll
;       for (int i = 0; i < 4; ++i) { ra[i] = *(const u32x4*)(ga + (size_t)i * 32 * lda + k0); rb[i] = *(const u32x4*)(gb + (size_t)i * 32 * ldb + k0); }
;     }
;     const bf16_t* ab = sA + cur * 128 * LDT + (64 * wr + l32) * LDT + h * 8;
;     const bf16_t* bb = sB + cur * 128 * LDT + (64 * wc + l32) * LDT + h * 8;
;     __builtin_amdgcn_s_setprio(1);
;     __builtin_amdgcn_iglp_opt(0);
; #pragma unroll
;     for (int ks = 0; ks < 4; ++ks) {
;       const bf16x8 a0 = *(const bf16x8*)(ab + ks * 16), a1 = *(const bf16x8*)(ab + 32 * LDT + ks * 16);
;       const bf16x8 b0 = *(const bf16x8*)(bb + ks * 16), b1 = *(const bf16x8*)(bb + 32 * LDT + ks * 16);
;       if (!SWAP) {
;         acc[0][0] = MFMA(a0, b0, acc[0][0]); acc[0][1] = MFMA(a0, b1, acc[0][1]);
;         acc[1][0] = MFMA(a1, b0, acc[1][0]); acc[1][1] = MFMA(a1, b1, acc[1][1]);
;       } else {
;         acc[0][0] = MFMA(b0, a0, acc[0][0]); acc[0][1] = MFMA(b1, a0, acc[0][1]);
;         acc[1][0] = MFMA(b0, a1, acc[1][0]); acc[1][1] = MFMA(b1, a1, acc[1][1]);
;       }
;     }
;     __builtin_amdgcn_s_setprio(0);
;     if (more) {
;       const int nb = (cur ^ 1) * 128 * LDT;
; #pragma unroll
;       for (int i = 0; i < 4; ++i) { *(u32x4*)(sA + nb + soff + i * 32 * LDT) = ra[i]; *(u32x4*)(sB + nb + soff + i * 32 * LDT) = rb[i]; }
;     }
;     __syncthreads();
	ds_read_b128 v[120:123], v66
	ds_read_b128 v[128:131], v0 offset:36864
	ds_read_b128 v[132:135], v0 offset:41472
	ds_read_b128 v[124:127], v66 offset:4608
	ds_read_b128 v[136:139], v66 offset:32
	ds_read_b128 v[184:187], v0 offset:36896
	ds_read_b128 v[200:203], v0 offset:41504
	ds_read_b128 v[140:143], v66 offset:4640
	s_setprio 1
	s_waitcnt lgkmcnt(4)
	v_mfma_f32_32x32x16_bf16 v[34:49], v[120:123], v[128:131], v[34:49]
	global_load_dwordx4 v[88:91], v[68:69], off offset:512
	v_mfma_f32_32x32x16_bf16 v[18:33], v[120:123], v[132:135], v[18:33]
	s_waitcnt vmcnt(8)
	ds_write_b128 v85, v[152:155] offset:18432
	v_mfma_f32_32x32x16_bf16 v[50:65], v[124:127], v[132:135], v[50:65]
	global_load_dwordx4 v[92:95], v[70:71], off offset:512
	v_mfma_f32_32x32x16_bf16 v[2:17], v[124:127], v[128:131], v[2:17]
	s_waitcnt vmcnt(8)
	ds_write_b128 v85, v[156:159] offset:55296
	ds_read_b128 v[120:123], v66 offset:64
	ds_read_b128 v[128:131], v0 offset:36928
	ds_read_b128 v[132:135], v0 offset:41536
	ds_read_b128 v[124:127], v66 offset:4672
	s_waitcnt lgkmcnt(6)
	v_mfma_f32_32x32x16_bf16 v[34:49], v[136:139], v[184:187], v[34:49]
	global_load_dwordx4 v[96:99], v[72:73], off offset:512
	v_mfma_f32_32x32x16_bf16 v[18:33], v[136:139], v[200:203], v[18:33]
	s_waitcnt vmcnt(8)
	ds_write_b128 v85, v[160:163] offset:23040
	v_mfma_f32_32x32x16_bf16 v[50:65], v[140:143], v[200:203], v[50:65]
	global_load_dwordx4 v[100:103], v[74:75], off offset:512
	v_mfma_f32_32x32x16_bf16 v[2:17], v[140:143], v[184:187], v[2:17]
	s_waitcnt vmcnt(8)
	ds_write_b128 v85, v[164:167] offset:59904
	ds_read_b128 v[136:139], v66 offset:96
	ds_read_b128 v[184:187], v0 offset:36960
	ds_read_b128 v[200:203], v0 offset:41568
	ds_read_b128 v[140:143], v66 offset:4704
	s_waitcnt lgkmcnt(6)
	v_mfma_f32_32x32x16_bf16 v[34:49], v[120:123], v[128:131], v[34:49]
	global_load_dwordx4 v[104:107], v[76:77], off offset:512
	v_mfma_f32_32x32x16_bf16 v[18:33], v[120:123], v[132:135], v[18:33]
	s_waitcnt vmcnt(8)
	ds_write_b128 v85, v[168:171] offset:27648
	v_mfma_f32_32x32x16_bf16 v[50:65], v[124:127], v[132:135], v[50:65]
	global_load_dwordx4 v[108:111], v[78:79], off offset:512
	v_mfma_f32_32x32x16_bf16 v[2:17], v[124:127], v[128:131], v[2:17]
	s_waitcnt vmcnt(8)
	ds_write_b128 v85, v[172:175] offset:64512
	s_waitcnt lgkmcnt(2)
	v_mfma_f32_32x32x16_bf16 v[34:49], v[136:139], v[184:187], v[34:49]
	global_load_dwordx4 v[112:115], v[80:81], off offset:512
	v_mfma_f32_32x32x16_bf16 v[18:33], v[136:139], v[200:203], v[18:33]
	s_waitcnt vmcnt(8)
	ds_write_b128 v85, v[176:179] offset:32256
	v_mfma_f32_32x32x16_bf16 v[50:65], v[140:143], v[200:203], v[50:65]
	global_load_dwordx4 v[116:119], v[82:83], off offset:512
	v_mfma_f32_32x32x16_bf16 v[2:17], v[140:143], v[184:187], v[2:17]
	s_waitcnt vmcnt(8)
	ds_write_b128 v86, v[180:183] offset:32256
	s_setprio 0
	s_waitcnt lgkmcnt(0)
	s_barrier
	ds_read_b128 v[120:123], v66 offset:18432
	ds_read_b128 v[128:131], v0 offset:55296
	ds_read_b128 v[132:135], v0 offset:59904
	ds_read_b128 v[124:127], v66 offset:23040
	ds_read_b128 v[136:139], v66 offset:18464
	ds_read_b128 v[184:187], v0 offset:55328
	ds_read_b128 v[200:203], v0 offset:59936
	ds_read_b128 v[140:143], v66 offset:23072
	s_setprio 1
	s_waitcnt lgkmcnt(4)
	v_mfma_f32_32x32x16_bf16 v[34:49], v[120:123], v[128:131], v[34:49]
	global_load_dwordx4 v[152:155], v[68:69], off offset:640
	v_mfma_f32_32x32x16_bf16 v[18:33], v[120:123], v[132:135], v[18:33]
	s_waitcnt vmcnt(8)
	ds_write_b128 v85, v[88:91]
	v_mfma_f32_32x32x16_bf16 v[50:65], v[124:127], v[132:135], v[50:65]
	global_load_dwordx4 v[156:159], v[70:71], off offset:640
	v_mfma_f32_32x32x16_bf16 v[2:17], v[124:127], v[128:131], v[2:17]
	s_waitcnt vmcnt(8)
	ds_write_b128 v85, v[92:95] offset:36864
	ds_read_b128 v[120:123], v66 offset:18496
	ds_read_b128 v[128:131], v0 offset:55360
	ds_read_b128 v[132:135], v0 offset:59968
	ds_read_b128 v[124:127], v66 offset:23104
	s_waitcnt lgkmcnt(6)
	v_mfma_f32_32x32x16_bf16 v[34:49], v[136:139], v[184:187], v[34:49]
	global_load_dwordx4 v[160:163], v[72:73], off offset:640
	v_mfma_f32_32x32x16_bf16 v[18:33], v[136:139], v[200:203], v[18:33]
	s_waitcnt vmcnt(8)
	ds_write_b128 v85, v[96:99] offset:4608
	v_mfma_f32_32x32x16_bf16 v[50:65], v[140:143], v[200:203], v[50:65]
	global_load_dwordx4 v[164:167], v[74:75], off offset:640
	v_mfma_f32_32x32x16_bf16 v[2:17], v[140:143], v[184:187], v[2:17]
	s_waitcnt vmcnt(8)
	ds_write_b128 v85, v[100:103] offset:41472
	ds_read_b128 v[136:139], v66 offset:18528
	ds_read_b128 v[184:187], v0 offset:55392
	ds_read_b128 v[200:203], v0 offset:60000
	ds_read_b128 v[140:143], v66 offset:23136
	s_waitcnt lgkmcnt(6)
	v_mfma_f32_32x32x16_bf16 v[34:49], v[120:123], v[128:131], v[34:49]
	global_load_dwordx4 v[168:171], v[76:77], off offset:640
	v_mfma_f32_32x32x16_bf16 v[18:33], v[120:123], v[132:135], v[18:33]
	s_waitcnt vmcnt(8)
	ds_write_b128 v85, v[104:107] offset:9216
	v_mfma_f32_32x32x16_bf16 v[50:65], v[124:127], v[132:135], v[50:65]
	global_load_dwordx4 v[172:175], v[78:79], off offset:640
	v_mfma_f32_32x32x16_bf16 v[2:17], v[124:127], v[128:131], v[2:17]
	s_waitcnt vmcnt(8)
	ds_write_b128 v85, v[108:111] offset:46080
	s_waitcnt lgkmcnt(2)
	v_mfma_f32_32x32x16_bf16 v[34:49], v[136:139], v[184:187], v[34:49]
	global_load_dwordx4 v[176:179], v[80:81], off offset:640
	v_mfma_f32_32x32x16_bf16 v[18:33], v[136:139], v[200:203], v[18:33]
	s_waitcnt vmcnt(8)
	ds_write_b128 v85, v[112:115] offset:13824
	v_mfma_f32_32x32x16_bf16 v[50:65], v[140:143], v[200:203], v[50:65]
	global_load_dwordx4 v[180:183], v[82:83], off offset:640
	v_mfma_f32_32x32x16_bf16 v[2:17], v[140:143], v[184:187], v[2:17]
	s_waitcnt vmcnt(8)
	ds_write_b128 v85, v[116:119] offset:50688
	s_setprio 0
	s_waitcnt lgkmcnt(0)
	s_barrier
; #define MFMA(a, b, c) __builtin_amdgcn_mfma_f32_32x32x16_bf16((a), (b), (c), 0, 0, 0)
; template <bool SWAP>
; DI void gemm_block(const bf16_t* __restrict__ A, int lda, const bf16_t* __restrict__ Bt, int ldb, int K, f32x16 (&acc)[2][2], bf16_t* sA, bf16_t* sB) {
;     ...
;   for (int kt = 0; kt < nk; ++kt) {
;     const int cur = kt & 1;
;     const bool more = kt + 1 < nk;
;     if (more) {
;       const int k0 = (kt + 1) * 64;
; #pragma unroll
;       for (int i = 0; i < 4; ++i) { ra[i] = *(const u32x4*)(ga + (size_t)i * 32 * lda + k0); rb[i] = *(const u32x4*)(gb + (size_t)i * 32 * ldb + k0); }
;     }
;     const bf16_t* ab = sA + cur * 128 * LDT + (64 * wr + l32) * LDT + h * 8;
;     const bf16_t* bb = sB + cur * 128 * LDT + (64 * wc + l32) * LDT + h * 8;
;     __builtin_amdgcn_s_setprio(1);
;     __builtin_amdgcn_iglp_opt(0);
; #pragma unroll
;     for (int ks = 0; ks < 4; ++ks) {
;       const bf16x8 a0 = *(const bf16x8*)(ab + ks * 16), a1 = *(const bf16x8*)(ab + 32 * LDT + ks * 16);
;       const bf16x8 b0 = *(const bf16x8*)(bb + ks * 16), b1 = *(const bf16x8*)(bb + 32 * LDT + ks * 16);
;       if (!SWAP) {
;         acc[0][0] = MFMA(a0, b0, acc[0][0]); acc[0][1] = MFMA(a0, b1, acc[0][1]);
;         acc[1][0] = MFMA(a1, b0, acc[1][0]); acc[1][1] = MFMA(a1, b1, acc[1][1]);
;       } else {
;         acc[0][0] = MFMA(b0, a0, acc[0][0]); acc[0][1] = MFMA(b1, a0, acc[0][1]);
;         acc[1][0] = MFMA(b0, a1, acc[1][0]); acc[1][1] = MFMA(b1, a1, acc[1][1]);
;       }
;     }
;     __builtin_amdgcn_s_setprio(0);
;     if (more) {
;       const int nb = (cur ^ 1) * 128 * LDT;
; #pragma unroll
;       for (int i = 0; i < 4; ++i) { *(u32x4*)(sA + nb + soff + i * 32 * LDT) = ra[i]; *(u32x4*)(sB + nb + soff + i * 32 * LDT) = rb[i]; }
;     }
;     __syncthreads();
	ds_read_b128 v[120:123], v66
	ds_read_b128 v[128:131], v0 offset:36864
	ds_read_b128 v[132:135], v0 offset:41472
	ds_read_b128 v[124:127], v66 offset:4608
	ds_read_b128 v[136:139], v66 offset:32
	ds_read_b128 v[184:187], v0 offset:36896
	ds_read_b128 v[200:203], v0 offset:41504
	ds_read_b128 v[140:143], v66 offset:4640
	s_setprio 1
	s_waitcnt lgkmcnt(4)
	v_mfma_f32_32x32x16_bf16 v[34:49], v[120:123], v[128:131], v[34:49]
	global_load_dwordx4 v[88:91], v[68:69], off offset:768
	v_mfma_f32_32x32x16_bf16 v[18:33], v[120:123], v[132:135], v[18:33]
	s_waitcnt vmcnt(8)
	ds_write_b128 v85, v[152:155] offset:18432
	v_mfma_f32_32x32x16_bf16 v[50:65], v[124:127], v[132:135], v[50:65]
	global_load_dwordx4 v[92:95], v[70:71], off offset:768
	v_mfma_f32_32x32x16_bf16 v[2:17], v[124:127], v[128:131], v[2:17]
	s_waitcnt vmcnt(8)
	ds_write_b128 v85, v[156:159] offset:55296
	ds_read_b128 v[120:123], v66 offset:64
	ds_read_b128 v[128:131], v0 offset:36928
	ds_read_b128 v[132:135], v0 offset:41536
	ds_read_b128 v[124:127], v66 offset:4672
	s_waitcnt lgkmcnt(6)
	v_mfma_f32_32x32x16_bf16 v[34:49], v[136:139], v[184:187], v[34:49]
	global_load_dwordx4 v[96:99], v[72:73], off offset:768
	v_mfma_f32_32x32x16_bf16 v[18:33], v[136:139], v[200:203], v[18:33]
	s_waitcnt vmcnt(8)
	ds_write_b128 v85, v[160:163] offset:23040
	v_mfma_f32_32x32x16_bf16 v[50:65], v[140:143], v[200:203], v[50:65]
	global_load_dwordx4 v[100:103], v[74:75], off offset:768
	v_mfma_f32_32x32x16_bf16 v[2:17], v[140:143], v[184:187], v[2:17]
	s_waitcnt vmcnt(8)
	ds_write_b128 v85, v[164:167] offset:59904
	ds_read_b128 v[136:139], v66 offset:96
	ds_read_b128 v[184:187], v0 offset:36960
	ds_read_b128 v[200:203], v0 offset:41568
	ds_read_b128 v[140:143], v66 offset:4704
	s_waitcnt lgkmcnt(6)
	v_mfma_f32_32x32x16_bf16 v[34:49], v[120:123], v[128:131], v[34:49]
	global_load_dwordx4 v[104:107], v[76:77], off offset:768
	v_mfma_f32_32x32x16_bf16 v[18:33], v[120:123], v[132:135], v[18:33]
	s_waitcnt vmcnt(8)
	ds_write_b128 v85, v[168:171] offset:27648
	v_mfma_f32_32x32x16_bf16 v[50:65], v[124:127], v[132:135], v[50:65]
	global_load_dwordx4 v[108:111], v[78:79], off offset:768
	v_mfma_f32_32x32x16_bf16 v[2:17], v[124:127], v[128:131], v[2:17]
	s_waitcnt vmcnt(8)
	ds_write_b128 v85, v[172:175] offset:64512
	s_waitcnt lgkmcnt(2)
	v_mfma_f32_32x32x16_bf16 v[34:49], v[136:139], v[184:187], v[34:49]
	global_load_dwordx4 v[112:115], v[80:81], off offset:768
	v_mfma_f32_32x32x16_bf16 v[18:33], v[136:139], v[200:203], v[18:33]
	s_waitcnt vmcnt(8)
	ds_write_b128 v85, v[176:179] offset:32256
	v_mfma_f32_32x32x16_bf16 v[50:65], v[140:143], v[200:203], v[50:65]
	global_load_dwordx4 v[116:119], v[82:83], off offset:768
	v_mfma_f32_32x32x16_bf16 v[2:17], v[140:143], v[184:187], v[2:17]
	s_waitcnt vmcnt(8)
	ds_write_b128 v86, v[180:183] offset:32256
	s_setprio 0
	s_waitcnt lgkmcnt(0)
	s_barrier
	ds_read_b128 v[120:123], v66 offset:18432
	ds_read_b128 v[128:131], v0 offset:55296
	ds_read_b128 v[132:135], v0 offset:59904
	ds_read_b128 v[124:127], v66 offset:23040
	ds_read_b128 v[136:139], v66 offset:18464
	ds_read_b128 v[184:187], v0 offset:55328
	ds_read_b128 v[200:203], v0 offset:59936
	ds_read_b128 v[140:143], v66 offset:23072
	s_setprio 1
	s_waitcnt lgkmcnt(4)
	v_mfma_f32_32x32x16_bf16 v[34:49], v[120:123], v[128:131], v[34:49]
	global_load_dwordx4 v[152:155], v[68:69], off offset:896
	v_mfma_f32_32x32x16_bf16 v[18:33], v[120:123], v[132:135], v[18:33]
	s_waitcnt vmcnt(8)
	ds_write_b128 v85, v[88:91]
	v_mfma_f32_32x32x16_bf16 v[50:65], v[124:127], v[132:135], v[50:65]
	global_load_dwordx4 v[156:159], v[70:71], off offset:896
	v_mfma_f32_32x32x16_bf16 v[2:17], v[124:127], v[128:131], v[2:17]
	s_waitcnt vmcnt(8)
	ds_write_b128 v85, v[92:95] offset:36864
	ds_read_b128 v[120:123], v66 offset:18496
	ds_read_b128 v[128:131], v0 offset:55360
	ds_read_b128 v[132:135], v0 offset:59968
	ds_read_b128 v[124:127], v66 offset:23104
	s_waitcnt lgkmcnt(6)
	v_mfma_f32_32x32x16_bf16 v[34:49], v[136:139], v[184:187], v[34:49]
	global_load_dwordx4 v[160:163], v[72:73], off offset:896
	v_mfma_f32_32x32x16_bf16 v[18:33], v[136:139], v[200:203], v[18:33]
	s_waitcnt vmcnt(8)
	ds_write_b128 v85, v[96:99] offset:4608
	v_mfma_f32_32x32x16_bf16 v[50:65], v[140:143], v[200:203], v[50:65]
	global_load_dwordx4 v[164:167], v[74:75], off offset:896
	v_mfma_f32_32x32x16_bf16 v[2:17], v[140:143], v[184:187], v[2:17]
	s_waitcnt vmcnt(8)
	ds_write_b128 v85, v[100:103] offset:41472
	ds_read_b128 v[136:139], v66 offset:18528
	ds_read_b128 v[184:187], v0 offset:55392
	ds_read_b128 v[200:203], v0 offset:60000
	ds_read_b128 v[140:143], v66 offset:23136
	s_waitcnt lgkmcnt(6)
	v_mfma_f32_32x32x16_bf16 v[34:49], v[120:123], v[128:131], v[34:49]
	global_load_dwordx4 v[168:171], v[76:77], off offset:896
	v_mfma_f32_32x32x16_bf16 v[18:33], v[120:123], v[132:135], v[18:33]
	s_waitcnt vmcnt(8)
	ds_write_b128 v85, v[104:107] offset:9216
	v_mfma_f32_32x32x16_bf16 v[50:65], v[124:127], v[132:135], v[50:65]
	global_load_dwordx4 v[172:175], v[78:79], off offset:896
	v_mfma_f32_32x32x16_bf16 v[2:17], v[124:127], v[128:131], v[2:17]
	s_waitcnt vmcnt(8)
	ds_write_b128 v85, v[108:111] offset:46080
	s_waitcnt lgkmcnt(2)
	v_mfma_f32_32x32x16_bf16 v[34:49], v[136:139], v[184:187], v[34:49]
	global_load_dwordx4 v[176:179], v[80:81], off offset:896
	v_mfma_f32_32x32x16_bf16 v[18:33], v[136:139], v[200:203], v[18:33]
	s_waitcnt vmcnt(8)
	ds_write_b128 v85, v[112:115] offset:13824
	v_mfma_f32_32x32x16_bf16 v[50:65], v[140:143], v[200:203], v[50:65]
	global_load_dwordx4 v[180:183], v[82:83], off offset:896
	v_mfma_f32_32x32x16_bf16 v[2:17], v[140:143], v[184:187], v[2:17]
	s_waitcnt vmcnt(8)
	ds_write_b128 v85, v[116:119] offset:50688
	s_setprio 0
	s_waitcnt lgkmcnt(0)
	s_barrier
; #define MFMA(a, b, c) __builtin_amdgcn_mfma_f32_32x32x16_bf16((a), (b), (c), 0, 0, 0)
; template <bool SWAP>
; DI void gemm_block(const bf16_t* __restrict__ A, int lda, const bf16_t* __restrict__ Bt, int ldb, int K, f32x16 (&acc)[2][2], bf16_t* sA, bf16_t* sB) {
;     ...
;   for (int kt = 0; kt < nk; ++kt) {
;     const int cur = kt & 1;
;     const bool more = kt + 1 < nk;
;     if (more) {
;       const int k0 = (kt + 1) * 64;
; #pragma unroll
;       for (int i = 0; i < 4; ++i) { ra[i] = *(const u32x4*)(ga + (size_t)i * 32 * lda + k0); rb[i] = *(const u32x4*)(gb + (size_t)i * 32 * ldb + k0); }
;     }
;     const bf16_t* ab = sA + cur * 128 * LDT + (64 * wr + l32) * LDT + h * 8;
;     const bf16_t* bb = sB + cur * 128 * LDT + (64 * wc + l32) * LDT + h * 8;
;     __builtin_amdgcn_s_setprio(1);
;     __builtin_amdgcn_iglp_opt(0);
; #pragma unroll
;     for (int ks = 0; ks < 4; ++ks) {
;       const bf16x8 a0 = *(const bf16x8*)(ab + ks * 16), a1 = *(const bf16x8*)(ab + 32 * LDT + ks * 16);
;       const bf16x8 b0 = *(const bf16x8*)(bb + ks * 16), b1 = *(const bf16x8*)(bb + 32 * LDT + ks * 16);
;       if (!SWAP) {
;         acc[0][0] = MFMA(a0, b0, acc[0][0]); acc[0][1] = MFMA(a0, b1, acc[0][1]);
;         acc[1][0] = MFMA(a1, b0, acc[1][0]); acc[1][1] = MFMA(a1, b1, acc[1][1]);
;       } else {
;         acc[0][0] = MFMA(b0, a0, acc[0][0]); acc[0][1] = MFMA(b1, a0, acc[0][1]);
;         acc[1][0] = MFMA(b0, a1, acc[1][0]); acc[1][1] = MFMA(b1, a1, acc[1][1]);
;       }
;     }
;     __builtin_amdgcn_s_setprio(0);
;     if (more) {
;       const int nb = (cur ^ 1) * 128 * LDT;
; #pragma unroll
;       for (int i = 0; i < 4; ++i) { *(u32x4*)(sA + nb + soff + i * 32 * LDT) = ra[i]; *(u32x4*)(sB + nb + soff + i * 32 * LDT) = rb[i]; }
;     }
;     __syncthreads();
	ds_read_b128 v[120:123], v66
	ds_read_b128 v[128:131], v0 offset:36864
	ds_read_b128 v[132:135], v0 offset:41472
	ds_read_b128 v[124:127], v66 offset:4608
	ds_read_b128 v[136:139], v66 offset:32
	ds_read_b128 v[184:187], v0 offset:36896
	ds_read_b128 v[200:203], v0 offset:41504
	ds_read_b128 v[140:143], v66 offset:4640
	s_setprio 1
	s_waitcnt lgkmcnt(4)
	v_mfma_f32_32x32x16_bf16 v[34:49], v[120:123], v[128:131], v[34:49]
	global_load_dwordx4 v[88:91], v[68:69], off offset:1024
	v_mfma_f32_32x32x16_bf16 v[18:33], v[120:123], v[132:135], v[18:33]
	s_waitcnt vmcnt(8)
	ds_write_b128 v85, v[152:155] offset:18432
	v_mfma_f32_32x32x16_bf16 v[50:65], v[124:127], v[132:135], v[50:65]
	global_load_dwordx4 v[92:95], v[70:71], off offset:1024
	v_mfma_f32_32x32x16_bf16 v[2:17], v[124:127], v[128:131], v[2:17]
	s_waitcnt vmcnt(8)
	ds_write_b128 v85, v[156:159] offset:55296
	ds_read_b128 v[120:123], v66 offset:64
	ds_read_b128 v[128:131], v0 offset:36928
	ds_read_b128 v[132:135], v0 offset:41536
	ds_read_b128 v[124:127], v66 offset:4672
	s_waitcnt lgkmcnt(6)
	v_mfma_f32_32x32x16_bf16 v[34:49], v[136:139], v[184:187], v[34:49]
	global_load_dwordx4 v[96:99], v[72:73], off offset:1024
	v_mfma_f32_32x32x16_bf16 v[18:33], v[136:139], v[200:203], v[18:33]
	s_waitcnt vmcnt(8)
	ds_write_b128 v85, v[160:163] offset:23040
	v_mfma_f32_32x32x16_bf16 v[50:65], v[140:143], v[200:203], v[50:65]
	global_load_dwordx4 v[100:103], v[74:75], off offset:1024
	v_mfma_f32_32x32x16_bf16 v[2:17], v[140:143], v[184:187], v[2:17]
	s_waitcnt vmcnt(8)
	ds_write_b128 v85, v[164:167] offset:59904
	ds_read_b128 v[136:139], v66 offset:96
	ds_read_b128 v[184:187], v0 offset:36960
	ds_read_b128 v[200:203], v0 offset:41568
	ds_read_b128 v[140:143], v66 offset:4704
	s_waitcnt lgkmcnt(6)
	v_mfma_f32_32x32x16_bf16 v[34:49], v[120:123], v[128:131], v[34:49]
	global_load_dwordx4 v[104:107], v[76:77], off offset:1024
	v_mfma_f32_32x32x16_bf16 v[18:33], v[120:123], v[132:135], v[18:33]
	s_waitcnt vmcnt(8)
	ds_write_b128 v85, v[168:171] offset:27648
	v_mfma_f32_32x32x16_bf16 v[50:65], v[124:127], v[132:135], v[50:65]
	global_load_dwordx4 v[108:111], v[78:79], off offset:1024
	v_mfma_f32_32x32x16_bf16 v[2:17], v[124:127], v[128:131], v[2:17]
	s_waitcnt vmcnt(8)
	ds_write_b128 v85, v[172:175] offset:64512
	s_waitcnt lgkmcnt(2)
	v_mfma_f32_32x32x16_bf16 v[34:49], v[136:139], v[184:187], v[34:49]
	global_load_dwordx4 v[112:115], v[80:81], off offset:1024
	v_mfma_f32_32x32x16_bf16 v[18:33], v[136:139], v[200:203], v[18:33]
	s_waitcnt vmcnt(8)
	ds_write_b128 v85, v[176:179] offset:32256
	v_mfma_f32_32x32x16_bf16 v[50:65], v[140:143], v[200:203], v[50:65]
	global_load_dwordx4 v[116:119], v[82:83], off offset:1024
	v_mfma_f32_32x32x16_bf16 v[2:17], v[140:143], v[184:187], v[2:17]
	s_waitcnt vmcnt(8)
	ds_write_b128 v86, v[180:183] offset:32256
	s_setprio 0
	s_waitcnt lgkmcnt(0)
	s_barrier
	ds_read_b128 v[120:123], v66 offset:18432
	ds_read_b128 v[128:131], v0 offset:55296
	ds_read_b128 v[132:135], v0 offset:59904
	ds_read_b128 v[124:127], v66 offset:23040
	ds_read_b128 v[136:139], v66 offset:18464
	ds_read_b128 v[184:187], v0 offset:55328
	ds_read_b128 v[200:203], v0 offset:59936
	ds_read_b128 v[140:143], v66 offset:23072
	s_setprio 1
	s_waitcnt lgkmcnt(4)
	v_mfma_f32_32x32x16_bf16 v[34:49], v[120:123], v[128:131], v[34:49]
	global_load_dwordx4 v[152:155], v[68:69], off offset:1152
	v_mfma_f32_32x32x16_bf16 v[18:33], v[120:123], v[132:135], v[18:33]
	s_waitcnt vmcnt(8)
	ds_write_b128 v85, v[88:91]
	v_mfma_f32_32x32x16_bf16 v[50:65], v[124:127], v[132:135], v[50:65]
	global_load_dwordx4 v[156:159], v[70:71], off offset:1152
	v_mfma_f32_32x32x16_bf16 v[2:17], v[124:127], v[128:131], v[2:17]
	s_waitcnt vmcnt(8)
	ds_write_b128 v85, v[92:95] offset:36864
	ds_read_b128 v[120:123], v66 offset:18496
	ds_read_b128 v[128:131], v0 offset:55360
	ds_read_b128 v[132:135], v0 offset:59968
	ds_read_b128 v[124:127], v66 offset:23104
	s_waitcnt lgkmcnt(6)
	v_mfma_f32_32x32x16_bf16 v[34:49], v[136:139], v[184:187], v[34:49]
	global_load_dwordx4 v[160:163], v[72:73], off offset:1152
	v_mfma_f32_32x32x16_bf16 v[18:33], v[136:139], v[200:203], v[18:33]
	s_waitcnt vmcnt(8)
	ds_write_b128 v85, v[96:99] offset:4608
	v_mfma_f32_32x32x16_bf16 v[50:65], v[140:143], v[200:203], v[50:65]
	global_load_dwordx4 v[164:167], v[74:75], off offset:1152
	v_mfma_f32_32x32x16_bf16 v[2:17], v[140:143], v[184:187], v[2:17]
	s_waitcnt vmcnt(8)
	ds_write_b128 v85, v[100:103] offset:41472
	ds_read_b128 v[136:139], v66 offset:18528
	ds_read_b128 v[184:187], v0 offset:55392
	ds_read_b128 v[200:203], v0 offset:60000
	ds_read_b128 v[140:143], v66 offset:23136
	s_waitcnt lgkmcnt(6)
	v_mfma_f32_32x32x16_bf16 v[34:49], v[120:123], v[128:131], v[34:49]
	global_load_dwordx4 v[168:171], v[76:77], off offset:1152
	v_mfma_f32_32x32x16_bf16 v[18:33], v[120:123], v[132:135], v[18:33]
	s_waitcnt vmcnt(8)
	ds_write_b128 v85, v[104:107] offset:9216
	v_mfma_f32_32x32x16_bf16 v[50:65], v[124:127], v[132:135], v[50:65]
	global_load_dwordx4 v[172:175], v[78:79], off offset:1152
	v_mfma_f32_32x32x16_bf16 v[2:17], v[124:127], v[128:131], v[2:17]
	s_waitcnt vmcnt(8)
	ds_write_b128 v85, v[108:111] offset:46080
	s_waitcnt lgkmcnt(2)
	v_mfma_f32_32x32x16_bf16 v[34:49], v[136:139], v[184:187], v[34:49]
	global_load_dwordx4 v[176:179], v[80:81], off offset:1152
	v_mfma_f32_32x32x16_bf16 v[18:33], v[136:139], v[200:203], v[18:33]
	s_waitcnt vmcnt(8)
	ds_write_b128 v85, v[112:115] offset:13824
	v_mfma_f32_32x32x16_bf16 v[50:65], v[140:143], v[200:203], v[50:65]
	global_load_dwordx4 v[180:183], v[82:83], off offset:1152
	v_mfma_f32_32x32x16_bf16 v[2:17], v[140:143], v[184:187], v[2:17]
	s_waitcnt vmcnt(8)
	ds_write_b128 v85, v[116:119] offset:50688
	s_setprio 0
	s_waitcnt lgkmcnt(0)
	s_barrier
; #define MFMA(a, b, c) __builtin_amdgcn_mfma_f32_32x32x16_bf16((a), (b), (c), 0, 0, 0)
; template <bool SWAP>
; DI void gemm_block(const bf16_t* __restrict__ A, int lda, const bf16_t* __restrict__ Bt, int ldb, int K, f32x16 (&acc)[2][2], bf16_t* sA, bf16_t* sB) {
;     ...
;   for (int kt = 0; kt < nk; ++kt) {
;     const int cur = kt & 1;
;     const bool more = kt + 1 < nk;
;     if (more) {
;       const int k0 = (kt + 1) * 64;
; #pragma unroll
;       for (int i = 0; i < 4; ++i) { ra[i] = *(const u32x4*)(ga + (size_t)i * 32 * lda + k0); rb[i] = *(const u32x4*)(gb + (size_t)i * 32 * ldb + k0); }
;     }
;     const bf16_t* ab = sA + cur * 128 * LDT + (64 * wr + l32) * LDT + h * 8;
;     const bf16_t* bb = sB + cur * 128 * LDT + (64 * wc + l32) * LDT + h * 8;
;     __builtin_amdgcn_s_setprio(1);
;     __builtin_amdgcn_iglp_opt(0);
; #pragma unroll
;     for (int ks = 0; ks < 4; ++ks) {
;       const bf16x8 a0 = *(const bf16x8*)(ab + ks * 16), a1 = *(const bf16x8*)(ab + 32 * LDT + ks * 16);
;       const bf16x8 b0 = *(const bf16x8*)(bb + ks * 16), b1 = *(const bf16x8*)(bb + 32 * LDT + ks * 16);
;       if (!SWAP) {
;         acc[0][0] = MFMA(a0, b0, acc[0][0]); acc[0][1] = MFMA(a0, b1, acc[0][1]);
;         acc[1][0] = MFMA(a1, b0, acc[1][0]); acc[1][1] = MFMA(a1, b1, acc[1][1]);
;       } else {
;         acc[0][0] = MFMA(b0, a0, acc[0][0]); acc[0][1] = MFMA(b1, a0, acc[0][1]);
;         acc[1][0] = MFMA(b0, a1, acc[1][0]); acc[1][1] = MFMA(b1, a1, acc[1][1]);
;       }
;     }
;     __builtin_amdgcn_s_setprio(0);
;     if (more) {
;       const int nb = (cur ^ 1) * 128 * LDT;
; #pragma unroll
;       for (int i = 0; i < 4; ++i) { *(u32x4*)(sA + nb + soff + i * 32 * LDT) = ra[i]; *(u32x4*)(sB + nb + soff + i * 32 * LDT) = rb[i]; }
;     }
;     __syncthreads();
	ds_read_b128 v[120:123], v66
	ds_read_b128 v[128:131], v0 offset:36864
	ds_read_b128 v[132:135], v0 offset:41472
	ds_read_b128 v[124:127], v66 offset:4608
	ds_read_b128 v[136:139], v66 offset:32
	ds_read_b128 v[184:187], v0 offset:36896
	ds_read_b128 v[200:203], v0 offset:41504
	ds_read_b128 v[140:143], v66 offset:4640
	s_setprio 1
	s_waitcnt lgkmcnt(4)
	v_mfma_f32_32x32x16_bf16 v[34:49], v[120:123], v[128:131], v[34:49]
	global_load_dwordx4 v[88:91], v[68:69], off offset:1280
	v_mfma_f32_32x32x16_bf16 v[18:33], v[120:123], v[132:135], v[18:33]
	s_waitcnt vmcnt(8)
	ds_write_b128 v85, v[152:155] offset:18432
	v_mfma_f32_32x32x16_bf16 v[50:65], v[124:127], v[132:135], v[50:65]
	global_load_dwordx4 v[92:95], v[70:71], off offset:1280
	v_mfma_f32_32x32x16_bf16 v[2:17], v[124:127], v[128:131], v[2:17]
	s_waitcnt vmcnt(8)
	ds_write_b128 v85, v[156:159] offset:55296
	ds_read_b128 v[120:123], v66 offset:64
	ds_read_b128 v[128:131], v0 offset:36928
	ds_read_b128 v[132:135], v0 offset:41536
	ds_read_b128 v[124:127], v66 offset:4672
	s_waitcnt lgkmcnt(6)
	v_mfma_f32_32x32x16_bf16 v[34:49], v[136:139], v[184:187], v[34:49]
	global_load_dwordx4 v[96:99], v[72:73], off offset:1280
	v_mfma_f32_32x32x16_bf16 v[18:33], v[136:139], v[200:203], v[18:33]
	s_waitcnt vmcnt(8)
	ds_write_b128 v85, v[160:163] offset:23040
	v_mfma_f32_32x32x16_bf16 v[50:65], v[140:143], v[200:203], v[50:65]
	global_load_dwordx4 v[100:103], v[74:75], off offset:1280
	v_mfma_f32_32x32x16_bf16 v[2:17], v[140:143], v[184:187], v[2:17]
	s_waitcnt vmcnt(8)
	ds_write_b128 v85, v[164:167] offset:59904
	ds_read_b128 v[136:139], v66 offset:96
	ds_read_b128 v[184:187], v0 offset:36960
	ds_read_b128 v[200:203], v0 offset:41568
	ds_read_b128 v[140:143], v66 offset:4704
	s_waitcnt lgkmcnt(6)
	v_mfma_f32_32x32x16_bf16 v[34:49], v[120:123], v[128:131], v[34:49]
	global_load_dwordx4 v[104:107], v[76:77], off offset:1280
	v_mfma_f32_32x32x16_bf16 v[18:33], v[120:123], v[132:135], v[18:33]
	s_waitcnt vmcnt(8)
	ds_write_b128 v85, v[168:171] offset:27648
	v_mfma_f32_32x32x16_bf16 v[50:65], v[124:127], v[132:135], v[50:65]
	global_load_dwordx4 v[108:111], v[78:79], off offset:1280
	v_mfma_f32_32x32x16_bf16 v[2:17], v[124:127], v[128:131], v[2:17]
	s_waitcnt vmcnt(8)
	ds_write_b128 v85, v[172:175] offset:64512
	s_waitcnt lgkmcnt(2)
	v_mfma_f32_32x32x16_bf16 v[34:49], v[136:139], v[184:187], v[34:49]
	global_load_dwordx4 v[112:115], v[80:81], off offset:1280
	v_mfma_f32_32x32x16_bf16 v[18:33], v[136:139], v[200:203], v[18:33]
	s_waitcnt vmcnt(8)
	ds_write_b128 v85, v[176:179] offset:32256
	v_mfma_f32_32x32x16_bf16 v[50:65], v[140:143], v[200:203], v[50:65]
	global_load_dwordx4 v[116:119], v[82:83], off offset:1280
	v_mfma_f32_32x32x16_bf16 v[2:17], v[140:143], v[184:187], v[2:17]
	s_waitcnt vmcnt(8)
	ds_write_b128 v86, v[180:183] offset:32256
	s_setprio 0
	s_waitcnt lgkmcnt(0)
	s_barrier
	ds_read_b128 v[120:123], v66 offset:18432
	ds_read_b128 v[128:131], v0 offset:55296
	ds_read_b128 v[132:135], v0 offset:59904
	ds_read_b128 v[124:127], v66 offset:23040
	ds_read_b128 v[136:139], v66 offset:18464
	ds_read_b128 v[184:187], v0 offset:55328
	ds_read_b128 v[200:203], v0 offset:59936
	ds_read_b128 v[140:143], v66 offset:23072
	s_setprio 1
	s_waitcnt lgkmcnt(4)
	v_mfma_f32_32x32x16_bf16 v[34:49], v[120:123], v[128:131], v[34:49]
	global_load_dwordx4 v[152:155], v[68:69], off offset:1408
	v_mfma_f32_32x32x16_bf16 v[18:33], v[120:123], v[132:135], v[18:33]
	s_waitcnt vmcnt(8)
	ds_write_b128 v85, v[88:91]
	v_mfma_f32_32x32x16_bf16 v[50:65], v[124:127], v[132:135], v[50:65]
	global_load_dwordx4 v[156:159], v[70:71], off offset:1408
	v_mfma_f32_32x32x16_bf16 v[2:17], v[124:127], v[128:131], v[2:17]
	s_waitcnt vmcnt(8)
	ds_write_b128 v85, v[92:95] offset:36864
	ds_read_b128 v[120:123], v66 offset:18496
	ds_read_b128 v[128:131], v0 offset:55360
	ds_read_b128 v[132:135], v0 offset:59968
	ds_read_b128 v[124:127], v66 offset:23104
	s_waitcnt lgkmcnt(6)
	v_mfma_f32_32x32x16_bf16 v[34:49], v[136:139], v[184:187], v[34:49]
	global_load_dwordx4 v[160:163], v[72:73], off offset:1408
	v_mfma_f32_32x32x16_bf16 v[18:33], v[136:139], v[200:203], v[18:33]
	s_waitcnt vmcnt(8)
	ds_write_b128 v85, v[96:99] offset:4608
	v_mfma_f32_32x32x16_bf16 v[50:65], v[140:143], v[200:203], v[50:65]
	global_load_dwordx4 v[164:167], v[74:75], off offset:1408
	v_mfma_f32_32x32x16_bf16 v[2:17], v[140:143], v[184:187], v[2:17]
	s_waitcnt vmcnt(8)
	ds_write_b128 v85, v[100:103] offset:41472
	ds_read_b128 v[136:139], v66 offset:18528
	ds_read_b128 v[184:187], v0 offset:55392
	ds_read_b128 v[200:203], v0 offset:60000
	ds_read_b128 v[140:143], v66 offset:23136
	s_waitcnt lgkmcnt(6)
	v_mfma_f32_32x32x16_bf16 v[34:49], v[120:123], v[128:131], v[34:49]
	global_load_dwordx4 v[168:171], v[76:77], off offset:1408
	v_mfma_f32_32x32x16_bf16 v[18:33], v[120:123], v[132:135], v[18:33]
	s_waitcnt vmcnt(8)
	ds_write_b128 v85, v[104:107] offset:9216
	v_mfma_f32_32x32x16_bf16 v[50:65], v[124:127], v[132:135], v[50:65]
	global_load_dwordx4 v[172:175], v[78:79], off offset:1408
	v_mfma_f32_32x32x16_bf16 v[2:17], v[124:127], v[128:131], v[2:17]
	s_waitcnt vmcnt(8)
	ds_write_b128 v85, v[108:111] offset:46080
	s_waitcnt lgkmcnt(2)
	v_mfma_f32_32x32x16_bf16 v[34:49], v[136:139], v[184:187], v[34:49]
	global_load_dwordx4 v[176:179], v[80:81], off offset:1408
	v_mfma_f32_32x32x16_bf16 v[18:33], v[136:139], v[200:203], v[18:33]
	s_waitcnt vmcnt(8)
	ds_write_b128 v85, v[112:115] offset:13824
	v_mfma_f32_32x32x16_bf16 v[50:65], v[140:143], v[200:203], v[50:65]
	global_load_dwordx4 v[180:183], v[82:83], off offset:1408
	v_mfma_f32_32x32x16_bf16 v[2:17], v[140:143], v[184:187], v[2:17]
	s_waitcnt vmcnt(8)
	ds_write_b128 v85, v[116:119] offset:50688
	s_setprio 0
	s_waitcnt lgkmcnt(0)
	s_barrier
; #define MFMA(a, b, c) __builtin_amdgcn_mfma_f32_32x32x16_bf16((a), (b), (c), 0, 0, 0)
; template <bool SWAP>
; DI void gemm_block(const bf16_t* __restrict__ A, int lda, const bf16_t* __restrict__ Bt, int ldb, int K, f32x16 (&acc)[2][2], bf16_t* sA, bf16_t* sB) {
;     ...
;   for (int kt = 0; kt < nk; ++kt) {
;     const int cur = kt & 1;
;     const bool more = kt + 1 < nk;
;     if (more) {
;       const int k0 = (kt + 1) * 64;
; #pragma unroll
;       for (int i = 0; i < 4; ++i) { ra[i] = *(const u32x4*)(ga + (size_t)i * 32 * lda + k0); rb[i] = *(const u32x4*)(gb + (size_t)i * 32 * ldb + k0); }
;     }
;     const bf16_t* ab = sA + cur * 128 * LDT + (64 * wr + l32) * LDT + h * 8;
;     const bf16_t* bb = sB + cur * 128 * LDT + (64 * wc + l32) * LDT + h * 8;
;     __builtin_amdgcn_s_setprio(1);
;     __builtin_amdgcn_iglp_opt(0);
; #pragma unroll
;     for (int ks = 0; ks < 4; ++ks) {
;       const bf16x8 a0 = *(const bf16x8*)(ab + ks * 16), a1 = *(const bf16x8*)(ab + 32 * LDT + ks * 16);
;       const bf16x8 b0 = *(const bf16x8*)(bb + ks * 16), b1 = *(const bf16x8*)(bb + 32 * LDT + ks * 16);
;       if (!SWAP) {
;         acc[0][0] = MFMA(a0, b0, acc[0][0]); acc[0][1] = MFMA(a0, b1, acc[0][1]);
;         acc[1][0] = MFMA(a1, b0, acc[1][0]); acc[1][1] = MFMA(a1, b1, acc[1][1]);
;       } else {
;         acc[0][0] = MFMA(b0, a0, acc[0][0]); acc[0][1] = MFMA(b1, a0, acc[0][1]);
;         acc[1][0] = MFMA(b0, a1, acc[1][0]); acc[1][1] = MFMA(b1, a1, acc[1][1]);
;       }
;     }
;     __builtin_amdgcn_s_setprio(0);
;     if (more) {
;       const int nb = (cur ^ 1) * 128 * LDT;
; #pragma unroll
;       for (int i = 0; i < 4; ++i) { *(u32x4*)(sA + nb + soff + i * 32 * LDT) = ra[i]; *(u32x4*)(sB + nb + soff + i * 32 * LDT) = rb[i]; }
;     }
;     __syncthreads();
	ds_read_b128 v[120:123], v66
	ds_read_b128 v[128:131], v0 offset:36864
	ds_read_b128 v[132:135], v0 offset:41472
	ds_read_b128 v[124:127], v66 offset:4608
	ds_read_b128 v[136:139], v66 offset:32
	ds_read_b128 v[184:187], v0 offset:36896
	ds_read_b128 v[200:203], v0 offset:41504
	ds_read_b128 v[140:143], v66 offset:4640
	s_setprio 1
	s_waitcnt lgkmcnt(4)
	v_mfma_f32_32x32x16_bf16 v[34:49], v[120:123], v[128:131], v[34:49]
	global_load_dwordx4 v[88:91], v[68:69], off offset:1536
	v_mfma_f32_32x32x16_bf16 v[18:33], v[120:123], v[132:135], v[18:33]
	s_waitcnt vmcnt(8)
	ds_write_b128 v85, v[152:155] offset:18432
	v_mfma_f32_32x32x16_bf16 v[50:65], v[124:127], v[132:135], v[50:65]
	global_load_dwordx4 v[92:95], v[70:71], off offset:1536
	v_mfma_f32_32x32x16_bf16 v[2:17], v[124:127], v[128:131], v[2:17]
	s_waitcnt vmcnt(8)
	ds_write_b128 v85, v[156:159] offset:55296
	ds_read_b128 v[120:123], v66 offset:64
	ds_read_b128 v[128:131], v0 offset:36928
	ds_read_b128 v[132:135], v0 offset:41536
	ds_read_b128 v[124:127], v66 offset:4672
	s_waitcnt lgkmcnt(6)
	v_mfma_f32_32x32x16_bf16 v[34:49], v[136:139], v[184:187], v[34:49]
	global_load_dwordx4 v[96:99], v[72:73], off offset:1536
	v_mfma_f32_32x32x16_bf16 v[18:33], v[136:139], v[200:203], v[18:33]
	s_waitcnt vmcnt(8)
	ds_write_b128 v85, v[160:163] offset:23040
	v_mfma_f32_32x32x16_bf16 v[50:65], v[140:143], v[200:203], v[50:65]
	global_load_dwordx4 v[100:103], v[74:75], off offset:1536
	v_mfma_f32_32x32x16_bf16 v[2:17], v[140:143], v[184:187], v[2:17]
	s_waitcnt vmcnt(8)
	ds_write_b128 v85, v[164:167] offset:59904
	ds_read_b128 v[136:139], v66 offset:96
	ds_read_b128 v[184:187], v0 offset:36960
	ds_read_b128 v[200:203], v0 offset:41568
	ds_read_b128 v[140:143], v66 offset:4704
	s_waitcnt lgkmcnt(6)
	v_mfma_f32_32x32x16_bf16 v[34:49], v[120:123], v[128:131], v[34:49]
	global_load_dwordx4 v[104:107], v[76:77], off offset:1536
	v_mfma_f32_32x32x16_bf16 v[18:33], v[120:123], v[132:135], v[18:33]
	s_waitcnt vmcnt(8)
	ds_write_b128 v85, v[168:171] offset:27648
	v_mfma_f32_32x32x16_bf16 v[50:65], v[124:127], v[132:135], v[50:65]
	global_load_dwordx4 v[108:111], v[78:79], off offset:1536
	v_mfma_f32_32x32x16_bf16 v[2:17], v[124:127], v[128:131], v[2:17]
	s_waitcnt vmcnt(8)
	ds_write_b128 v85, v[172:175] offset:64512
	s_waitcnt lgkmcnt(2)
	v_mfma_f32_32x32x16_bf16 v[34:49], v[136:139], v[184:187], v[34:49]
	global_load_dwordx4 v[112:115], v[80:81], off offset:1536
	v_mfma_f32_32x32x16_bf16 v[18:33], v[136:139], v[200:203], v[18:33]
	s_waitcnt vmcnt(8)
	ds_write_b128 v85, v[176:179] offset:32256
	v_mfma_f32_32x32x16_bf16 v[50:65], v[140:143], v[200:203], v[50:65]
	global_load_dwordx4 v[116:119], v[82:83], off offset:1536
	v_mfma_f32_32x32x16_bf16 v[2:17], v[140:143], v[184:187], v[2:17]
	s_waitcnt vmcnt(8)
	ds_write_b128 v86, v[180:183] offset:32256
	s_setprio 0
	s_waitcnt lgkmcnt(0)
	s_barrier
	ds_read_b128 v[120:123], v66 offset:18432
	ds_read_b128 v[128:131], v0 offset:55296
	ds_read_b128 v[132:135], v0 offset:59904
	ds_read_b128 v[124:127], v66 offset:23040
	ds_read_b128 v[136:139], v66 offset:18464
	ds_read_b128 v[184:187], v0 offset:55328
	ds_read_b128 v[200:203], v0 offset:59936
	ds_read_b128 v[140:143], v66 offset:23072
	s_setprio 1
	s_waitcnt lgkmcnt(4)
	v_mfma_f32_32x32x16_bf16 v[34:49], v[120:123], v[128:131], v[34:49]
	global_load_dwordx4 v[152:155], v[68:69], off offset:1664
	v_mfma_f32_32x32x16_bf16 v[18:33], v[120:123], v[132:135], v[18:33]
	s_waitcnt vmcnt(8)
	ds_write_b128 v85, v[88:91]
	v_mfma_f32_32x32x16_bf16 v[50:65], v[124:127], v[132:135], v[50:65]
	global_load_dwordx4 v[156:159], v[70:71], off offset:1664
	v_mfma_f32_32x32x16_bf16 v[2:17], v[124:127], v[128:131], v[2:17]
	s_waitcnt vmcnt(8)
	ds_write_b128 v85, v[92:95] offset:36864
	ds_read_b128 v[120:123], v66 offset:18496
	ds_read_b128 v[128:131], v0 offset:55360
	ds_read_b128 v[132:135], v0 offset:59968
	ds_read_b128 v[124:127], v66 offset:23104
	s_waitcnt lgkmcnt(6)
	v_mfma_f32_32x32x16_bf16 v[34:49], v[136:139], v[184:187], v[34:49]
	global_load_dwordx4 v[160:163], v[72:73], off offset:1664
	v_mfma_f32_32x32x16_bf16 v[18:33], v[136:139], v[200:203], v[18:33]
	s_waitcnt vmcnt(8)
	ds_write_b128 v85, v[96:99] offset:4608
	v_mfma_f32_32x32x16_bf16 v[50:65], v[140:143], v[200:203], v[50:65]
	global_load_dwordx4 v[164:167], v[74:75], off offset:1664
	v_mfma_f32_32x32x16_bf16 v[2:17], v[140:143], v[184:187], v[2:17]
	s_waitcnt vmcnt(8)
	ds_write_b128 v85, v[100:103] offset:41472
	ds_read_b128 v[136:139], v66 offset:18528
	ds_read_b128 v[184:187], v0 offset:55392
	ds_read_b128 v[200:203], v0 offset:60000
	ds_read_b128 v[140:143], v66 offset:23136
	s_waitcnt lgkmcnt(6)
	v_mfma_f32_32x32x16_bf16 v[34:49], v[120:123], v[128:131], v[34:49]
	global_load_dwordx4 v[168:171], v[76:77], off offset:1664
	v_mfma_f32_32x32x16_bf16 v[18:33], v[120:123], v[132:135], v[18:33]
	s_waitcnt vmcnt(8)
	ds_write_b128 v85, v[104:107] offset:9216
	v_mfma_f32_32x32x16_bf16 v[50:65], v[124:127], v[132:135], v[50:65]
	global_load_dwordx4 v[172:175], v[78:79], off offset:1664
	v_mfma_f32_32x32x16_bf16 v[2:17], v[124:127], v[128:131], v[2:17]
	s_waitcnt vmcnt(8)
	ds_write_b128 v85, v[108:111] offset:46080
	s_waitcnt lgkmcnt(2)
	v_mfma_f32_32x32x16_bf16 v[34:49], v[136:139], v[184:187], v[34:49]
	global_load_dwordx4 v[176:179], v[80:81], off offset:1664
	v_mfma_f32_32x32x16_bf16 v[18:33], v[136:139], v[200:203], v[18:33]
	s_waitcnt vmcnt(8)
	ds_write_b128 v85, v[112:115] offset:13824
	v_mfma_f32_32x32x16_bf16 v[50:65], v[140:143], v[200:203], v[50:65]
	global_load_dwordx4 v[180:183], v[82:83], off offset:1664
	v_mfma_f32_32x32x16_bf16 v[2:17], v[140:143], v[184:187], v[2:17]
	s_waitcnt vmcnt(8)
	ds_write_b128 v85, v[116:119] offset:50688
	s_setprio 0
	s_waitcnt lgkmcnt(0)
	s_barrier
; #define MFMA(a, b, c) __builtin_amdgcn_mfma_f32_32x32x16_bf16((a), (b), (c), 0, 0, 0)
; template <bool SWAP>
; DI void gemm_block(const bf16_t* __restrict__ A, int lda, const bf16_t* __restrict__ Bt, int ldb, int K, f32x16 (&acc)[2][2], bf16_t* sA, bf16_t* sB) {
;     ...
;   for (int kt = 0; kt < nk; ++kt) {
;     const int cur = kt & 1;
;     const bool more = kt + 1 < nk;
;     if (more) {
;       const int k0 = (kt + 1) * 64;
; #pragma unroll
;       for (int i = 0; i < 4; ++i) { ra[i] = *(const u32x4*)(ga + (size_t)i * 32 * lda + k0); rb[i] = *(const u32x4*)(gb + (size_t)i * 32 * ldb + k0); }
;     }
;     const bf16_t* ab = sA + cur * 128 * LDT + (64 * wr + l32) * LDT + h * 8;
;     const bf16_t* bb = sB + cur * 128 * LDT + (64 * wc + l32) * LDT + h * 8;
;     __builtin_amdgcn_s_setprio(1);
;     __builtin_amdgcn_iglp_opt(0);
; #pragma unroll
;     for (int ks = 0; ks < 4; ++ks) {
;       const bf16x8 a0 = *(const bf16x8*)(ab + ks * 16), a1 = *(const bf16x8*)(ab + 32 * LDT + ks * 16);
;       const bf16x8 b0 = *(const bf16x8*)(bb + ks * 16), b1 = *(const bf16x8*)(bb + 32 * LDT + ks * 16);
;       if (!SWAP) {
;         acc[0][0] = MFMA(a0, b0, acc[0][0]); acc[0][1] = MFMA(a0, b1, acc[0][1]);
;         acc[1][0] = MFMA(a1, b0, acc[1][0]); acc[1][1] = MFMA(a1, b1, acc[1][1]);
;       } else {
;         acc[0][0] = MFMA(b0, a0, acc[0][0]); acc[0][1] = MFMA(b1, a0, acc[0][1]);
;         acc[1][0] = MFMA(b0, a1, acc[1][0]); acc[1][1] = MFMA(b1, a1, acc[1][1]);
;       }
;     }
;     __builtin_amdgcn_s_setprio(0);
;     if (more) {
;       const int nb = (cur ^ 1) * 128 * LDT;
; #pragma unroll
;       for (int i = 0; i < 4; ++i) { *(u32x4*)(sA + nb + soff + i * 32 * LDT) = ra[i]; *(u32x4*)(sB + nb + soff + i * 32 * LDT) = rb[i]; }
;     }
;     __syncthreads();
	ds_read_b128 v[120:123], v66
	ds_read_b128 v[128:131], v0 offset:36864
	ds_read_b128 v[132:135], v0 offset:41472
	ds_read_b128 v[124:127], v66 offset:4608
	ds_read_b128 v[136:139], v66 offset:32
	ds_read_b128 v[184:187], v0 offset:36896
	ds_read_b128 v[200:203], v0 offset:41504
	ds_read_b128 v[140:143], v66 offset:4640
	s_setprio 1
	s_waitcnt lgkmcnt(4)
	v_mfma_f32_32x32x16_bf16 v[34:49], v[120:123], v[128:131], v[34:49]
	global_load_dwordx4 v[88:91], v[68:69], off offset:1792
	v_mfma_f32_32x32x16_bf16 v[18:33], v[120:123], v[132:135], v[18:33]
	s_waitcnt vmcnt(8)
	ds_write_b128 v85, v[152:155] offset:18432
	v_mfma_f32_32x32x16_bf16 v[50:65], v[124:127], v[132:135], v[50:65]
	global_load_dwordx4 v[92:95], v[70:71], off offset:1792
	v_mfma_f32_32x32x16_bf16 v[2:17], v[124:127], v[128:131], v[2:17]
	s_waitcnt vmcnt(8)
	ds_write_b128 v85, v[156:159] offset:55296
	ds_read_b128 v[120:123], v66 offset:64
	ds_read_b128 v[128:131], v0 offset:36928
	ds_read_b128 v[132:135], v0 offset:41536
	ds_read_b128 v[124:127], v66 offset:4672
	s_waitcnt lgkmcnt(6)
	v_mfma_f32_32x32x16_bf16 v[34:49], v[136:139], v[184:187], v[34:49]
	global_load_dwordx4 v[96:99], v[72:73], off offset:1792
	v_mfma_f32_32x32x16_bf16 v[18:33], v[136:139], v[200:203], v[18:33]
	s_waitcnt vmcnt(8)
	ds_write_b128 v85, v[160:163] offset:23040
	v_mfma_f32_32x32x16_bf16 v[50:65], v[140:143], v[200:203], v[50:65]
	global_load_dwordx4 v[100:103], v[74:75], off offset:1792
	v_mfma_f32_32x32x16_bf16 v[2:17], v[140:143], v[184:187], v[2:17]
	s_waitcnt vmcnt(8)
	ds_write_b128 v85, v[164:167] offset:59904
	ds_read_b128 v[136:139], v66 offset:96
	ds_read_b128 v[184:187], v0 offset:36960
	ds_read_b128 v[200:203], v0 offset:41568
	ds_read_b128 v[140:143], v66 offset:4704
	s_waitcnt lgkmcnt(6)
	v_mfma_f32_32x32x16_bf16 v[34:49], v[120:123], v[128:131], v[34:49]
	global_load_dwordx4 v[104:107], v[76:77], off offset:1792
	v_mfma_f32_32x32x16_bf16 v[18:33], v[120:123], v[132:135], v[18:33]
	s_waitcnt vmcnt(8)
	ds_write_b128 v85, v[168:171] offset:27648
	v_mfma_f32_32x32x16_bf16 v[50:65], v[124:127], v[132:135], v[50:65]
	global_load_dwordx4 v[108:111], v[78:79], off offset:1792
	v_mfma_f32_32x32x16_bf16 v[2:17], v[124:127], v[128:131], v[2:17]
	s_waitcnt vmcnt(8)
	ds_write_b128 v85, v[172:175] offset:64512
	s_waitcnt lgkmcnt(2)
	v_mfma_f32_32x32x16_bf16 v[34:49], v[136:139], v[184:187], v[34:49]
	global_load_dwordx4 v[112:115], v[80:81], off offset:1792
	v_mfma_f32_32x32x16_bf16 v[18:33], v[136:139], v[200:203], v[18:33]
	s_waitcnt vmcnt(8)
	ds_write_b128 v85, v[176:179] offset:32256
	v_mfma_f32_32x32x16_bf16 v[50:65], v[140:143], v[200:203], v[50:65]
	global_load_dwordx4 v[116:119], v[82:83], off offset:1792
	v_mfma_f32_32x32x16_bf16 v[2:17], v[140:143], v[184:187], v[2:17]
	s_waitcnt vmcnt(8)
	ds_write_b128 v86, v[180:183] offset:32256
	s_setprio 0
	s_waitcnt lgkmcnt(0)
	s_barrier
	ds_read_b128 v[120:123], v66 offset:18432
	ds_read_b128 v[128:131], v0 offset:55296
	ds_read_b128 v[132:135], v0 offset:59904
	ds_read_b128 v[124:127], v66 offset:23040
	ds_read_b128 v[136:139], v66 offset:18464
	ds_read_b128 v[184:187], v0 offset:55328
	ds_read_b128 v[200:203], v0 offset:59936
	ds_read_b128 v[140:143], v66 offset:23072
	s_setprio 1
	s_waitcnt lgkmcnt(4)
	v_mfma_f32_32x32x16_bf16 v[34:49], v[120:123], v[128:131], v[34:49]
	global_load_dwordx4 v[152:155], v[68:69], off offset:1920
	v_mfma_f32_32x32x16_bf16 v[18:33], v[120:123], v[132:135], v[18:33]
	s_waitcnt vmcnt(8)
	ds_write_b128 v85, v[88:91]
	v_mfma_f32_32x32x16_bf16 v[50:65], v[124:127], v[132:135], v[50:65]
	global_load_dwordx4 v[156:159], v[70:71], off offset:1920
	v_mfma_f32_32x32x16_bf16 v[2:17], v[124:127], v[128:131], v[2:17]
	s_waitcnt vmcnt(8)
	ds_write_b128 v85, v[92:95] offset:36864
	ds_read_b128 v[120:123], v66 offset:18496
	ds_read_b128 v[128:131], v0 offset:55360
	ds_read_b128 v[132:135], v0 offset:59968
	ds_read_b128 v[124:127], v66 offset:23104
	s_waitcnt lgkmcnt(6)
	v_mfma_f32_32x32x16_bf16 v[34:49], v[136:139], v[184:187], v[34:49]
	global_load_dwordx4 v[160:163], v[72:73], off offset:1920
	v_mfma_f32_32x32x16_bf16 v[18:33], v[136:139], v[200:203], v[18:33]
	s_waitcnt vmcnt(8)
	ds_write_b128 v85, v[96:99] offset:4608
	v_mfma_f32_32x32x16_bf16 v[50:65], v[140:143], v[200:203], v[50:65]
	global_load_dwordx4 v[164:167], v[74:75], off offset:1920
	v_mfma_f32_32x32x16_bf16 v[2:17], v[140:143], v[184:187], v[2:17]
	s_waitcnt vmcnt(8)
	ds_write_b128 v85, v[100:103] offset:41472
	ds_read_b128 v[136:139], v66 offset:18528
	ds_read_b128 v[184:187], v0 offset:55392
	ds_read_b128 v[200:203], v0 offset:60000
	ds_read_b128 v[140:143], v66 offset:23136
	s_waitcnt lgkmcnt(6)
	v_mfma_f32_32x32x16_bf16 v[34:49], v[120:123], v[128:131], v[34:49]
	global_load_dwordx4 v[168:171], v[76:77], off offset:1920
	v_mfma_f32_32x32x16_bf16 v[18:33], v[120:123], v[132:135], v[18:33]
	s_waitcnt vmcnt(8)
	ds_write_b128 v85, v[104:107] offset:9216
	v_mfma_f32_32x32x16_bf16 v[50:65], v[124:127], v[132:135], v[50:65]
	global_load_dwordx4 v[172:175], v[78:79], off offset:1920
	v_mfma_f32_32x32x16_bf16 v[2:17], v[124:127], v[128:131], v[2:17]
	s_waitcnt vmcnt(8)
	ds_write_b128 v85, v[108:111] offset:46080
	s_waitcnt lgkmcnt(2)
	v_mfma_f32_32x32x16_bf16 v[34:49], v[136:139], v[184:187], v[34:49]
	global_load_dwordx4 v[176:179], v[80:81], off offset:1920
	v_mfma_f32_32x32x16_bf16 v[18:33], v[136:139], v[200:203], v[18:33]
	s_waitcnt vmcnt(8)
	ds_write_b128 v85, v[112:115] offset:13824
	v_mfma_f32_32x32x16_bf16 v[50:65], v[140:143], v[200:203], v[50:65]
	global_load_dwordx4 v[180:183], v[82:83], off offset:1920
	v_mfma_f32_32x32x16_bf16 v[2:17], v[140:143], v[184:187], v[2:17]
	s_waitcnt vmcnt(8)
	ds_write_b128 v85, v[116:119] offset:50688
	s_setprio 0
	s_waitcnt lgkmcnt(0)
	s_barrier
; #define MFMA(a, b, c) __builtin_amdgcn_mfma_f32_32x32x16_bf16((a), (b), (c), 0, 0, 0)
; template <bool SWAP>
; DI void gemm_block(const bf16_t* __restrict__ A, int lda, const bf16_t* __restrict__ Bt, int ldb, int K, f32x16 (&acc)[2][2], bf16_t* sA, bf16_t* sB) {
;     ...
;   for (int kt = 0; kt < nk; ++kt) {
;     const int cur = kt & 1;
;     const bool more = kt + 1 < nk;
;     if (more) {
;       const int k0 = (kt + 1) * 64;
; #pragma unroll
;       for (int i = 0; i < 4; ++i) { ra[i] = *(const u32x4*)(ga + (size_t)i * 32 * lda + k0); rb[i] = *(const u32x4*)(gb + (size_t)i * 32 * ldb + k0); }
;     }
;     const bf16_t* ab = sA + cur * 128 * LDT + (64 * wr + l32) * LDT + h * 8;
;     const bf16_t* bb = sB + cur * 128 * LDT + (64 * wc + l32) * LDT + h * 8;
;     __builtin_amdgcn_s_setprio(1);
;     __builtin_amdgcn_iglp_opt(0);
; #pragma unroll
;     for (int ks = 0; ks < 4; ++ks) {
;       const bf16x8 a0 = *(const bf16x8*)(ab + ks * 16), a1 = *(const bf16x8*)(ab + 32 * LDT + ks * 16);
;       const bf16x8 b0 = *(const bf16x8*)(bb + ks * 16), b1 = *(const bf16x8*)(bb + 32 * LDT + ks * 16);
;       if (!SWAP) {
;         acc[0][0] = MFMA(a0, b0, acc[0][0]); acc[0][1] = MFMA(a0, b1, acc[0][1]);
;         acc[1][0] = MFMA(a1, b0, acc[1][0]); acc[1][1] = MFMA(a1, b1, acc[1][1]);
;       } else {
;         acc[0][0] = MFMA(b0, a0, acc[0][0]); acc[0][1] = MFMA(b1, a0, acc[0][1]);
;         acc[1][0] = MFMA(b0, a1, acc[1][0]); acc[1][1] = MFMA(b1, a1, acc[1][1]);
;       }
;     }
;     __builtin_amdgcn_s_setprio(0);
;     if (more) {
;       const int nb = (cur ^ 1) * 128 * LDT;
; #pragma unroll
;       for (int i = 0; i < 4; ++i) { *(u32x4*)(sA + nb + soff + i * 32 * LDT) = ra[i]; *(u32x4*)(sB + nb + soff + i * 32 * LDT) = rb[i]; }
;     }
;     __syncthreads();
	ds_read_b128 v[120:123], v66
	ds_read_b128 v[128:131], v0 offset:36864
	ds_read_b128 v[132:135], v0 offset:41472
	ds_read_b128 v[124:127], v66 offset:4608
	ds_read_b128 v[136:139], v66 offset:32
	ds_read_b128 v[184:187], v0 offset:36896
	ds_read_b128 v[200:203], v0 offset:41504
	ds_read_b128 v[140:143], v66 offset:4640
	s_setprio 1
	s_waitcnt lgkmcnt(4)
	v_mfma_f32_32x32x16_bf16 v[34:49], v[120:123], v[128:131], v[34:49]
	v_mfma_f32_32x32x16_bf16 v[18:33], v[120:123], v[132:135], v[18:33]
	s_waitcnt vmcnt(7)
	ds_write_b128 v85, v[152:155] offset:18432
	v_mfma_f32_32x32x16_bf16 v[50:65], v[124:127], v[132:135], v[50:65]
	v_mfma_f32_32x32x16_bf16 v[2:17], v[124:127], v[128:131], v[2:17]
	s_waitcnt vmcnt(6)
	ds_write_b128 v85, v[156:159] offset:55296
	ds_read_b128 v[120:123], v66 offset:64
	ds_read_b128 v[128:131], v0 offset:36928
	ds_read_b128 v[132:135], v0 offset:41536
	ds_read_b128 v[124:127], v66 offset:4672
	s_waitcnt lgkmcnt(6)
	v_mfma_f32_32x32x16_bf16 v[34:49], v[136:139], v[184:187], v[34:49]
	v_mfma_f32_32x32x16_bf16 v[18:33], v[136:139], v[200:203], v[18:33]
	s_waitcnt vmcnt(5)
	ds_write_b128 v85, v[160:163] offset:23040
	v_mfma_f32_32x32x16_bf16 v[50:65], v[140:143], v[200:203], v[50:65]
	v_mfma_f32_32x32x16_bf16 v[2:17], v[140:143], v[184:187], v[2:17]
	s_waitcnt vmcnt(4)
	ds_write_b128 v85, v[164:167] offset:59904
	ds_read_b128 v[136:139], v66 offset:96
	ds_read_b128 v[184:187], v0 offset:36960
	ds_read_b128 v[200:203], v0 offset:41568
	ds_read_b128 v[140:143], v66 offset:4704
	s_waitcnt lgkmcnt(6)
	v_mfma_f32_32x32x16_bf16 v[34:49], v[120:123], v[128:131], v[34:49]
	v_mfma_f32_32x32x16_bf16 v[18:33], v[120:123], v[132:135], v[18:33]
	s_waitcnt vmcnt(3)
	ds_write_b128 v85, v[168:171] offset:27648
	v_mfma_f32_32x32x16_bf16 v[50:65], v[124:127], v[132:135], v[50:65]
	v_mfma_f32_32x32x16_bf16 v[2:17], v[124:127], v[128:131], v[2:17]
	s_waitcnt vmcnt(2)
	ds_write_b128 v85, v[172:175] offset:64512
	s_waitcnt lgkmcnt(2)
	v_mfma_f32_32x32x16_bf16 v[34:49], v[136:139], v[184:187], v[34:49]
	v_mfma_f32_32x32x16_bf16 v[18:33], v[136:139], v[200:203], v[18:33]
	s_waitcnt vmcnt(1)
	ds_write_b128 v85, v[176:179] offset:32256
	v_mfma_f32_32x32x16_bf16 v[50:65], v[140:143], v[200:203], v[50:65]
	v_mfma_f32_32x32x16_bf16 v[2:17], v[140:143], v[184:187], v[2:17]
	s_waitcnt vmcnt(0)
	ds_write_b128 v86, v[180:183] offset:32256
	s_setprio 0
	s_waitcnt lgkmcnt(0)
	s_barrier
	ds_read_b128 v[120:123], v66 offset:18432
	ds_read_b128 v[128:131], v0 offset:55296
	ds_read_b128 v[132:135], v0 offset:59904
	ds_read_b128 v[124:127], v66 offset:23040
	ds_read_b128 v[136:139], v66 offset:18464
	ds_read_b128 v[184:187], v0 offset:55328
	ds_read_b128 v[200:203], v0 offset:59936
	ds_read_b128 v[140:143], v66 offset:23072
	s_setprio 1
	s_waitcnt lgkmcnt(4)
	v_mfma_f32_32x32x16_bf16 v[34:49], v[120:123], v[128:131], v[34:49]
	v_mfma_f32_32x32x16_bf16 v[18:33], v[120:123], v[132:135], v[18:33]
	v_mfma_f32_32x32x16_bf16 v[50:65], v[124:127], v[132:135], v[50:65]
	v_mfma_f32_32x32x16_bf16 v[2:17], v[124:127], v[128:131], v[2:17]
	ds_read_b128 v[120:123], v66 offset:18496
	ds_read_b128 v[128:131], v0 offset:55360
	ds_read_b128 v[132:135], v0 offset:59968
	ds_read_b128 v[124:127], v66 offset:23104
	s_waitcnt lgkmcnt(4)
	v_mfma_f32_32x32x16_bf16 v[34:49], v[136:139], v[184:187], v[34:49]
	v_mfma_f32_32x32x16_bf16 v[18:33], v[136:139], v[200:203], v[18:33]
	v_mfma_f32_32x32x16_bf16 v[50:65], v[140:143], v[200:203], v[50:65]
	v_mfma_f32_32x32x16_bf16 v[2:17], v[140:143], v[184:187], v[2:17]
	ds_read_b128 v[136:139], v66 offset:18528
	ds_read_b128 v[184:187], v0 offset:55392
	ds_read_b128 v[200:203], v0 offset:60000
	ds_read_b128 v[140:143], v66 offset:23136
	s_waitcnt lgkmcnt(4)
	v_mfma_f32_32x32x16_bf16 v[34:49], v[120:123], v[128:131], v[34:49]
	v_mfma_f32_32x32x16_bf16 v[18:33], v[120:123], v[132:135], v[18:33]
	v_mfma_f32_32x32x16_bf16 v[50:65], v[124:127], v[132:135], v[50:65]
	v_mfma_f32_32x32x16_bf16 v[2:17], v[124:127], v[128:131], v[2:17]
	s_waitcnt lgkmcnt(0)
	v_mfma_f32_32x32x16_bf16 v[34:49], v[136:139], v[184:187], v[34:49]
	v_mfma_f32_32x32x16_bf16 v[18:33], v[136:139], v[200:203], v[18:33]
	v_mfma_f32_32x32x16_bf16 v[50:65], v[140:143], v[200:203], v[50:65]
	v_mfma_f32_32x32x16_bf16 v[2:17], v[140:143], v[184:187], v[2:17]
	s_setprio 0
	s_nop 7
	s_nop 7
	s_barrier

; template <bool SWAP>
; DI void gemm_block(const bf16_t* __restrict__ A, int lda, const bf16_t* __restrict__ Bt, int ldb, int K, f32x16 (&acc)[2][2], bf16_t* sA, bf16_t* sB) {
;     ...
;   const int lrow = tid >> 3, lch = (tid & 7) * 8;
;   const bf16_t* ga = A + (size_t)lrow * lda + lch;
;   const bf16_t* gb = Bt + (size_t)lrow * ldb + lch;
;   const int soff = lrow * LDT + lch;
;   u32x4 ra[4], rb[4];
; #pragma unroll
;   for (int i = 0; i < 4; ++i) { ra[i] = *(const u32x4*)(ga + (size_t)i * 32 * lda); rb[i] = *(const u32x4*)(gb + (size_t)i * 32 * ldb); }
; #pragma unroll
;   for (int i = 0; i < 4; ++i) { *(u32x4*)(sA + soff + i * 32 * LDT) = ra[i]; *(u32x4*)(sB + soff + i * 32 * LDT) = rb[i]; }
;   __syncthreads();
;   const int nk = K >> 6;
;   for (int kt = 0; kt < nk; ++kt) {
;     const int cur = kt & 1;
;     const bool more = kt + 1 < nk;
;     if (more) {
;       const int k0 = (kt + 1) * 64;
; #pragma unroll
;       for (int i = 0; i < 4; ++i) { ra[i] = *(const u32x4*)(ga + (size_t)i * 32 * lda + k0); rb[i] = *(const u32x4*)(gb + (size_t)i * 32 * ldb + k0); }
;     }
;     const bf16_t* ab = sA + cur * 128 * LDT + (64 * wr + l32) * LDT + h * 8;
;     const bf16_t* bb = sB + cur * 128 * LDT + (64 * wc + l32) * LDT + h * 8;
;     __builtin_amdgcn_s_setprio(1);
;     __builtin_amdgcn_iglp_opt(0);
; #pragma unroll
;     for (int ks = 0; ks < 4; ++ks) {
;       const bf16x8 a0 = *(const bf16x8*)(ab + ks * 16), a1 = *(const bf16x8*)(ab + 32 * LDT + ks * 16);
;       const bf16x8 b0 = *(const bf16x8*)(bb + ks * 16), b1 = *(const bf16x8*)(bb + 32 * LDT + ks * 16);
;       if (!SWAP) {
;         acc[0][0] = MFMA(a0, b0, acc[0][0]); acc[0][1] = MFMA(a0, b1, acc[0][1]);
;         acc[1][0] = MFMA(a1, b0, acc[1][0]); acc[1][1] = MFMA(a1, b1, acc[1][1]);
;       } else {
;         acc[0][0] = MFMA(b0, a0, acc[0][0]); acc[0][1] = MFMA(b1, a0, acc[0][1]);
;         acc[1][0] = MFMA(b0, a1, acc[1][0]); acc[1][1] = MFMA(b1, a1, acc[1][1]);
;       }
;     }
; DI void phase4(PP p, int l, char* smem) {
;     ...
;     const int xcd = job & 7, q = job >> 3;
;     const int mt = (q >> 3) * 8 + xcd, nt = q & 7;
;     GJob J;
;     J.rs_k = 0; J.scale = 1.f; J.ld = 1024; J.headbase = 0; J.sshift = 13; J.dst = nullptr;
;     J.A = p->mixedg + (size_t)mt * 128 * 1024; J.lda = 1024; J.K = 1024; J.m0 = mt * 128;
;     J.Bt = p->WoutT + ((size_t)l * 1024 + nt * 128) * 1024; J.ldb = 1024;
.LBB0_645:
	s_ashr_i32 s10, s25, 3
	s_and_b32 s2, s25, 7
	s_and_b32 s10, s10, -8
	s_or_b32 s10, s10, s2
	s_ashr_i32 s11, s10, 31
	s_lshl_b64 s[12:13], s[10:11], 18
	s_waitcnt lgkmcnt(0)
	s_add_u32 s12, s6, s12
	s_addc_u32 s13, s7, s13
	s_lshl_b32 s2, s25, 4
	v_mov_b32_e32 v84, v188
	v_mov_b32_e32 v34, v188
	s_and_b32 s39, s2, 0x380
	s_lshl_b32 s2, s39, 11
	s_waitcnt vmcnt(7)
	v_ashrrev_i32_e32 v2, 3, v34
	v_lshlrev_b32_e32 v0, 3, v34
	v_ashrrev_i32_e32 v3, 31, v2
	s_or_b32 s2, s2, s24
	v_and_b32_e32 v35, 56, v0
	v_lshlrev_b64 v[4:5], 11, v[2:3]
	s_add_u32 s18, s8, s2
	s_waitcnt vmcnt(6)
	v_lshl_add_u64 v[6:7], s[12:13], 0, v[4:5]
	v_lshlrev_b32_e32 v0, 1, v35
	s_addc_u32 s19, s9, 0
	v_lshl_add_u64 v[68:69], v[6:7], 0, v[0:1]
	v_lshl_add_u64 v[4:5], s[18:19], 0, v[4:5]
	v_add_co_u32_e32 v72, vcc, s50, v68
	v_lshl_add_u64 v[70:71], v[4:5], 0, v[0:1]
	s_nop 0
	v_addc_co_u32_e32 v73, vcc, 0, v69, vcc
	v_add_co_u32_e32 v74, vcc, s50, v70
	v_mul_lo_u32 v0, v2, s33
	s_nop 0
	v_addc_co_u32_e32 v75, vcc, 0, v71, vcc
	v_add_co_u32_e32 v76, vcc, s51, v68
	global_load_dwordx4 v[2:5], v[68:69], off
	s_nop 0
	v_addc_co_u32_e32 v77, vcc, 0, v69, vcc
	v_add_co_u32_e32 v78, vcc, s51, v70
	global_load_dwordx4 v[6:9], v[70:71], off
	s_nop 0
	v_addc_co_u32_e32 v79, vcc, 0, v71, vcc
	v_add_co_u32_e32 v80, vcc, s52, v68
	global_load_dwordx4 v[10:13], v[72:73], off
	s_nop 0
	v_addc_co_u32_e32 v81, vcc, 0, v69, vcc
	v_add_co_u32_e32 v82, vcc, s52, v70
	global_load_dwordx4 v[14:17], v[74:75], off
	s_nop 0
	v_addc_co_u32_e32 v83, vcc, 0, v71, vcc
	global_load_dwordx4 v[18:21], v[76:77], off
	global_load_dwordx4 v[22:25], v[78:79], off
	global_load_dwordx4 v[26:29], v[80:81], off
	global_load_dwordx4 v[30:33], v[82:83], off
	global_load_dwordx4 v[152:155], v[68:69], off offset:128
	global_load_dwordx4 v[156:159], v[70:71], off offset:128
	global_load_dwordx4 v[160:163], v[72:73], off offset:128
	global_load_dwordx4 v[164:167], v[74:75], off offset:128
	global_load_dwordx4 v[168:171], v[76:77], off offset:128
	global_load_dwordx4 v[172:175], v[78:79], off offset:128
	global_load_dwordx4 v[176:179], v[80:81], off offset:128
	global_load_dwordx4 v[180:183], v[82:83], off offset:128
	v_add_lshl_u32 v85, v0, v35, 1
	v_and_b32_e32 v0, 31, v34
	s_mov_b32 s38, 0
	v_add_u32_e32 v86, 0x9000, v85
	s_waitcnt vmcnt(15)
	ds_write_b128 v85, v[2:5]
	v_lshrrev_b32_e32 v2, 1, v34
	v_and_or_b32 v3, v2, s53, v0
	v_and_b32_e32 v0, 16, v2
	v_and_b32_e32 v2, 0x5f, v34
	s_waitcnt vmcnt(14)
	ds_write_b128 v85, v[6:9] offset:36864
	v_mad_u64_u32 v[66:67], s[12:13], v3, s54, v[0:1]
	v_mad_u32_u24 v0, v2, s54, v0
	s_waitcnt vmcnt(13)
	ds_write_b128 v85, v[10:13] offset:4608
	s_waitcnt vmcnt(12)
	ds_write_b128 v85, v[14:17] offset:41472
	s_waitcnt vmcnt(11)
	ds_write_b128 v85, v[18:21] offset:9216
	s_waitcnt vmcnt(10)
	ds_write_b128 v85, v[22:25] offset:46080
	s_waitcnt vmcnt(9)
	ds_write_b128 v85, v[26:29] offset:13824
	s_waitcnt vmcnt(8)
	ds_write_b128 v85, v[30:33] offset:50688
	s_waitcnt lgkmcnt(0)
	s_barrier
	ds_read_b128 v[120:123], v66
	ds_read_b128 v[128:131], v0 offset:36864
	ds_read_b128 v[132:135], v0 offset:41472
	ds_read_b128 v[124:127], v66 offset:4608
	ds_read_b128 v[136:139], v66 offset:32
	ds_read_b128 v[184:187], v0 offset:36896
	ds_read_b128 v[200:203], v0 offset:41504
	ds_read_b128 v[140:143], v66 offset:4640
	s_setprio 1
	s_waitcnt lgkmcnt(4)
	v_mfma_f32_32x32x16_bf16 v[50:65], v[128:131], v[120:123], 0
	global_load_dwordx4 v[88:91], v[68:69], off offset:256
	v_mfma_f32_32x32x16_bf16 v[34:49], v[132:135], v[120:123], 0
	s_waitcnt vmcnt(8)
	ds_write_b128 v85, v[152:155] offset:18432
	v_mfma_f32_32x32x16_bf16 v[18:33], v[132:135], v[124:127], 0
	global_load_dwordx4 v[92:95], v[70:71], off offset:256
	v_mfma_f32_32x32x16_bf16 v[2:17], v[128:131], v[124:127], 0
	s_waitcnt vmcnt(8)
	ds_write_b128 v85, v[156:159] offset:55296
	ds_read_b128 v[120:123], v66 offset:64
	ds_read_b128 v[128:131], v0 offset:36928
	ds_read_b128 v[132:135], v0 offset:41536
	ds_read_b128 v[124:127], v66 offset:4672
	s_waitcnt lgkmcnt(6)
	v_mfma_f32_32x32x16_bf16 v[50:65], v[184:187], v[136:139], v[50:65]
	global_load_dwordx4 v[96:99], v[72:73], off offset:256
	v_mfma_f32_32x32x16_bf16 v[34:49], v[200:203], v[136:139], v[34:49]
	s_waitcnt vmcnt(8)
	ds_write_b128 v85, v[160:163] offset:23040
	v_mfma_f32_32x32x16_bf16 v[18:33], v[200:203], v[140:143], v[18:33]
	global_load_dwordx4 v[100:103], v[74:75], off offset:256
	v_mfma_f32_32x32x16_bf16 v[2:17], v[184:187], v[140:143], v[2:17]
	s_waitcnt vmcnt(8)
	ds_write_b128 v85, v[164:167] offset:59904
	ds_read_b128 v[136:139], v66 offset:96
	ds_read_b128 v[184:187], v0 offset:36960
	ds_read_b128 v[200:203], v0 offset:41568
	ds_read_b128 v[140:143], v66 offset:4704
	s_waitcnt lgkmcnt(6)
	v_mfma_f32_32x32x16_bf16 v[50:65], v[128:131], v[120:123], v[50:65]
	global_load_dwordx4 v[104:107], v[76:77], off offset:256
	v_mfma_f32_32x32x16_bf16 v[34:49], v[132:135], v[120:123], v[34:49]
	s_waitcnt vmcnt(8)
	ds_write_b128 v85, v[168:171] offset:27648
	v_mfma_f32_32x32x16_bf16 v[18:33], v[132:135], v[124:127], v[18:33]
	global_load_dwordx4 v[108:111], v[78:79], off offset:256
	v_mfma_f32_32x32x16_bf16 v[2:17], v[128:131], v[124:127], v[2:17]
	s_waitcnt vmcnt(8)
	ds_write_b128 v85, v[172:175] offset:64512
	s_waitcnt lgkmcnt(2)
	v_mfma_f32_32x32x16_bf16 v[50:65], v[184:187], v[136:139], v[50:65]
	global_load_dwordx4 v[112:115], v[80:81], off offset:256
	v_mfma_f32_32x32x16_bf16 v[34:49], v[200:203], v[136:139], v[34:49]
	s_waitcnt vmcnt(8)
	ds_write_b128 v85, v[176:179] offset:32256
	v_mfma_f32_32x32x16_bf16 v[18:33], v[200:203], v[140:143], v[18:33]
	global_load_dwordx4 v[116:119], v[82:83], off offset:256
	v_mfma_f32_32x32x16_bf16 v[2:17], v[184:187], v[140:143], v[2:17]
	s_waitcnt vmcnt(8)
	ds_write_b128 v86, v[180:183] offset:32256
	s_setprio 0
	s_waitcnt lgkmcnt(0)
	s_barrier
; #define MFMA(a, b, c) __builtin_amdgcn_mfma_f32_32x32x16_bf16((a), (b), (c), 0, 0, 0)
; template <bool SWAP>
; DI void gemm_block(const bf16_t* __restrict__ A, int lda, const bf16_t* __restrict__ Bt, int ldb, int K, f32x16 (&acc)[2][2], bf16_t* sA, bf16_t* sB) {
;     ...
;   for (int kt = 0; kt < nk; ++kt) {
;     const int cur = kt & 1;
;     const bool more = kt + 1 < nk;
;     if (more) {
;       const int k0 = (kt + 1) * 64;
; #pragma unroll
;       for (int i = 0; i < 4; ++i) { ra[i] = *(const u32x4*)(ga + (size_t)i * 32 * lda + k0); rb[i] = *(const u32x4*)(gb + (size_t)i * 32 * ldb + k0); }
;     }
;     const bf16_t* ab = sA + cur * 128 * LDT + (64 * wr + l32) * LDT + h * 8;
;     const bf16_t* bb = sB + cur * 128 * LDT + (64 * wc + l32) * LDT + h * 8;
;     __builtin_amdgcn_s_setprio(1);
;     __builtin_amdgcn_iglp_opt(0);
; #pragma unroll
;     for (int ks = 0; ks < 4; ++ks) {
;       const bf16x8 a0 = *(const bf16x8*)(ab + ks * 16), a1 = *(const bf16x8*)(ab + 32 * LDT + ks * 16);
;       const bf16x8 b0 = *(const bf16x8*)(bb + ks * 16), b1 = *(const bf16x8*)(bb + 32 * LDT + ks * 16);
;       if (!SWAP) {
;         acc[0][0] = MFMA(a0, b0, acc[0][0]); acc[0][1] = MFMA(a0, b1, acc[0][1]);
;         acc[1][0] = MFMA(a1, b0, acc[1][0]); acc[1][1] = MFMA(a1, b1, acc[1][1]);
;       } else {
;         acc[0][0] = MFMA(b0, a0, acc[0][0]); acc[0][1] = MFMA(b1, a0, acc[0][1]);
;         acc[1][0] = MFMA(b0, a1, acc[1][0]); acc[1][1] = MFMA(b1, a1, acc[1][1]);
;       }
;     }
;     __builtin_amdgcn_s_setprio(0);
;     if (more) {
;       const int nb = (cur ^ 1) * 128 * LDT;
; #pragma unroll
;       for (int i = 0; i < 4; ++i) { *(u32x4*)(sA + nb + soff + i * 32 * LDT) = ra[i]; *(u32x4*)(sB + nb + soff + i * 32 * LDT) = rb[i]; }
;     }
;     __syncthreads();
;   }
	ds_read_b128 v[120:123], v66 offset:18432
	ds_read_b128 v[128:131], v0 offset:55296
	ds_read_b128 v[132:135], v0 offset:59904
	ds_read_b128 v[124:127], v66 offset:23040
	ds_read_b128 v[136:139], v66 offset:18464
	ds_read_b128 v[184:187], v0 offset:55328
	ds_read_b128 v[200:203], v0 offset:59936
	ds_read_b128 v[140:143], v66 offset:23072
	s_setprio 1
	s_waitcnt lgkmcnt(4)
	v_mfma_f32_32x32x16_bf16 v[50:65], v[128:131], v[120:123], v[50:65]
	global_load_dwordx4 v[152:155], v[68:69], off offset:384
	v_mfma_f32_32x32x16_bf16 v[34:49], v[132:135], v[120:123], v[34:49]
	s_waitcnt vmcnt(8)
	ds_write_b128 v85, v[88:91]
	v_mfma_f32_32x32x16_bf16 v[18:33], v[132:135], v[124:127], v[18:33]
	global_load_dwordx4 v[156:159], v[70:71], off offset:384
	v_mfma_f32_32x32x16_bf16 v[2:17], v[128:131], v[124:127], v[2:17]
	s_waitcnt vmcnt(8)
	ds_write_b128 v85, v[92:95] offset:36864
	ds_read_b128 v[120:123], v66 offset:18496
	ds_read_b128 v[128:131], v0 offset:55360
	ds_read_b128 v[132:135], v0 offset:59968
	ds_read_b128 v[124:127], v66 offset:23104
	s_waitcnt lgkmcnt(6)
	v_mfma_f32_32x32x16_bf16 v[50:65], v[184:187], v[136:139], v[50:65]
	global_load_dwordx4 v[160:163], v[72:73], off offset:384
	v_mfma_f32_32x32x16_bf16 v[34:49], v[200:203], v[136:139], v[34:49]
	s_waitcnt vmcnt(8)
	ds_write_b128 v85, v[96:99] offset:4608
	v_mfma_f32_32x32x16_bf16 v[18:33], v[200:203], v[140:143], v[18:33]
	global_load_dwordx4 v[164:167], v[74:75], off offset:384
	v_mfma_f32_32x32x16_bf16 v[2:17], v[184:187], v[140:143], v[2:17]
	s_waitcnt vmcnt(8)
	ds_write_b128 v85, v[100:103] offset:41472
	ds_read_b128 v[136:139], v66 offset:18528
	ds_read_b128 v[184:187], v0 offset:55392
	ds_read_b128 v[200:203], v0 offset:60000
	ds_read_b128 v[140:143], v66 offset:23136
	s_waitcnt lgkmcnt(6)
	v_mfma_f32_32x32x16_bf16 v[50:65], v[128:131], v[120:123], v[50:65]
	global_load_dwordx4 v[168:171], v[76:77], off offset:384
	v_mfma_f32_32x32x16_bf16 v[34:49], v[132:135], v[120:123], v[34:49]
	s_waitcnt vmcnt(8)
	ds_write_b128 v85, v[104:107] offset:9216
	v_mfma_f32_32x32x16_bf16 v[18:33], v[132:135], v[124:127], v[18:33]
	global_load_dwordx4 v[172:175], v[78:79], off offset:384
	v_mfma_f32_32x32x16_bf16 v[2:17], v[128:131], v[124:127], v[2:17]
	s_waitcnt vmcnt(8)
	ds_write_b128 v85, v[108:111] offset:46080
	s_waitcnt lgkmcnt(2)
	v_mfma_f32_32x32x16_bf16 v[50:65], v[184:187], v[136:139], v[50:65]
	global_load_dwordx4 v[176:179], v[80:81], off offset:384
	v_mfma_f32_32x32x16_bf16 v[34:49], v[200:203], v[136:139], v[34:49]
	s_waitcnt vmcnt(8)
	ds_write_b128 v85, v[112:115] offset:13824
	v_mfma_f32_32x32x16_bf16 v[18:33], v[200:203], v[140:143], v[18:33]
	global_load_dwordx4 v[180:183], v[82:83], off offset:384
	v_mfma_f32_32x32x16_bf16 v[2:17], v[184:187], v[140:143], v[2:17]
	s_waitcnt vmcnt(8)
	ds_write_b128 v85, v[116:119] offset:50688
	s_setprio 0
	s_waitcnt lgkmcnt(0)
	s_barrier
	ds_read_b128 v[120:123], v66
	ds_read_b128 v[128:131], v0 offset:36864
	ds_read_b128 v[132:135], v0 offset:41472
	ds_read_b128 v[124:127], v66 offset:4608
	ds_read_b128 v[136:139], v66 offset:32
	ds_read_b128 v[184:187], v0 offset:36896
	ds_read_b128 v[200:203], v0 offset:41504
	ds_read_b128 v[140:143], v66 offset:4640
	s_setprio 1
	s_waitcnt lgkmcnt(4)
	v_mfma_f32_32x32x16_bf16 v[50:65], v[128:131], v[120:123], v[50:65]
	global_load_dwordx4 v[88:91], v[68:69], off offset:512
	v_mfma_f32_32x32x16_bf16 v[34:49], v[132:135], v[120:123], v[34:49]
	s_waitcnt vmcnt(8)
	ds_write_b128 v85, v[152:155] offset:18432
	v_mfma_f32_32x32x16_bf16 v[18:33], v[132:135], v[124:127], v[18:33]
	global_load_dwordx4 v[92:95], v[70:71], off offset:512
	v_mfma_f32_32x32x16_bf16 v[2:17], v[128:131], v[124:127], v[2:17]
	s_waitcnt vmcnt(8)
	ds_write_b128 v85, v[156:159] offset:55296
	ds_read_b128 v[120:123], v66 offset:64
	ds_read_b128 v[128:131], v0 offset:36928
	ds_read_b128 v[132:135], v0 offset:41536
	ds_read_b128 v[124:127], v66 offset:4672
	s_waitcnt lgkmcnt(6)
	v_mfma_f32_32x32x16_bf16 v[50:65], v[184:187], v[136:139], v[50:65]
	global_load_dwordx4 v[96:99], v[72:73], off offset:512
	v_mfma_f32_32x32x16_bf16 v[34:49], v[200:203], v[136:139], v[34:49]
	s_waitcnt vmcnt(8)
	ds_write_b128 v85, v[160:163] offset:23040
	v_mfma_f32_32x32x16_bf16 v[18:33], v[200:203], v[140:143], v[18:33]
	global_load_dwordx4 v[100:103], v[74:75], off offset:512
	v_mfma_f32_32x32x16_bf16 v[2:17], v[184:187], v[140:143], v[2:17]
	s_waitcnt vmcnt(8)
	ds_write_b128 v85, v[164:167] offset:59904
	ds_read_b128 v[136:139], v66 offset:96
	ds_read_b128 v[184:187], v0 offset:36960
	ds_read_b128 v[200:203], v0 offset:41568
	ds_read_b128 v[140:143], v66 offset:4704
	s_waitcnt lgkmcnt(6)
	v_mfma_f32_32x32x16_bf16 v[50:65], v[128:131], v[120:123], v[50:65]
	global_load_dwordx4 v[104:107], v[76:77], off offset:512
	v_mfma_f32_32x32x16_bf16 v[34:49], v[132:135], v[120:123], v[34:49]
	s_waitcnt vmcnt(8)
	ds_write_b128 v85, v[168:171] offset:27648
	v_mfma_f32_32x32x16_bf16 v[18:33], v[132:135], v[124:127], v[18:33]
	global_load_dwordx4 v[108:111], v[78:79], off offset:512
	v_mfma_f32_32x32x16_bf16 v[2:17], v[128:131], v[124:127], v[2:17]
	s_waitcnt vmcnt(8)
	ds_write_b128 v85, v[172:175] offset:64512
	s_waitcnt lgkmcnt(2)
	v_mfma_f32_32x32x16_bf16 v[50:65], v[184:187], v[136:139], v[50:65]
	global_load_dwordx4 v[112:115], v[80:81], off offset:512
	v_mfma_f32_32x32x16_bf16 v[34:49], v[200:203], v[136:139], v[34:49]
	s_waitcnt vmcnt(8)
	ds_write_b128 v85, v[176:179] offset:32256
	v_mfma_f32_32x32x16_bf16 v[18:33], v[200:203], v[140:143], v[18:33]
	global_load_dwordx4 v[116:119], v[82:83], off offset:512
	v_mfma_f32_32x32x16_bf16 v[2:17], v[184:187], v[140:143], v[2:17]
	s_waitcnt vmcnt(8)
	ds_write_b128 v86, v[180:183] offset:32256
	s_setprio 0
	s_waitcnt lgkmcnt(0)
	s_barrier
; #define MFMA(a, b, c) __builtin_amdgcn_mfma_f32_32x32x16_bf16((a), (b), (c), 0, 0, 0)
; template <bool SWAP>
; DI void gemm_block(const bf16_t* __restrict__ A, int lda, const bf16_t* __restrict__ Bt, int ldb, int K, f32x16 (&acc)[2][2], bf16_t* sA, bf16_t* sB) {
;     ...
;   for (int kt = 0; kt < nk; ++kt) {
;     const int cur = kt & 1;
;     const bool more = kt + 1 < nk;
;     if (more) {
;       const int k0 = (kt + 1) * 64;
; #pragma unroll
;       for (int i = 0; i < 4; ++i) { ra[i] = *(const u32x4*)(ga + (size_t)i * 32 * lda + k0); rb[i] = *(const u32x4*)(gb + (size_t)i * 32 * ldb + k0); }
;     }
;     const bf16_t* ab = sA + cur * 128 * LDT + (64 * wr + l32) * LDT + h * 8;
;     const bf16_t* bb = sB + cur * 128 * LDT + (64 * wc + l32) * LDT + h * 8;
;     __builtin_amdgcn_s_setprio(1);
;     __builtin_amdgcn_iglp_opt(0);
; #pragma unroll
;     for (int ks = 0; ks < 4; ++ks) {
;       const bf16x8 a0 = *(const bf16x8*)(ab + ks * 16), a1 = *(const bf16x8*)(ab + 32 * LDT + ks * 16);
;       const bf16x8 b0 = *(const bf16x8*)(bb + ks * 16), b1 = *(const bf16x8*)(bb + 32 * LDT + ks * 16);
;       if (!SWAP) {
;         acc[0][0] = MFMA(a0, b0, acc[0][0]); acc[0][1] = MFMA(a0, b1, acc[0][1]);
;         acc[1][0] = MFMA(a1, b0, acc[1][0]); acc[1][1] = MFMA(a1, b1, acc[1][1]);
;       } else {
;         acc[0][0] = MFMA(b0, a0, acc[0][0]); acc[0][1] = MFMA(b1, a0, acc[0][1]);
;         acc[1][0] = MFMA(b0, a1, acc[1][0]); acc[1][1] = MFMA(b1, a1, acc[1][1]);
;       }
;     }
;     __builtin_amdgcn_s_setprio(0);
;     if (more) {
;       const int nb = (cur ^ 1) * 128 * LDT;
; #pragma unroll
;       for (int i = 0; i < 4; ++i) { *(u32x4*)(sA + nb + soff + i * 32 * LDT) = ra[i]; *(u32x4*)(sB + nb + soff + i * 32 * LDT) = rb[i]; }
;     }
;     __syncthreads();
;   }
	ds_read_b128 v[120:123], v66 offset:18432
	ds_read_b128 v[128:131], v0 offset:55296
	ds_read_b128 v[132:135], v0 offset:59904
	ds_read_b128 v[124:127], v66 offset:23040
	ds_read_b128 v[136:139], v66 offset:18464
	ds_read_b128 v[184:187], v0 offset:55328
	ds_read_b128 v[200:203], v0 offset:59936
	ds_read_b128 v[140:143], v66 offset:23072
	s_setprio 1
	s_waitcnt lgkmcnt(4)
	v_mfma_f32_32x32x16_bf16 v[50:65], v[128:131], v[120:123], v[50:65]
	global_load_dwordx4 v[152:155], v[68:69], off offset:640
	v_mfma_f32_32x32x16_bf16 v[34:49], v[132:135], v[120:123], v[34:49]
	s_waitcnt vmcnt(8)
	ds_write_b128 v85, v[88:91]
	v_mfma_f32_32x32x16_bf16 v[18:33], v[132:135], v[124:127], v[18:33]
	global_load_dwordx4 v[156:159], v[70:71], off offset:640
	v_mfma_f32_32x32x16_bf16 v[2:17], v[128:131], v[124:127], v[2:17]
	s_waitcnt vmcnt(8)
	ds_write_b128 v85, v[92:95] offset:36864
	ds_read_b128 v[120:123], v66 offset:18496
	ds_read_b128 v[128:131], v0 offset:55360
	ds_read_b128 v[132:135], v0 offset:59968
	ds_read_b128 v[124:127], v66 offset:23104
	s_waitcnt lgkmcnt(6)
	v_mfma_f32_32x32x16_bf16 v[50:65], v[184:187], v[136:139], v[50:65]
	global_load_dwordx4 v[160:163], v[72:73], off offset:640
	v_mfma_f32_32x32x16_bf16 v[34:49], v[200:203], v[136:139], v[34:49]
	s_waitcnt vmcnt(8)
	ds_write_b128 v85, v[96:99] offset:4608
	v_mfma_f32_32x32x16_bf16 v[18:33], v[200:203], v[140:143], v[18:33]
	global_load_dwordx4 v[164:167], v[74:75], off offset:640
	v_mfma_f32_32x32x16_bf16 v[2:17], v[184:187], v[140:143], v[2:17]
	s_waitcnt vmcnt(8)
	ds_write_b128 v85, v[100:103] offset:41472
	ds_read_b128 v[136:139], v66 offset:18528
	ds_read_b128 v[184:187], v0 offset:55392
	ds_read_b128 v[200:203], v0 offset:60000
	ds_read_b128 v[140:143], v66 offset:23136
	s_waitcnt lgkmcnt(6)
	v_mfma_f32_32x32x16_bf16 v[50:65], v[128:131], v[120:123], v[50:65]
	global_load_dwordx4 v[168:171], v[76:77], off offset:640
	v_mfma_f32_32x32x16_bf16 v[34:49], v[132:135], v[120:123], v[34:49]
	s_waitcnt vmcnt(8)
	ds_write_b128 v85, v[104:107] offset:9216
	v_mfma_f32_32x32x16_bf16 v[18:33], v[132:135], v[124:127], v[18:33]
	global_load_dwordx4 v[172:175], v[78:79], off offset:640
	v_mfma_f32_32x32x16_bf16 v[2:17], v[128:131], v[124:127], v[2:17]
	s_waitcnt vmcnt(8)
	ds_write_b128 v85, v[108:111] offset:46080
	s_waitcnt lgkmcnt(2)
	v_mfma_f32_32x32x16_bf16 v[50:65], v[184:187], v[136:139], v[50:65]
	global_load_dwordx4 v[176:179], v[80:81], off offset:640
	v_mfma_f32_32x32x16_bf16 v[34:49], v[200:203], v[136:139], v[34:49]
	s_waitcnt vmcnt(8)
	ds_write_b128 v85, v[112:115] offset:13824
	v_mfma_f32_32x32x16_bf16 v[18:33], v[200:203], v[140:143], v[18:33]
	global_load_dwordx4 v[180:183], v[82:83], off offset:640
	v_mfma_f32_32x32x16_bf16 v[2:17], v[184:187], v[140:143], v[2:17]
	s_waitcnt vmcnt(8)
	ds_write_b128 v85, v[116:119] offset:50688
	s_setprio 0
	s_waitcnt lgkmcnt(0)
	s_barrier
	ds_read_b128 v[120:123], v66
	ds_read_b128 v[128:131], v0 offset:36864
	ds_read_b128 v[132:135], v0 offset:41472
	ds_read_b128 v[124:127], v66 offset:4608
	ds_read_b128 v[136:139], v66 offset:32
	ds_read_b128 v[184:187], v0 offset:36896
	ds_read_b128 v[200:203], v0 offset:41504
	ds_read_b128 v[140:143], v66 offset:4640
	s_setprio 1
	s_waitcnt lgkmcnt(4)
	v_mfma_f32_32x32x16_bf16 v[50:65], v[128:131], v[120:123], v[50:65]
	global_load_dwordx4 v[88:91], v[68:69], off offset:768
	v_mfma_f32_32x32x16_bf16 v[34:49], v[132:135], v[120:123], v[34:49]
	s_waitcnt vmcnt(8)
	ds_write_b128 v85, v[152:155] offset:18432
	v_mfma_f32_32x32x16_bf16 v[18:33], v[132:135], v[124:127], v[18:33]
	global_load_dwordx4 v[92:95], v[70:71], off offset:768
	v_mfma_f32_32x32x16_bf16 v[2:17], v[128:131], v[124:127], v[2:17]
	s_waitcnt vmcnt(8)
	ds_write_b128 v85, v[156:159] offset:55296
	ds_read_b128 v[120:123], v66 offset:64
	ds_read_b128 v[128:131], v0 offset:36928
	ds_read_b128 v[132:135], v0 offset:41536
	ds_read_b128 v[124:127], v66 offset:4672
	s_waitcnt lgkmcnt(6)
	v_mfma_f32_32x32x16_bf16 v[50:65], v[184:187], v[136:139], v[50:65]
	global_load_dwordx4 v[96:99], v[72:73], off offset:768
	v_mfma_f32_32x32x16_bf16 v[34:49], v[200:203], v[136:139], v[34:49]
	s_waitcnt vmcnt(8)
	ds_write_b128 v85, v[160:163] offset:23040
	v_mfma_f32_32x32x16_bf16 v[18:33], v[200:203], v[140:143], v[18:33]
	global_load_dwordx4 v[100:103], v[74:75], off offset:768
	v_mfma_f32_32x32x16_bf16 v[2:17], v[184:187], v[140:143], v[2:17]
	s_waitcnt vmcnt(8)
	ds_write_b128 v85, v[164:167] offset:59904
	ds_read_b128 v[136:139], v66 offset:96
	ds_read_b128 v[184:187], v0 offset:36960
	ds_read_b128 v[200:203], v0 offset:41568
	ds_read_b128 v[140:143], v66 offset:4704
	s_waitcnt lgkmcnt(6)
	v_mfma_f32_32x32x16_bf16 v[50:65], v[128:131], v[120:123], v[50:65]
	global_load_dwordx4 v[104:107], v[76:77], off offset:768
	v_mfma_f32_32x32x16_bf16 v[34:49], v[132:135], v[120:123], v[34:49]
	s_waitcnt vmcnt(8)
	ds_write_b128 v85, v[168:171] offset:27648
	v_mfma_f32_32x32x16_bf16 v[18:33], v[132:135], v[124:127], v[18:33]
	global_load_dwordx4 v[108:111], v[78:79], off offset:768
	v_mfma_f32_32x32x16_bf16 v[2:17], v[128:131], v[124:127], v[2:17]
	s_waitcnt vmcnt(8)
	ds_write_b128 v85, v[172:175] offset:64512
	s_waitcnt lgkmcnt(2)
	v_mfma_f32_32x32x16_bf16 v[50:65], v[184:187], v[136:139], v[50:65]
	global_load_dwordx4 v[112:115], v[80:81], off offset:768
	v_mfma_f32_32x32x16_bf16 v[34:49], v[200:203], v[136:139], v[34:49]
	s_waitcnt vmcnt(8)
	ds_write_b128 v85, v[176:179] offset:32256
	v_mfma_f32_32x32x16_bf16 v[18:33], v[200:203], v[140:143], v[18:33]
	global_load_dwordx4 v[116:119], v[82:83], off offset:768
	v_mfma_f32_32x32x16_bf16 v[2:17], v[184:187], v[140:143], v[2:17]
	s_waitcnt vmcnt(8)
	ds_write_b128 v86, v[180:183] offset:32256
	s_setprio 0
	s_waitcnt lgkmcnt(0)
	s_barrier
; #define MFMA(a, b, c) __builtin_amdgcn_mfma_f32_32x32x16_bf16((a), (b), (c), 0, 0, 0)
; template <bool SWAP>
; DI void gemm_block(const bf16_t* __restrict__ A, int lda, const bf16_t* __restrict__ Bt, int ldb, int K, f32x16 (&acc)[2][2], bf16_t* sA, bf16_t* sB) {
;     ...
;   for (int kt = 0; kt < nk; ++kt) {
;     const int cur = kt & 1;
;     const bool more = kt + 1 < nk;
;     if (more) {
;       const int k0 = (kt + 1) * 64;
; #pragma unroll
;       for (int i = 0; i < 4; ++i) { ra[i] = *(const u32x4*)(ga + (size_t)i * 32 * lda + k0); rb[i] = *(const u32x4*)(gb + (size_t)i * 32 * ldb + k0); }
;     }
;     const bf16_t* ab = sA + cur * 128 * LDT + (64 * wr + l32) * LDT + h * 8;
;     const bf16_t* bb = sB + cur * 128 * LDT + (64 * wc + l32) * LDT + h * 8;
;     __builtin_amdgcn_s_setprio(1);
;     __builtin_amdgcn_iglp_opt(0);
; #pragma unroll
;     for (int ks = 0; ks < 4; ++ks) {
;       const bf16x8 a0 = *(const bf16x8*)(ab + ks * 16), a1 = *(const bf16x8*)(ab + 32 * LDT + ks * 16);
;       const bf16x8 b0 = *(const bf16x8*)(bb + ks * 16), b1 = *(const bf16x8*)(bb + 32 * LDT + ks * 16);
;       if (!SWAP) {
;         acc[0][0] = MFMA(a0, b0, acc[0][0]); acc[0][1] = MFMA(a0, b1, acc[0][1]);
;         acc[1][0] = MFMA(a1, b0, acc[1][0]); acc[1][1] = MFMA(a1, b1, acc[1][1]);
;       } else {
;         acc[0][0] = MFMA(b0, a0, acc[0][0]); acc[0][1] = MFMA(b1, a0, acc[0][1]);
;         acc[1][0] = MFMA(b0, a1, acc[1][0]); acc[1][1] = MFMA(b1, a1, acc[1][1]);
;       }
;     }
;     __builtin_amdgcn_s_setprio(0);
;     if (more) {
;       const int nb = (cur ^ 1) * 128 * LDT;
; #pragma unroll
;       for (int i = 0; i < 4; ++i) { *(u32x4*)(sA + nb + soff + i * 32 * LDT) = ra[i]; *(u32x4*)(sB + nb + soff + i * 32 * LDT) = rb[i]; }
;     }
;     __syncthreads();
;   }
	ds_read_b128 v[120:123], v66 offset:18432
	ds_read_b128 v[128:131], v0 offset:55296
	ds_read_b128 v[132:135], v0 offset:59904
	ds_read_b128 v[124:127], v66 offset:23040
	ds_read_b128 v[136:139], v66 offset:18464
	ds_read_b128 v[184:187], v0 offset:55328
	ds_read_b128 v[200:203], v0 offset:59936
	ds_read_b128 v[140:143], v66 offset:23072
	s_setprio 1
	s_waitcnt lgkmcnt(4)
	v_mfma_f32_32x32x16_bf16 v[50:65], v[128:131], v[120:123], v[50:65]
	global_load_dwordx4 v[152:155], v[68:69], off offset:896
	v_mfma_f32_32x32x16_bf16 v[34:49], v[132:135], v[120:123], v[34:49]
	s_waitcnt vmcnt(8)
	ds_write_b128 v85, v[88:91]
	v_mfma_f32_32x32x16_bf16 v[18:33], v[132:135], v[124:127], v[18:33]
	global_load_dwordx4 v[156:159], v[70:71], off offset:896
	v_mfma_f32_32x32x16_bf16 v[2:17], v[128:131], v[124:127], v[2:17]
	s_waitcnt vmcnt(8)
	ds_write_b128 v85, v[92:95] offset:36864
	ds_read_b128 v[120:123], v66 offset:18496
	ds_read_b128 v[128:131], v0 offset:55360
	ds_read_b128 v[132:135], v0 offset:59968
	ds_read_b128 v[124:127], v66 offset:23104
	s_waitcnt lgkmcnt(6)
	v_mfma_f32_32x32x16_bf16 v[50:65], v[184:187], v[136:139], v[50:65]
	global_load_dwordx4 v[160:163], v[72:73], off offset:896
	v_mfma_f32_32x32x16_bf16 v[34:49], v[200:203], v[136:139], v[34:49]
	s_waitcnt vmcnt(8)
	ds_write_b128 v85, v[96:99] offset:4608
	v_mfma_f32_32x32x16_bf16 v[18:33], v[200:203], v[140:143], v[18:33]
	global_load_dwordx4 v[164:167], v[74:75], off offset:896
	v_mfma_f32_32x32x16_bf16 v[2:17], v[184:187], v[140:143], v[2:17]
	s_waitcnt vmcnt(8)
	ds_write_b128 v85, v[100:103] offset:41472
	ds_read_b128 v[136:139], v66 offset:18528
	ds_read_b128 v[184:187], v0 offset:55392
	ds_read_b128 v[200:203], v0 offset:60000
	ds_read_b128 v[140:143], v66 offset:23136
	s_waitcnt lgkmcnt(6)
	v_mfma_f32_32x32x16_bf16 v[50:65], v[128:131], v[120:123], v[50:65]
	global_load_dwordx4 v[168:171], v[76:77], off offset:896
	v_mfma_f32_32x32x16_bf16 v[34:49], v[132:135], v[120:123], v[34:49]
	s_waitcnt vmcnt(8)
	ds_write_b128 v85, v[104:107] offset:9216
	v_mfma_f32_32x32x16_bf16 v[18:33], v[132:135], v[124:127], v[18:33]
	global_load_dwordx4 v[172:175], v[78:79], off offset:896
	v_mfma_f32_32x32x16_bf16 v[2:17], v[128:131], v[124:127], v[2:17]
	s_waitcnt vmcnt(8)
	ds_write_b128 v85, v[108:111] offset:46080
	s_waitcnt lgkmcnt(2)
	v_mfma_f32_32x32x16_bf16 v[50:65], v[184:187], v[136:139], v[50:65]
	global_load_dwordx4 v[176:179], v[80:81], off offset:896
	v_mfma_f32_32x32x16_bf16 v[34:49], v[200:203], v[136:139], v[34:49]
	s_waitcnt vmcnt(8)
	ds_write_b128 v85, v[112:115] offset:13824
	v_mfma_f32_32x32x16_bf16 v[18:33], v[200:203], v[140:143], v[18:33]
	global_load_dwordx4 v[180:183], v[82:83], off offset:896
	v_mfma_f32_32x32x16_bf16 v[2:17], v[184:187], v[140:143], v[2:17]
	s_waitcnt vmcnt(8)
	ds_write_b128 v85, v[116:119] offset:50688
	s_setprio 0
	s_waitcnt lgkmcnt(0)
	s_barrier
	ds_read_b128 v[120:123], v66
	ds_read_b128 v[128:131], v0 offset:36864
	ds_read_b128 v[132:135], v0 offset:41472
	ds_read_b128 v[124:127], v66 offset:4608
	ds_read_b128 v[136:139], v66 offset:32
	ds_read_b128 v[184:187], v0 offset:36896
	ds_read_b128 v[200:203], v0 offset:41504
	ds_read_b128 v[140:143], v66 offset:4640
	s_setprio 1
	s_waitcnt lgkmcnt(4)
	v_mfma_f32_32x32x16_bf16 v[50:65], v[128:131], v[120:123], v[50:65]
	global_load_dwordx4 v[88:91], v[68:69], off offset:1024
	v_mfma_f32_32x32x16_bf16 v[34:49], v[132:135], v[120:123], v[34:49]
	s_waitcnt vmcnt(8)
	ds_write_b128 v85, v[152:155] offset:18432
	v_mfma_f32_32x32x16_bf16 v[18:33], v[132:135], v[124:127], v[18:33]
	global_load_dwordx4 v[92:95], v[70:71], off offset:1024
	v_mfma_f32_32x32x16_bf16 v[2:17], v[128:131], v[124:127], v[2:17]
	s_waitcnt vmcnt(8)
	ds_write_b128 v85, v[156:159] offset:55296
	ds_read_b128 v[120:123], v66 offset:64
	ds_read_b128 v[128:131], v0 offset:36928
	ds_read_b128 v[132:135], v0 offset:41536
	ds_read_b128 v[124:127], v66 offset:4672
	s_waitcnt lgkmcnt(6)
	v_mfma_f32_32x32x16_bf16 v[50:65], v[184:187], v[136:139], v[50:65]
	global_load_dwordx4 v[96:99], v[72:73], off offset:1024
	v_mfma_f32_32x32x16_bf16 v[34:49], v[200:203], v[136:139], v[34:49]
	s_waitcnt vmcnt(8)
	ds_write_b128 v85, v[160:163] offset:23040
	v_mfma_f32_32x32x16_bf16 v[18:33], v[200:203], v[140:143], v[18:33]
	global_load_dwordx4 v[100:103], v[74:75], off offset:1024
	v_mfma_f32_32x32x16_bf16 v[2:17], v[184:187], v[140:143], v[2:17]
	s_waitcnt vmcnt(8)
	ds_write_b128 v85, v[164:167] offset:59904
	ds_read_b128 v[136:139], v66 offset:96
	ds_read_b128 v[184:187], v0 offset:36960
	ds_read_b128 v[200:203], v0 offset:41568
	ds_read_b128 v[140:143], v66 offset:4704
	s_waitcnt lgkmcnt(6)
	v_mfma_f32_32x32x16_bf16 v[50:65], v[128:131], v[120:123], v[50:65]
	global_load_dwordx4 v[104:107], v[76:77], off offset:1024
	v_mfma_f32_32x32x16_bf16 v[34:49], v[132:135], v[120:123], v[34:49]
	s_waitcnt vmcnt(8)
	ds_write_b128 v85, v[168:171] offset:27648
	v_mfma_f32_32x32x16_bf16 v[18:33], v[132:135], v[124:127], v[18:33]
	global_load_dwordx4 v[108:111], v[78:79], off offset:1024
	v_mfma_f32_32x32x16_bf16 v[2:17], v[128:131], v[124:127], v[2:17]
	s_waitcnt vmcnt(8)
	ds_write_b128 v85, v[172:175] offset:64512
	s_waitcnt lgkmcnt(2)
	v_mfma_f32_32x32x16_bf16 v[50:65], v[184:187], v[136:139], v[50:65]
	global_load_dwordx4 v[112:115], v[80:81], off offset:1024
	v_mfma_f32_32x32x16_bf16 v[34:49], v[200:203], v[136:139], v[34:49]
	s_waitcnt vmcnt(8)
	ds_write_b128 v85, v[176:179] offset:32256
	v_mfma_f32_32x32x16_bf16 v[18:33], v[200:203], v[140:143], v[18:33]
	global_load_dwordx4 v[116:119], v[82:83], off offset:1024
	v_mfma_f32_32x32x16_bf16 v[2:17], v[184:187], v[140:143], v[2:17]
	s_waitcnt vmcnt(8)
	ds_write_b128 v86, v[180:183] offset:32256
	s_setprio 0
	s_waitcnt lgkmcnt(0)
	s_barrier
; #define MFMA(a, b, c) __builtin_amdgcn_mfma_f32_32x32x16_bf16((a), (b), (c), 0, 0, 0)
; template <bool SWAP>
; DI void gemm_block(const bf16_t* __restrict__ A, int lda, const bf16_t* __restrict__ Bt, int ldb, int K, f32x16 (&acc)[2][2], bf16_t* sA, bf16_t* sB) {
;     ...
;   for (int kt = 0; kt < nk; ++kt) {
;     const int cur = kt & 1;
;     const bool more = kt + 1 < nk;
;     if (more) {
;       const int k0 = (kt + 1) * 64;
; #pragma unroll
;       for (int i = 0; i < 4; ++i) { ra[i] = *(const u32x4*)(ga + (size_t)i * 32 * lda + k0); rb[i] = *(const u32x4*)(gb + (size_t)i * 32 * ldb + k0); }
;     }
;     const bf16_t* ab = sA + cur * 128 * LDT + (64 * wr + l32) * LDT + h * 8;
;     const bf16_t* bb = sB + cur * 128 * LDT + (64 * wc + l32) * LDT + h * 8;
;     __builtin_amdgcn_s_setprio(1);
;     __builtin_amdgcn_iglp_opt(0);
; #pragma unroll
;     for (int ks = 0; ks < 4; ++ks) {
;       const bf16x8 a0 = *(const bf16x8*)(ab + ks * 16), a1 = *(const bf16x8*)(ab + 32 * LDT + ks * 16);
;       const bf16x8 b0 = *(const bf16x8*)(bb + ks * 16), b1 = *(const bf16x8*)(bb + 32 * LDT + ks * 16);
;       if (!SWAP) {
;         acc[0][0] = MFMA(a0, b0, acc[0][0]); acc[0][1] = MFMA(a0, b1, acc[0][1]);
;         acc[1][0] = MFMA(a1, b0, acc[1][0]); acc[1][1] = MFMA(a1, b1, acc[1][1]);
;       } else {
;         acc[0][0] = MFMA(b0, a0, acc[0][0]); acc[0][1] = MFMA(b1, a0, acc[0][1]);
;         acc[1][0] = MFMA(b0, a1, acc[1][0]); acc[1][1] = MFMA(b1, a1, acc[1][1]);
;       }
;     }
;     __builtin_amdgcn_s_setprio(0);
;     if (more) {
;       const int nb = (cur ^ 1) * 128 * LDT;
; #pragma unroll
;       for (int i = 0; i < 4; ++i) { *(u32x4*)(sA + nb + soff + i * 32 * LDT) = ra[i]; *(u32x4*)(sB + nb + soff + i * 32 * LDT) = rb[i]; }
;     }
;     __syncthreads();
;   }
	ds_read_b128 v[120:123], v66 offset:18432
	ds_read_b128 v[128:131], v0 offset:55296
	ds_read_b128 v[132:135], v0 offset:59904
	ds_read_b128 v[124:127], v66 offset:23040
	ds_read_b128 v[136:139], v66 offset:18464
	ds_read_b128 v[184:187], v0 offset:55328
	ds_read_b128 v[200:203], v0 offset:59936
	ds_read_b128 v[140:143], v66 offset:23072
	s_setprio 1
	s_waitcnt lgkmcnt(4)
	v_mfma_f32_32x32x16_bf16 v[50:65], v[128:131], v[120:123], v[50:65]
	global_load_dwordx4 v[152:155], v[68:69], off offset:1152
	v_mfma_f32_32x32x16_bf16 v[34:49], v[132:135], v[120:123], v[34:49]
	s_waitcnt vmcnt(8)
	ds_write_b128 v85, v[88:91]
	v_mfma_f32_32x32x16_bf16 v[18:33], v[132:135], v[124:127], v[18:33]
	global_load_dwordx4 v[156:159], v[70:71], off offset:1152
	v_mfma_f32_32x32x16_bf16 v[2:17], v[128:131], v[124:127], v[2:17]
	s_waitcnt vmcnt(8)
	ds_write_b128 v85, v[92:95] offset:36864
	ds_read_b128 v[120:123], v66 offset:18496
	ds_read_b128 v[128:131], v0 offset:55360
	ds_read_b128 v[132:135], v0 offset:59968
	ds_read_b128 v[124:127], v66 offset:23104
	s_waitcnt lgkmcnt(6)
	v_mfma_f32_32x32x16_bf16 v[50:65], v[184:187], v[136:139], v[50:65]
	global_load_dwordx4 v[160:163], v[72:73], off offset:1152
	v_mfma_f32_32x32x16_bf16 v[34:49], v[200:203], v[136:139], v[34:49]
	s_waitcnt vmcnt(8)
	ds_write_b128 v85, v[96:99] offset:4608
	v_mfma_f32_32x32x16_bf16 v[18:33], v[200:203], v[140:143], v[18:33]
	global_load_dwordx4 v[164:167], v[74:75], off offset:1152
	v_mfma_f32_32x32x16_bf16 v[2:17], v[184:187], v[140:143], v[2:17]
	s_waitcnt vmcnt(8)
	ds_write_b128 v85, v[100:103] offset:41472
	ds_read_b128 v[136:139], v66 offset:18528
	ds_read_b128 v[184:187], v0 offset:55392
	ds_read_b128 v[200:203], v0 offset:60000
	ds_read_b128 v[140:143], v66 offset:23136
	s_waitcnt lgkmcnt(6)
	v_mfma_f32_32x32x16_bf16 v[50:65], v[128:131], v[120:123], v[50:65]
	global_load_dwordx4 v[168:171], v[76:77], off offset:1152
	v_mfma_f32_32x32x16_bf16 v[34:49], v[132:135], v[120:123], v[34:49]
	s_waitcnt vmcnt(8)
	ds_write_b128 v85, v[104:107] offset:9216
	v_mfma_f32_32x32x16_bf16 v[18:33], v[132:135], v[124:127], v[18:33]
	global_load_dwordx4 v[172:175], v[78:79], off offset:1152
	v_mfma_f32_32x32x16_bf16 v[2:17], v[128:131], v[124:127], v[2:17]
	s_waitcnt vmcnt(8)
	ds_write_b128 v85, v[108:111] offset:46080
	s_waitcnt lgkmcnt(2)
	v_mfma_f32_32x32x16_bf16 v[50:65], v[184:187], v[136:139], v[50:65]
	global_load_dwordx4 v[176:179], v[80:81], off offset:1152
	v_mfma_f32_32x32x16_bf16 v[34:49], v[200:203], v[136:139], v[34:49]
	s_waitcnt vmcnt(8)
	ds_write_b128 v85, v[112:115] offset:13824
	v_mfma_f32_32x32x16_bf16 v[18:33], v[200:203], v[140:143], v[18:33]
	global_load_dwordx4 v[180:183], v[82:83], off offset:1152
	v_mfma_f32_32x32x16_bf16 v[2:17], v[184:187], v[140:143], v[2:17]
	s_waitcnt vmcnt(8)
	ds_write_b128 v85, v[116:119] offset:50688
	s_setprio 0
	s_waitcnt lgkmcnt(0)
	s_barrier
	ds_read_b128 v[120:123], v66
	ds_read_b128 v[128:131], v0 offset:36864
	ds_read_b128 v[132:135], v0 offset:41472
	ds_read_b128 v[124:127], v66 offset:4608
	ds_read_b128 v[136:139], v66 offset:32
	ds_read_b128 v[184:187], v0 offset:36896
	ds_read_b128 v[200:203], v0 offset:41504
	ds_read_b128 v[140:143], v66 offset:4640
	s_setprio 1
	s_waitcnt lgkmcnt(4)
	v_mfma_f32_32x32x16_bf16 v[50:65], v[128:131], v[120:123], v[50:65]
	global_load_dwordx4 v[88:91], v[68:69], off offset:1280
	v_mfma_f32_32x32x16_bf16 v[34:49], v[132:135], v[120:123], v[34:49]
	s_waitcnt vmcnt(8)
	ds_write_b128 v85, v[152:155] offset:18432
	v_mfma_f32_32x32x16_bf16 v[18:33], v[132:135], v[124:127], v[18:33]
	global_load_dwordx4 v[92:95], v[70:71], off offset:1280
	v_mfma_f32_32x32x16_bf16 v[2:17], v[128:131], v[124:127], v[2:17]
	s_waitcnt vmcnt(8)
	ds_write_b128 v85, v[156:159] offset:55296
	ds_read_b128 v[120:123], v66 offset:64
	ds_read_b128 v[128:131], v0 offset:36928
	ds_read_b128 v[132:135], v0 offset:41536
	ds_read_b128 v[124:127], v66 offset:4672
	s_waitcnt lgkmcnt(6)
	v_mfma_f32_32x32x16_bf16 v[50:65], v[184:187], v[136:139], v[50:65]
	global_load_dwordx4 v[96:99], v[72:73], off offset:1280
	v_mfma_f32_32x32x16_bf16 v[34:49], v[200:203], v[136:139], v[34:49]
	s_waitcnt vmcnt(8)
	ds_write_b128 v85, v[160:163] offset:23040
	v_mfma_f32_32x32x16_bf16 v[18:33], v[200:203], v[140:143], v[18:33]
	global_load_dwordx4 v[100:103], v[74:75], off offset:1280
	v_mfma_f32_32x32x16_bf16 v[2:17], v[184:187], v[140:143], v[2:17]
	s_waitcnt vmcnt(8)
	ds_write_b128 v85, v[164:167] offset:59904
	ds_read_b128 v[136:139], v66 offset:96
	ds_read_b128 v[184:187], v0 offset:36960
	ds_read_b128 v[200:203], v0 offset:41568
	ds_read_b128 v[140:143], v66 offset:4704
	s_waitcnt lgkmcnt(6)
	v_mfma_f32_32x32x16_bf16 v[50:65], v[128:131], v[120:123], v[50:65]
	global_load_dwordx4 v[104:107], v[76:77], off offset:1280
	v_mfma_f32_32x32x16_bf16 v[34:49], v[132:135], v[120:123], v[34:49]
	s_waitcnt vmcnt(8)
	ds_write_b128 v85, v[168:171] offset:27648
	v_mfma_f32_32x32x16_bf16 v[18:33], v[132:135], v[124:127], v[18:33]
	global_load_dwordx4 v[108:111], v[78:79], off offset:1280
	v_mfma_f32_32x32x16_bf16 v[2:17], v[128:131], v[124:127], v[2:17]
	s_waitcnt vmcnt(8)
	ds_write_b128 v85, v[172:175] offset:64512
	s_waitcnt lgkmcnt(2)
	v_mfma_f32_32x32x16_bf16 v[50:65], v[184:187], v[136:139], v[50:65]
	global_load_dwordx4 v[112:115], v[80:81], off offset:1280
	v_mfma_f32_32x32x16_bf16 v[34:49], v[200:203], v[136:139], v[34:49]
	s_waitcnt vmcnt(8)
	ds_write_b128 v85, v[176:179] offset:32256
	v_mfma_f32_32x32x16_bf16 v[18:33], v[200:203], v[140:143], v[18:33]
	global_load_dwordx4 v[116:119], v[82:83], off offset:1280
	v_mfma_f32_32x32x16_bf16 v[2:17], v[184:187], v[140:143], v[2:17]
	s_waitcnt vmcnt(8)
	ds_write_b128 v86, v[180:183] offset:32256
	s_setprio 0
	s_waitcnt lgkmcnt(0)
	s_barrier
; #define MFMA(a, b, c) __builtin_amdgcn_mfma_f32_32x32x16_bf16((a), (b), (c), 0, 0, 0)
; template <bool SWAP>
; DI void gemm_block(const bf16_t* __restrict__ A, int lda, const bf16_t* __restrict__ Bt, int ldb, int K, f32x16 (&acc)[2][2], bf16_t* sA, bf16_t* sB) {
;     ...
;   for (int kt = 0; kt < nk; ++kt) {
;     const int cur = kt & 1;
;     const bool more = kt + 1 < nk;
;     if (more) {
;       const int k0 = (kt + 1) * 64;
; #pragma unroll
;       for (int i = 0; i < 4; ++i) { ra[i] = *(const u32x4*)(ga + (size_t)i * 32 * lda + k0); rb[i] = *(const u32x4*)(gb + (size_t)i * 32 * ldb + k0); }
;     }
;     const bf16_t* ab = sA + cur * 128 * LDT + (64 * wr + l32) * LDT + h * 8;
;     const bf16_t* bb = sB + cur * 128 * LDT + (64 * wc + l32) * LDT + h * 8;
;     __builtin_amdgcn_s_setprio(1);
;     __builtin_amdgcn_iglp_opt(0);
; #pragma unroll
;     for (int ks = 0; ks < 4; ++ks) {
;       const bf16x8 a0 = *(const bf16x8*)(ab + ks * 16), a1 = *(const bf16x8*)(ab + 32 * LDT + ks * 16);
;       const bf16x8 b0 = *(const bf16x8*)(bb + ks * 16), b1 = *(const bf16x8*)(bb + 32 * LDT + ks * 16);
;       if (!SWAP) {
;         acc[0][0] = MFMA(a0, b0, acc[0][0]); acc[0][1] = MFMA(a0, b1, acc[0][1]);
;         acc[1][0] = MFMA(a1, b0, acc[1][0]); acc[1][1] = MFMA(a1, b1, acc[1][1]);
;       } else {
;         acc[0][0] = MFMA(b0, a0, acc[0][0]); acc[0][1] = MFMA(b1, a0, acc[0][1]);
;         acc[1][0] = MFMA(b0, a1, acc[1][0]); acc[1][1] = MFMA(b1, a1, acc[1][1]);
;       }
;     }
;     __builtin_amdgcn_s_setprio(0);
;     if (more) {
;       const int nb = (cur ^ 1) * 128 * LDT;
; #pragma unroll
;       for (int i = 0; i < 4; ++i) { *(u32x4*)(sA + nb + soff + i * 32 * LDT) = ra[i]; *(u32x4*)(sB + nb + soff + i * 32 * LDT) = rb[i]; }
;     }
;     __syncthreads();
;   }
	ds_read_b128 v[120:123], v66 offset:18432
	ds_read_b128 v[128:131], v0 offset:55296
	ds_read_b128 v[132:135], v0 offset:59904
	ds_read_b128 v[124:127], v66 offset:23040
	ds_read_b128 v[136:139], v66 offset:18464
	ds_read_b128 v[184:187], v0 offset:55328
	ds_read_b128 v[200:203], v0 offset:59936
	ds_read_b128 v[140:143], v66 offset:23072
	s_setprio 1
	s_waitcnt lgkmcnt(4)
	v_mfma_f32_32x32x16_bf16 v[50:65], v[128:131], v[120:123], v[50:65]
	global_load_dwordx4 v[152:155], v[68:69], off offset:1408
	v_mfma_f32_32x32x16_bf16 v[34:49], v[132:135], v[120:123], v[34:49]
	s_waitcnt vmcnt(8)
	ds_write_b128 v85, v[88:91]
	v_mfma_f32_32x32x16_bf16 v[18:33], v[132:135], v[124:127], v[18:33]
	global_load_dwordx4 v[156:159], v[70:71], off offset:1408
	v_mfma_f32_32x32x16_bf16 v[2:17], v[128:131], v[124:127], v[2:17]
	s_waitcnt vmcnt(8)
	ds_write_b128 v85, v[92:95] offset:36864
	ds_read_b128 v[120:123], v66 offset:18496
	ds_read_b128 v[128:131], v0 offset:55360
	ds_read_b128 v[132:135], v0 offset:59968
	ds_read_b128 v[124:127], v66 offset:23104
	s_waitcnt lgkmcnt(6)
	v_mfma_f32_32x32x16_bf16 v[50:65], v[184:187], v[136:139], v[50:65]
	global_load_dwordx4 v[160:163], v[72:73], off offset:1408
	v_mfma_f32_32x32x16_bf16 v[34:49], v[200:203], v[136:139], v[34:49]
	s_waitcnt vmcnt(8)
	ds_write_b128 v85, v[96:99] offset:4608
	v_mfma_f32_32x32x16_bf16 v[18:33], v[200:203], v[140:143], v[18:33]
	global_load_dwordx4 v[164:167], v[74:75], off offset:1408
	v_mfma_f32_32x32x16_bf16 v[2:17], v[184:187], v[140:143], v[2:17]
	s_waitcnt vmcnt(8)
	ds_write_b128 v85, v[100:103] offset:41472
	ds_read_b128 v[136:139], v66 offset:18528
	ds_read_b128 v[184:187], v0 offset:55392
	ds_read_b128 v[200:203], v0 offset:60000
	ds_read_b128 v[140:143], v66 offset:23136
	s_waitcnt lgkmcnt(6)
	v_mfma_f32_32x32x16_bf16 v[50:65], v[128:131], v[120:123], v[50:65]
	global_load_dwordx4 v[168:171], v[76:77], off offset:1408
	v_mfma_f32_32x32x16_bf16 v[34:49], v[132:135], v[120:123], v[34:49]
	s_waitcnt vmcnt(8)
	ds_write_b128 v85, v[104:107] offset:9216
	v_mfma_f32_32x32x16_bf16 v[18:33], v[132:135], v[124:127], v[18:33]
	global_load_dwordx4 v[172:175], v[78:79], off offset:1408
	v_mfma_f32_32x32x16_bf16 v[2:17], v[128:131], v[124:127], v[2:17]
	s_waitcnt vmcnt(8)
	ds_write_b128 v85, v[108:111] offset:46080
	s_waitcnt lgkmcnt(2)
	v_mfma_f32_32x32x16_bf16 v[50:65], v[184:187], v[136:139], v[50:65]
	global_load_dwordx4 v[176:179], v[80:81], off offset:1408
	v_mfma_f32_32x32x16_bf16 v[34:49], v[200:203], v[136:139], v[34:49]
	s_waitcnt vmcnt(8)
	ds_write_b128 v85, v[112:115] offset:13824
	v_mfma_f32_32x32x16_bf16 v[18:33], v[200:203], v[140:143], v[18:33]
	global_load_dwordx4 v[180:183], v[82:83], off offset:1408
	v_mfma_f32_32x32x16_bf16 v[2:17], v[184:187], v[140:143], v[2:17]
	s_waitcnt vmcnt(8)
	ds_write_b128 v85, v[116:119] offset:50688
	s_setprio 0
	s_waitcnt lgkmcnt(0)
	s_barrier
	ds_read_b128 v[120:123], v66
	ds_read_b128 v[128:131], v0 offset:36864
	ds_read_b128 v[132:135], v0 offset:41472
	ds_read_b128 v[124:127], v66 offset:4608
	ds_read_b128 v[136:139], v66 offset:32
	ds_read_b128 v[184:187], v0 offset:36896
	ds_read_b128 v[200:203], v0 offset:41504
	ds_read_b128 v[140:143], v66 offset:4640
	s_setprio 1
	s_waitcnt lgkmcnt(4)
	v_mfma_f32_32x32x16_bf16 v[50:65], v[128:131], v[120:123], v[50:65]
	global_load_dwordx4 v[88:91], v[68:69], off offset:1536
	v_mfma_f32_32x32x16_bf16 v[34:49], v[132:135], v[120:123], v[34:49]
	s_waitcnt vmcnt(8)
	ds_write_b128 v85, v[152:155] offset:18432
	v_mfma_f32_32x32x16_bf16 v[18:33], v[132:135], v[124:127], v[18:33]
	global_load_dwordx4 v[92:95], v[70:71], off offset:1536
	v_mfma_f32_32x32x16_bf16 v[2:17], v[128:131], v[124:127], v[2:17]
	s_waitcnt vmcnt(8)
	ds_write_b128 v85, v[156:159] offset:55296
	ds_read_b128 v[120:123], v66 offset:64
	ds_read_b128 v[128:131], v0 offset:36928
	ds_read_b128 v[132:135], v0 offset:41536
	ds_read_b128 v[124:127], v66 offset:4672
	s_waitcnt lgkmcnt(6)
	v_mfma_f32_32x32x16_bf16 v[50:65], v[184:187], v[136:139], v[50:65]
	global_load_dwordx4 v[96:99], v[72:73], off offset:1536
	v_mfma_f32_32x32x16_bf16 v[34:49], v[200:203], v[136:139], v[34:49]
	s_waitcnt vmcnt(8)
	ds_write_b128 v85, v[160:163] offset:23040
	v_mfma_f32_32x32x16_bf16 v[18:33], v[200:203], v[140:143], v[18:33]
	global_load_dwordx4 v[100:103], v[74:75], off offset:1536
	v_mfma_f32_32x32x16_bf16 v[2:17], v[184:187], v[140:143], v[2:17]
	s_waitcnt vmcnt(8)
	ds_write_b128 v85, v[164:167] offset:59904
	ds_read_b128 v[136:139], v66 offset:96
	ds_read_b128 v[184:187], v0 offset:36960
	ds_read_b128 v[200:203], v0 offset:41568
	ds_read_b128 v[140:143], v66 offset:4704
	s_waitcnt lgkmcnt(6)
	v_mfma_f32_32x32x16_bf16 v[50:65], v[128:131], v[120:123], v[50:65]
	global_load_dwordx4 v[104:107], v[76:77], off offset:1536
	v_mfma_f32_32x32x16_bf16 v[34:49], v[132:135], v[120:123], v[34:49]
	s_waitcnt vmcnt(8)
	ds_write_b128 v85, v[168:171] offset:27648
	v_mfma_f32_32x32x16_bf16 v[18:33], v[132:135], v[124:127], v[18:33]
	global_load_dwordx4 v[108:111], v[78:79], off offset:1536
	v_mfma_f32_32x32x16_bf16 v[2:17], v[128:131], v[124:127], v[2:17]
	s_waitcnt vmcnt(8)
	ds_write_b128 v85, v[172:175] offset:64512
	s_waitcnt lgkmcnt(2)
	v_mfma_f32_32x32x16_bf16 v[50:65], v[184:187], v[136:139], v[50:65]
	global_load_dwordx4 v[112:115], v[80:81], off offset:1536
	v_mfma_f32_32x32x16_bf16 v[34:49], v[200:203], v[136:139], v[34:49]
	s_waitcnt vmcnt(8)
	ds_write_b128 v85, v[176:179] offset:32256
	v_mfma_f32_32x32x16_bf16 v[18:33], v[200:203], v[140:143], v[18:33]
	global_load_dwordx4 v[116:119], v[82:83], off offset:1536
	v_mfma_f32_32x32x16_bf16 v[2:17], v[184:187], v[140:143], v[2:17]
	s_waitcnt vmcnt(8)
	ds_write_b128 v86, v[180:183] offset:32256
	s_setprio 0
	s_waitcnt lgkmcnt(0)
	s_barrier
; #define MFMA(a, b, c) __builtin_amdgcn_mfma_f32_32x32x16_bf16((a), (b), (c), 0, 0, 0)
; template <bool SWAP>
; DI void gemm_block(const bf16_t* __restrict__ A, int lda, const bf16_t* __restrict__ Bt, int ldb, int K, f32x16 (&acc)[2][2], bf16_t* sA, bf16_t* sB) {
;     ...
;   for (int kt = 0; kt < nk; ++kt) {
;     const int cur = kt & 1;
;     const bool more = kt + 1 < nk;
;     if (more) {
;       const int k0 = (kt + 1) * 64;
; #pragma unroll
;       for (int i = 0; i < 4; ++i) { ra[i] = *(const u32x4*)(ga + (size_t)i * 32 * lda + k0); rb[i] = *(const u32x4*)(gb + (size_t)i * 32 * ldb + k0); }
;     }
;     const bf16_t* ab = sA + cur * 128 * LDT + (64 * wr + l32) * LDT + h * 8;
;     const bf16_t* bb = sB + cur * 128 * LDT + (64 * wc + l32) * LDT + h * 8;
;     __builtin_amdgcn_s_setprio(1);
;     __builtin_amdgcn_iglp_opt(0);
; #pragma unroll
;     for (int ks = 0; ks < 4; ++ks) {
;       const bf16x8 a0 = *(const bf16x8*)(ab + ks * 16), a1 = *(const bf16x8*)(ab + 32 * LDT + ks * 16);
;       const bf16x8 b0 = *(const bf16x8*)(bb + ks * 16), b1 = *(const bf16x8*)(bb + 32 * LDT + ks * 16);
;       if (!SWAP) {
;         acc[0][0] = MFMA(a0, b0, acc[0][0]); acc[0][1] = MFMA(a0, b1, acc[0][1]);
;         acc[1][0] = MFMA(a1, b0, acc[1][0]); acc[1][1] = MFMA(a1, b1, acc[1][1]);
;       } else {
;         acc[0][0] = MFMA(b0, a0, acc[0][0]); acc[0][1] = MFMA(b1, a0, acc[0][1]);
;         acc[1][0] = MFMA(b0, a1, acc[1][0]); acc[1][1] = MFMA(b1, a1, acc[1][1]);
;       }
;     }
;     __builtin_amdgcn_s_setprio(0);
;     if (more) {
;       const int nb = (cur ^ 1) * 128 * LDT;
; #pragma unroll
;       for (int i = 0; i < 4; ++i) { *(u32x4*)(sA + nb + soff + i * 32 * LDT) = ra[i]; *(u32x4*)(sB + nb + soff + i * 32 * LDT) = rb[i]; }
;     }
;     __syncthreads();
;   }
	ds_read_b128 v[120:123], v66 offset:18432
	ds_read_b128 v[128:131], v0 offset:55296
	ds_read_b128 v[132:135], v0 offset:59904
	ds_read_b128 v[124:127], v66 offset:23040
	ds_read_b128 v[136:139], v66 offset:18464
	ds_read_b128 v[184:187], v0 offset:55328
	ds_read_b128 v[200:203], v0 offset:59936
	ds_read_b128 v[140:143], v66 offset:23072
	s_setprio 1
	s_waitcnt lgkmcnt(4)
	v_mfma_f32_32x32x16_bf16 v[50:65], v[128:131], v[120:123], v[50:65]
	global_load_dwordx4 v[152:155], v[68:69], off offset:1664
	v_mfma_f32_32x32x16_bf16 v[34:49], v[132:135], v[120:123], v[34:49]
	s_waitcnt vmcnt(8)
	ds_write_b128 v85, v[88:91]
	v_mfma_f32_32x32x16_bf16 v[18:33], v[132:135], v[124:127], v[18:33]
	global_load_dwordx4 v[156:159], v[70:71], off offset:1664
	v_mfma_f32_32x32x16_bf16 v[2:17], v[128:131], v[124:127], v[2:17]
	s_waitcnt vmcnt(8)
	ds_write_b128 v85, v[92:95] offset:36864
	ds_read_b128 v[120:123], v66 offset:18496
	ds_read_b128 v[128:131], v0 offset:55360
	ds_read_b128 v[132:135], v0 offset:59968
	ds_read_b128 v[124:127], v66 offset:23104
	s_waitcnt lgkmcnt(6)
	v_mfma_f32_32x32x16_bf16 v[50:65], v[184:187], v[136:139], v[50:65]
	global_load_dwordx4 v[160:163], v[72:73], off offset:1664
	v_mfma_f32_32x32x16_bf16 v[34:49], v[200:203], v[136:139], v[34:49]
	s_waitcnt vmcnt(8)
	ds_write_b128 v85, v[96:99] offset:4608
	v_mfma_f32_32x32x16_bf16 v[18:33], v[200:203], v[140:143], v[18:33]
	global_load_dwordx4 v[164:167], v[74:75], off offset:1664
	v_mfma_f32_32x32x16_bf16 v[2:17], v[184:187], v[140:143], v[2:17]
	s_waitcnt vmcnt(8)
	ds_write_b128 v85, v[100:103] offset:41472
	ds_read_b128 v[136:139], v66 offset:18528
	ds_read_b128 v[184:187], v0 offset:55392
	ds_read_b128 v[200:203], v0 offset:60000
	ds_read_b128 v[140:143], v66 offset:23136
	s_waitcnt lgkmcnt(6)
	v_mfma_f32_32x32x16_bf16 v[50:65], v[128:131], v[120:123], v[50:65]
	global_load_dwordx4 v[168:171], v[76:77], off offset:1664
	v_mfma_f32_32x32x16_bf16 v[34:49], v[132:135], v[120:123], v[34:49]
	s_waitcnt vmcnt(8)
	ds_write_b128 v85, v[104:107] offset:9216
	v_mfma_f32_32x32x16_bf16 v[18:33], v[132:135], v[124:127], v[18:33]
	global_load_dwordx4 v[172:175], v[78:79], off offset:1664
	v_mfma_f32_32x32x16_bf16 v[2:17], v[128:131], v[124:127], v[2:17]
	s_waitcnt vmcnt(8)
	ds_write_b128 v85, v[108:111] offset:46080
	s_waitcnt lgkmcnt(2)
	v_mfma_f32_32x32x16_bf16 v[50:65], v[184:187], v[136:139], v[50:65]
	global_load_dwordx4 v[176:179], v[80:81], off offset:1664
	v_mfma_f32_32x32x16_bf16 v[34:49], v[200:203], v[136:139], v[34:49]
	s_waitcnt vmcnt(8)
	ds_write_b128 v85, v[112:115] offset:13824
	v_mfma_f32_32x32x16_bf16 v[18:33], v[200:203], v[140:143], v[18:33]
	global_load_dwordx4 v[180:183], v[82:83], off offset:1664
	v_mfma_f32_32x32x16_bf16 v[2:17], v[184:187], v[140:143], v[2:17]
	s_waitcnt vmcnt(8)
	ds_write_b128 v85, v[116:119] offset:50688
	s_setprio 0
	s_waitcnt lgkmcnt(0)
	s_barrier
	ds_read_b128 v[120:123], v66
	ds_read_b128 v[128:131], v0 offset:36864
	ds_read_b128 v[132:135], v0 offset:41472
	ds_read_b128 v[124:127], v66 offset:4608
	ds_read_b128 v[136:139], v66 offset:32
	ds_read_b128 v[184:187], v0 offset:36896
	ds_read_b128 v[200:203], v0 offset:41504
	ds_read_b128 v[140:143], v66 offset:4640
	s_setprio 1
	s_waitcnt lgkmcnt(4)
	v_mfma_f32_32x32x16_bf16 v[50:65], v[128:131], v[120:123], v[50:65]
	global_load_dwordx4 v[88:91], v[68:69], off offset:1792
	v_mfma_f32_32x32x16_bf16 v[34:49], v[132:135], v[120:123], v[34:49]
	s_waitcnt vmcnt(8)
	ds_write_b128 v85, v[152:155] offset:18432
	v_mfma_f32_32x32x16_bf16 v[18:33], v[132:135], v[124:127], v[18:33]
	global_load_dwordx4 v[92:95], v[70:71], off offset:1792
	v_mfma_f32_32x32x16_bf16 v[2:17], v[128:131], v[124:127], v[2:17]
	s_waitcnt vmcnt(8)
	ds_write_b128 v85, v[156:159] offset:55296
	ds_read_b128 v[120:123], v66 offset:64
	ds_read_b128 v[128:131], v0 offset:36928
	ds_read_b128 v[132:135], v0 offset:41536
	ds_read_b128 v[124:127], v66 offset:4672
	s_waitcnt lgkmcnt(6)
	v_mfma_f32_32x32x16_bf16 v[50:65], v[184:187], v[136:139], v[50:65]
	global_load_dwordx4 v[96:99], v[72:73], off offset:1792
	v_mfma_f32_32x32x16_bf16 v[34:49], v[200:203], v[136:139], v[34:49]
	s_waitcnt vmcnt(8)
	ds_write_b128 v85, v[160:163] offset:23040
	v_mfma_f32_32x32x16_bf16 v[18:33], v[200:203], v[140:143], v[18:33]
	global_load_dwordx4 v[100:103], v[74:75], off offset:1792
	v_mfma_f32_32x32x16_bf16 v[2:17], v[184:187], v[140:143], v[2:17]
	s_waitcnt vmcnt(8)
	ds_write_b128 v85, v[164:167] offset:59904
	ds_read_b128 v[136:139], v66 offset:96
	ds_read_b128 v[184:187], v0 offset:36960
	ds_read_b128 v[200:203], v0 offset:41568
	ds_read_b128 v[140:143], v66 offset:4704
	s_waitcnt lgkmcnt(6)
	v_mfma_f32_32x32x16_bf16 v[50:65], v[128:131], v[120:123], v[50:65]
	global_load_dwordx4 v[104:107], v[76:77], off offset:1792
	v_mfma_f32_32x32x16_bf16 v[34:49], v[132:135], v[120:123], v[34:49]
	s_waitcnt vmcnt(8)
	ds_write_b128 v85, v[168:171] offset:27648
	v_mfma_f32_32x32x16_bf16 v[18:33], v[132:135], v[124:127], v[18:33]
	global_load_dwordx4 v[108:111], v[78:79], off offset:1792
	v_mfma_f32_32x32x16_bf16 v[2:17], v[128:131], v[124:127], v[2:17]
	s_waitcnt vmcnt(8)
	ds_write_b128 v85, v[172:175] offset:64512
	s_waitcnt lgkmcnt(2)
	v_mfma_f32_32x32x16_bf16 v[50:65], v[184:187], v[136:139], v[50:65]
	global_load_dwordx4 v[112:115], v[80:81], off offset:1792
	v_mfma_f32_32x32x16_bf16 v[34:49], v[200:203], v[136:139], v[34:49]
	s_waitcnt vmcnt(8)
	ds_write_b128 v85, v[176:179] offset:32256
	v_mfma_f32_32x32x16_bf16 v[18:33], v[200:203], v[140:143], v[18:33]
	global_load_dwordx4 v[116:119], v[82:83], off offset:1792
	v_mfma_f32_32x32x16_bf16 v[2:17], v[184:187], v[140:143], v[2:17]
	s_waitcnt vmcnt(8)
	ds_write_b128 v86, v[180:183] offset:32256
	s_setprio 0
	s_waitcnt lgkmcnt(0)
	s_barrier
; #define MFMA(a, b, c) __builtin_amdgcn_mfma_f32_32x32x16_bf16((a), (b), (c), 0, 0, 0)
; template <bool SWAP>
; DI void gemm_block(const bf16_t* __restrict__ A, int lda, const bf16_t* __restrict__ Bt, int ldb, int K, f32x16 (&acc)[2][2], bf16_t* sA, bf16_t* sB) {
;     ...
;   for (int kt = 0; kt < nk; ++kt) {
;     const int cur = kt & 1;
;     const bool more = kt + 1 < nk;
;     if (more) {
;       const int k0 = (kt + 1) * 64;
; #pragma unroll
;       for (int i = 0; i < 4; ++i) { ra[i] = *(const u32x4*)(ga + (size_t)i * 32 * lda + k0); rb[i] = *(const u32x4*)(gb + (size_t)i * 32 * ldb + k0); }
;     }
;     const bf16_t* ab = sA + cur * 128 * LDT + (64 * wr + l32) * LDT + h * 8;
;     const bf16_t* bb = sB + cur * 128 * LDT + (64 * wc + l32) * LDT + h * 8;
;     __builtin_amdgcn_s_setprio(1);
;     __builtin_amdgcn_iglp_opt(0);
; #pragma unroll
;     for (int ks = 0; ks < 4; ++ks) {
;       const bf16x8 a0 = *(const bf16x8*)(ab + ks * 16), a1 = *(const bf16x8*)(ab + 32 * LDT + ks * 16);
;       const bf16x8 b0 = *(const bf16x8*)(bb + ks * 16), b1 = *(const bf16x8*)(bb + 32 * LDT + ks * 16);
;       if (!SWAP) {
;         acc[0][0] = MFMA(a0, b0, acc[0][0]); acc[0][1] = MFMA(a0, b1, acc[0][1]);
;         acc[1][0] = MFMA(a1, b0, acc[1][0]); acc[1][1] = MFMA(a1, b1, acc[1][1]);
;       } else {
;         acc[0][0] = MFMA(b0, a0, acc[0][0]); acc[0][1] = MFMA(b1, a0, acc[0][1]);
;         acc[1][0] = MFMA(b0, a1, acc[1][0]); acc[1][1] = MFMA(b1, a1, acc[1][1]);
;       }
;     }
;     __builtin_amdgcn_s_setprio(0);
;     if (more) {
;       const int nb = (cur ^ 1) * 128 * LDT;
; #pragma unroll
;       for (int i = 0; i < 4; ++i) { *(u32x4*)(sA + nb + soff + i * 32 * LDT) = ra[i]; *(u32x4*)(sB + nb + soff + i * 32 * LDT) = rb[i]; }
;     }
;     __syncthreads();
;   }
	ds_read_b128 v[120:123], v66 offset:18432
	ds_read_b128 v[128:131], v0 offset:55296
	ds_read_b128 v[132:135], v0 offset:59904
	ds_read_b128 v[124:127], v66 offset:23040
	ds_read_b128 v[136:139], v66 offset:18464
	ds_read_b128 v[184:187], v0 offset:55328
	ds_read_b128 v[200:203], v0 offset:59936
	ds_read_b128 v[140:143], v66 offset:23072
	s_setprio 1
	s_waitcnt lgkmcnt(4)
	v_mfma_f32_32x32x16_bf16 v[50:65], v[128:131], v[120:123], v[50:65]
	global_load_dwordx4 v[152:155], v[68:69], off offset:1920
	v_mfma_f32_32x32x16_bf16 v[34:49], v[132:135], v[120:123], v[34:49]
	s_waitcnt vmcnt(8)
	ds_write_b128 v85, v[88:91]
	v_mfma_f32_32x32x16_bf16 v[18:33], v[132:135], v[124:127], v[18:33]
	global_load_dwordx4 v[156:159], v[70:71], off offset:1920
	v_mfma_f32_32x32x16_bf16 v[2:17], v[128:131], v[124:127], v[2:17]
	s_waitcnt vmcnt(8)
	ds_write_b128 v85, v[92:95] offset:36864
	ds_read_b128 v[120:123], v66 offset:18496
	ds_read_b128 v[128:131], v0 offset:55360
	ds_read_b128 v[132:135], v0 offset:59968
	ds_read_b128 v[124:127], v66 offset:23104
	s_waitcnt lgkmcnt(6)
	v_mfma_f32_32x32x16_bf16 v[50:65], v[184:187], v[136:139], v[50:65]
	global_load_dwordx4 v[160:163], v[72:73], off offset:1920
	v_mfma_f32_32x32x16_bf16 v[34:49], v[200:203], v[136:139], v[34:49]
	s_waitcnt vmcnt(8)
	ds_write_b128 v85, v[96:99] offset:4608
	v_mfma_f32_32x32x16_bf16 v[18:33], v[200:203], v[140:143], v[18:33]
	global_load_dwordx4 v[164:167], v[74:75], off offset:1920
	v_mfma_f32_32x32x16_bf16 v[2:17], v[184:187], v[140:143], v[2:17]
	s_waitcnt vmcnt(8)
	ds_write_b128 v85, v[100:103] offset:41472
	ds_read_b128 v[136:139], v66 offset:18528
	ds_read_b128 v[184:187], v0 offset:55392
	ds_read_b128 v[200:203], v0 offset:60000
	ds_read_b128 v[140:143], v66 offset:23136
	s_waitcnt lgkmcnt(6)
	v_mfma_f32_32x32x16_bf16 v[50:65], v[128:131], v[120:123], v[50:65]
	global_load_dwordx4 v[168:171], v[76:77], off offset:1920
	v_mfma_f32_32x32x16_bf16 v[34:49], v[132:135], v[120:123], v[34:49]
	s_waitcnt vmcnt(8)
	ds_write_b128 v85, v[104:107] offset:9216
	v_mfma_f32_32x32x16_bf16 v[18:33], v[132:135], v[124:127], v[18:33]
	global_load_dwordx4 v[172:175], v[78:79], off offset:1920
	v_mfma_f32_32x32x16_bf16 v[2:17], v[128:131], v[124:127], v[2:17]
	s_waitcnt vmcnt(8)
	ds_write_b128 v85, v[108:111] offset:46080
	s_waitcnt lgkmcnt(2)
	v_mfma_f32_32x32x16_bf16 v[50:65], v[184:187], v[136:139], v[50:65]
	global_load_dwordx4 v[176:179], v[80:81], off offset:1920
	v_mfma_f32_32x32x16_bf16 v[34:49], v[200:203], v[136:139], v[34:49]
	s_waitcnt vmcnt(8)
	ds_write_b128 v85, v[112:115] offset:13824
	v_mfma_f32_32x32x16_bf16 v[18:33], v[200:203], v[140:143], v[18:33]
	global_load_dwordx4 v[180:183], v[82:83], off offset:1920
	v_mfma_f32_32x32x16_bf16 v[2:17], v[184:187], v[140:143], v[2:17]
	s_waitcnt vmcnt(8)
	ds_write_b128 v85, v[116:119] offset:50688
	s_setprio 0
	s_waitcnt lgkmcnt(0)
	s_barrier
	ds_read_b128 v[120:123], v66
	ds_read_b128 v[128:131], v0 offset:36864
	ds_read_b128 v[132:135], v0 offset:41472
	ds_read_b128 v[124:127], v66 offset:4608
	ds_read_b128 v[136:139], v66 offset:32
	ds_read_b128 v[184:187], v0 offset:36896
	ds_read_b128 v[200:203], v0 offset:41504
	ds_read_b128 v[140:143], v66 offset:4640
	s_setprio 1
	s_waitcnt lgkmcnt(4)
	v_mfma_f32_32x32x16_bf16 v[50:65], v[128:131], v[120:123], v[50:65]
	v_mfma_f32_32x32x16_bf16 v[34:49], v[132:135], v[120:123], v[34:49]
	s_waitcnt vmcnt(7)
	ds_write_b128 v85, v[152:155] offset:18432
	v_mfma_f32_32x32x16_bf16 v[18:33], v[132:135], v[124:127], v[18:33]
	v_mfma_f32_32x32x16_bf16 v[2:17], v[128:131], v[124:127], v[2:17]
	s_waitcnt vmcnt(6)
	ds_write_b128 v85, v[156:159] offset:55296
	ds_read_b128 v[120:123], v66 offset:64
	ds_read_b128 v[128:131], v0 offset:36928
	ds_read_b128 v[132:135], v0 offset:41536
	ds_read_b128 v[124:127], v66 offset:4672
	s_waitcnt lgkmcnt(6)
	v_mfma_f32_32x32x16_bf16 v[50:65], v[184:187], v[136:139], v[50:65]
	v_mfma_f32_32x32x16_bf16 v[34:49], v[200:203], v[136:139], v[34:49]
	s_waitcnt vmcnt(5)
	ds_write_b128 v85, v[160:163] offset:23040
	v_mfma_f32_32x32x16_bf16 v[18:33], v[200:203], v[140:143], v[18:33]
	v_mfma_f32_32x32x16_bf16 v[2:17], v[184:187], v[140:143], v[2:17]
	s_waitcnt vmcnt(4)
	ds_write_b128 v85, v[164:167] offset:59904
	ds_read_b128 v[136:139], v66 offset:96
	ds_read_b128 v[184:187], v0 offset:36960
	ds_read_b128 v[200:203], v0 offset:41568
	ds_read_b128 v[140:143], v66 offset:4704
	s_waitcnt lgkmcnt(6)
	v_mfma_f32_32x32x16_bf16 v[50:65], v[128:131], v[120:123], v[50:65]
	v_mfma_f32_32x32x16_bf16 v[34:49], v[132:135], v[120:123], v[34:49]
	s_waitcnt vmcnt(3)
	ds_write_b128 v85, v[168:171] offset:27648
	v_mfma_f32_32x32x16_bf16 v[18:33], v[132:135], v[124:127], v[18:33]
	v_mfma_f32_32x32x16_bf16 v[2:17], v[128:131], v[124:127], v[2:17]
	s_waitcnt vmcnt(2)
	ds_write_b128 v85, v[172:175] offset:64512
	s_waitcnt lgkmcnt(2)
	v_mfma_f32_32x32x16_bf16 v[50:65], v[184:187], v[136:139], v[50:65]
	v_mfma_f32_32x32x16_bf16 v[34:49], v[200:203], v[136:139], v[34:49]
	s_waitcnt vmcnt(1)
	ds_write_b128 v85, v[176:179] offset:32256
	v_mfma_f32_32x32x16_bf16 v[18:33], v[200:203], v[140:143], v[18:33]
	v_mfma_f32_32x32x16_bf16 v[2:17], v[184:187], v[140:143], v[2:17]
	s_waitcnt vmcnt(0)
	ds_write_b128 v86, v[180:183] offset:32256
	s_setprio 0
	s_waitcnt lgkmcnt(0)
	s_barrier
; #define MFMA(a, b, c) __builtin_amdgcn_mfma_f32_32x32x16_bf16((a), (b), (c), 0, 0, 0)
; template <bool SWAP>
; DI void gemm_block(const bf16_t* __restrict__ A, int lda, const bf16_t* __restrict__ Bt, int ldb, int K, f32x16 (&acc)[2][2], bf16_t* sA, bf16_t* sB) {
;     ...
;   for (int kt = 0; kt < nk; ++kt) {
;     const int cur = kt & 1;
;     const bool more = kt + 1 < nk;
;     if (more) {
;       const int k0 = (kt + 1) * 64;
; #pragma unroll
;       for (int i = 0; i < 4; ++i) { ra[i] = *(const u32x4*)(ga + (size_t)i * 32 * lda + k0); rb[i] = *(const u32x4*)(gb + (size_t)i * 32 * ldb + k0); }
;     }
;     const bf16_t* ab = sA + cur * 128 * LDT + (64 * wr + l32) * LDT + h * 8;
;     const bf16_t* bb = sB + cur * 128 * LDT + (64 * wc + l32) * LDT + h * 8;
;     __builtin_amdgcn_s_setprio(1);
;     __builtin_amdgcn_iglp_opt(0);
; #pragma unroll
;     for (int ks = 0; ks < 4; ++ks) {
;       const bf16x8 a0 = *(const bf16x8*)(ab + ks * 16), a1 = *(const bf16x8*)(ab + 32 * LDT + ks * 16);
;       const bf16x8 b0 = *(const bf16x8*)(bb + ks * 16), b1 = *(const bf16x8*)(bb + 32 * LDT + ks * 16);
;       if (!SWAP) {
;         acc[0][0] = MFMA(a0, b0, acc[0][0]); acc[0][1] = MFMA(a0, b1, acc[0][1]);
;         acc[1][0] = MFMA(a1, b0, acc[1][0]); acc[1][1] = MFMA(a1, b1, acc[1][1]);
;       } else {
;         acc[0][0] = MFMA(b0, a0, acc[0][0]); acc[0][1] = MFMA(b1, a0, acc[0][1]);
;         acc[1][0] = MFMA(b0, a1, acc[1][0]); acc[1][1] = MFMA(b1, a1, acc[1][1]);
;       }
;     }
;     __builtin_amdgcn_s_setprio(0);
;     if (more) {
;       const int nb = (cur ^ 1) * 128 * LDT;
; #pragma unroll
;       for (int i = 0; i < 4; ++i) { *(u32x4*)(sA + nb + soff + i * 32 * LDT) = ra[i]; *(u32x4*)(sB + nb + soff + i * 32 * LDT) = rb[i]; }
;     }
;     __syncthreads();
;   }
; DI void gemm_job(PP p, int l, const GJob& J, char* smem) {
;     ...
;     float* sOf = (float*)smem;
; #pragma unroll
;     for (int i = 0; i < 2; ++i) {
;       const int mloc = 64 * wr + 32 * i + l32;
; #pragma unroll
;       for (int j = 0; j < 2; ++j)
; #pragma unroll
;         for (int g = 0; g < 4; ++g) {
;           f32x4 v = {acc[i][j][4 * g], acc[i][j][4 * g + 1], acc[i][j][4 * g + 2], acc[i][j][4 * g + 3]};
;           *(f32x4*)(sOf + mloc * 132 + 64 * wc + 32 * j + 8 * g + 4 * h) = v;
;         }
;     }
;     __syncthreads();
	ds_read_b128 v[120:123], v66 offset:18432
	ds_read_b128 v[128:131], v0 offset:55296
	ds_read_b128 v[132:135], v0 offset:59904
	ds_read_b128 v[124:127], v66 offset:23040
	ds_read_b128 v[136:139], v66 offset:18464
	ds_read_b128 v[184:187], v0 offset:55328
	ds_read_b128 v[200:203], v0 offset:59936
	ds_read_b128 v[140:143], v66 offset:23072
	s_setprio 1
	s_waitcnt lgkmcnt(4)
	v_mfma_f32_32x32x16_bf16 v[50:65], v[128:131], v[120:123], v[50:65]
	v_mfma_f32_32x32x16_bf16 v[34:49], v[132:135], v[120:123], v[34:49]
	v_mfma_f32_32x32x16_bf16 v[18:33], v[132:135], v[124:127], v[18:33]
	v_mfma_f32_32x32x16_bf16 v[2:17], v[128:131], v[124:127], v[2:17]
	ds_read_b128 v[120:123], v66 offset:18496
	ds_read_b128 v[128:131], v0 offset:55360
	ds_read_b128 v[132:135], v0 offset:59968
	ds_read_b128 v[124:127], v66 offset:23104
	s_waitcnt lgkmcnt(4)
	v_mfma_f32_32x32x16_bf16 v[50:65], v[184:187], v[136:139], v[50:65]
	v_mfma_f32_32x32x16_bf16 v[34:49], v[200:203], v[136:139], v[34:49]
	v_mfma_f32_32x32x16_bf16 v[18:33], v[200:203], v[140:143], v[18:33]
	v_mfma_f32_32x32x16_bf16 v[2:17], v[184:187], v[140:143], v[2:17]
	ds_read_b128 v[136:139], v66 offset:18528
	ds_read_b128 v[184:187], v0 offset:55392
	ds_read_b128 v[200:203], v0 offset:60000
	ds_read_b128 v[140:143], v66 offset:23136
	s_waitcnt lgkmcnt(4)
	v_mfma_f32_32x32x16_bf16 v[50:65], v[128:131], v[120:123], v[50:65]
	v_mfma_f32_32x32x16_bf16 v[34:49], v[132:135], v[120:123], v[34:49]
	v_mfma_f32_32x32x16_bf16 v[18:33], v[132:135], v[124:127], v[18:33]
	v_mfma_f32_32x32x16_bf16 v[2:17], v[128:131], v[124:127], v[2:17]
	s_waitcnt lgkmcnt(0)
	v_mfma_f32_32x32x16_bf16 v[50:65], v[184:187], v[136:139], v[50:65]
	v_mfma_f32_32x32x16_bf16 v[34:49], v[200:203], v[136:139], v[34:49]
	v_mfma_f32_32x32x16_bf16 v[18:33], v[200:203], v[140:143], v[18:33]
	v_mfma_f32_32x32x16_bf16 v[2:17], v[184:187], v[140:143], v[2:17]
	s_setprio 0
	s_nop 7
	s_nop 7
	v_and_b32_e32 v0, 31, v84
	v_lshrrev_b32_e32 v66, 1, v84
	s_lshl_b32 s2, s10, 7
	v_and_or_b32 v67, v66, s53, v0
	v_lshlrev_b32_e32 v68, 2, v84
	v_and_b32_e32 v0, 16, v66
	s_movk_i32 s10, 0x100
	v_and_or_b32 v0, v68, s10, v0
	v_mad_u64_u32 v[66:67], s[10:11], v67, s3, v[0:1]
	s_add_u32 s10, s4, s0
	s_addc_u32 s11, s5, 0
	s_add_u32 s12, s4, s1
	s_addc_u32 s13, s5, 0
	s_add_u32 s18, s4, s22
	s_addc_u32 s19, s5, 0
	s_add_u32 s20, s4, s23
	s_addc_u32 s21, s5, 0
	s_barrier
	ds_write_b128 v66, v[50:53]
	ds_write_b128 v66, v[54:57] offset:32
	ds_write_b128 v66, v[58:61] offset:64
	ds_write_b128 v66, v[62:65] offset:96
	ds_write_b128 v66, v[34:37] offset:128
	ds_write_b128 v66, v[38:41] offset:160
	ds_write_b128 v66, v[42:45] offset:192
	ds_write_b128 v66, v[46:49] offset:224
	ds_write_b128 v66, v[2:5] offset:16896
	ds_write_b128 v66, v[6:9] offset:16928
	ds_write_b128 v66, v[10:13] offset:16960
	ds_write_b128 v66, v[14:17] offset:16992
	ds_write_b128 v66, v[18:21] offset:17024
	ds_write_b128 v66, v[22:25] offset:17056
	ds_write_b128 v66, v[26:29] offset:17088
	ds_write_b128 v66, v[30:33] offset:17120
	s_waitcnt lgkmcnt(0)
	s_barrier
	s_load_dwordx2 s[18:19], s[18:19], 0x0
	v_and_b32_e32 v6, 0x7c, v68
	s_load_dwordx2 s[20:21], s[20:21], 0x0
	v_lshlrev_b32_e32 v0, 2, v6
	s_load_dwordx2 s[10:11], s[10:11], 0x0
	s_waitcnt lgkmcnt(0)
	v_lshl_add_u64 v[2:3], s[18:19], 0, v[0:1]
	s_load_dwordx2 s[18:19], s[12:13], 0x0
	v_lshl_add_u64 v[4:5], s[20:21], 0, v[0:1]
	s_load_dwordx2 s[20:21], s[4:5], 0x80
	s_lshl_b32 s30, s39, 2
	v_or_b32_e32 v6, s39, v6
	v_lshl_add_u64 v[2:3], v[2:3], 0, s[30:31]
	v_lshl_add_u64 v[4:5], v[4:5], 0, s[30:31]
	v_lshlrev_b32_e32 v6, 2, v6
